# GEMM main loops restructured: 32-MFMA merged bursts (8 barriers per K=128 instead of 16), A' fragments read with A/B, DMA groups issued one load segment after the last read of their LDS region, preamb
# baseline (speedup 1.0000x reference)
.LBB0_127:
	v_lshrrev_b32_e32 v18, 1, v2
	v_and_b32_e32 v18, 24, v18
	v_and_b32_e32 v9, 15, v2
	v_lshlrev_b32_e32 v19, 1, v18
	v_lshlrev_b32_e32 v2, 2, v2
	v_lshl_or_b32 v144, s0, 6, v9
	v_lshl_or_b32 v9, v9, 6, v19
	s_lshl_b32 s0, s0, 13
	v_and_b32_e32 v2, 32, v2
	v_lshl_add_u64 v[10:11], s[52:53], 0, v[194:195]
	v_mov_b32_e32 v135, v195
	v_bitop3_b32 v145, v9, s0, v2 bitop3:0xde
	s_lshl_b32 s0, s1, 5
	s_add_i32 s70, s55, 0x18000
	v_lshl_add_u64 v[12:13], s[52:53], 0, v[134:135]
	v_mov_b32_e32 v131, v195
	s_and_b32 s8, s0, 0x60
	v_lshl_add_u64 v[10:11], v[10:11], 0, s[76:77]
	s_mov_b32 m0, s70
	s_add_i32 s71, s55, 0x1a000
	v_lshl_add_u64 v[14:15], s[6:7], 0, v[130:131]
	v_mov_b32_e32 v133, v195
	s_lshl_b32 s0, s8, 7
	s_waitcnt vmcnt(0)
	s_barrier
	global_load_lds_dwordx4 v[10:11], off
	v_lshl_add_u64 v[10:11], v[12:13], 0, s[76:77]
	s_mov_b32 m0, s71
	s_add_i32 s33, s55, 0x8000
	s_add_i32 s35, s55, 0xa000
	v_lshl_add_u64 v[16:17], s[6:7], 0, v[132:133]
	v_bitop3_b32 v146, v9, s0, v2 bitop3:0xde
	global_load_lds_dwordx4 v[10:11], off
	v_lshl_add_u64 v[10:11], v[14:15], 0, s[76:77]
	s_mov_b32 m0, s33
	s_add_u32 s0, s52, 0x80080
	global_load_lds_dwordx4 v[10:11], off
	v_lshl_add_u64 v[10:11], v[16:17], 0, s[76:77]
	s_mov_b32 m0, s35
	s_addc_u32 s1, s53, 0
	s_add_i32 s67, s55, 0x1c000
	global_load_lds_dwordx4 v[10:11], off
	v_lshl_add_u64 v[10:11], s[0:1], 0, v[194:195]
	s_mov_b32 m0, s67
	s_add_i32 s17, s55, 0x1e000
	global_load_lds_dwordx4 v[10:11], off
	v_lshl_add_u64 v[10:11], s[0:1], 0, v[134:135]
	s_mov_b32 m0, s17
	v_lshlrev_b32_e32 v2, 15, v3
	global_load_lds_dwordx4 v[10:11], off
	v_and_b32_e32 v2, 0xffff0000, v2
	v_lshl_add_u32 v2, v4, 12, v2
	v_and_b32_e32 v3, 1, v3
	v_lshl_or_b32 v2, v3, 6, v2
	v_lshl_add_u32 v136, v5, 1, v2
	v_lshlrev_b32_e32 v2, 15, v6
	v_and_b32_e32 v2, 0xffff0000, v2
	s_waitcnt vmcnt(6)
	v_lshl_add_u32 v2, v7, 12, v2
	v_and_b32_e32 v3, 1, v6
	v_lshl_or_b32 v2, v3, 6, v2
	v_add_u32_e32 v147, 0xffffe400, v144
	v_add_u32_e32 v148, 0xfffffc00, v144
	s_lshr_b32 s0, s86, 3
	v_or_b32_e32 v149, s8, v18
	v_mov_b32_e32 v137, v195
	v_lshl_add_u32 v138, v8, 1, v2
	v_mov_b32_e32 v139, v195
	s_mov_b32 s26, 0
	s_add_i32 s12, s55, 0xc000
	s_add_i32 s78, s55, 0xe000
	s_mov_b64 s[62:63], s[6:7]
	s_mov_b64 s[60:61], s[52:53]
	s_barrier
	v_writelane_b32 v250, s0, 27
	s_branch .LBB0_129

.LBB0_139:
	v_add_u32_e32 v253, 0x10000, v146
	ds_read_b128 v[140:143], v253
	ds_read_b128 v[150:153], v253 offset:1024
	ds_read_b128 v[154:157], v253 offset:2048
	ds_read_b128 v[158:161], v253 offset:3072
	ds_read_b128 v[162:165], v145
	ds_read_b128 v[166:169], v145 offset:1024
	ds_read_b128 v[170:173], v145 offset:2048
	ds_read_b128 v[174:177], v145 offset:3072
	ds_read_b128 v[178:181], v145 offset:4096
	ds_read_b128 v[182:185], v145 offset:5120
	ds_read_b128 v[186:189], v145 offset:6144
	ds_read_b128 v[190:193], v145 offset:7168
	ds_read_b128 v[206:209], v253 offset:16384
	ds_read_b128 v[210:213], v253 offset:17408
	ds_read_b128 v[214:217], v253 offset:18432
	ds_read_b128 v[218:221], v253 offset:19456
	s_add_u32 s10, s6, 0xfff80080
	s_addc_u32 s11, s7, -1
	s_cmp_eq_u32 s41, 28
	s_cselect_b32 s11, s63, s11
	s_cselect_b32 s10, s62, s10
	s_cselect_b32 s53, s61, s29
	s_cselect_b32 s52, s60, s28
	s_mov_b32 m0, s12
	s_nop 0
	global_load_lds_dwordx4 v136, s[6:7]
	s_mov_b32 m0, s78
	s_nop 0
	global_load_lds_dwordx4 v138, s[6:7]
	s_waitcnt vmcnt(8)
	s_waitcnt lgkmcnt(0)
	s_setprio 1
	s_barrier
	v_mfma_f32_16x16x32_bf16 v[126:129], v[140:143], v[162:165], v[126:129]
	v_mfma_f32_16x16x32_bf16 v[122:125], v[154:157], v[162:165], v[122:125]
	v_mfma_f32_16x16x32_bf16 v[118:121], v[140:143], v[170:173], v[118:121]
	v_mfma_f32_16x16x32_bf16 v[110:113], v[154:157], v[170:173], v[110:113]
	v_mfma_f32_16x16x32_bf16 v[102:105], v[140:143], v[178:181], v[102:105]
	v_mfma_f32_16x16x32_bf16 v[94:97], v[154:157], v[178:181], v[94:97]
	v_mfma_f32_16x16x32_bf16 v[86:89], v[140:143], v[186:189], v[86:89]
	v_mfma_f32_16x16x32_bf16 v[78:81], v[154:157], v[186:189], v[78:81]
	v_mfma_f32_16x16x32_bf16 v[126:129], v[150:153], v[166:169], v[126:129]
	v_mfma_f32_16x16x32_bf16 v[122:125], v[158:161], v[166:169], v[122:125]
	v_mfma_f32_16x16x32_bf16 v[118:121], v[150:153], v[174:177], v[118:121]
	v_mfma_f32_16x16x32_bf16 v[110:113], v[158:161], v[174:177], v[110:113]
	v_mfma_f32_16x16x32_bf16 v[102:105], v[150:153], v[182:185], v[102:105]
	v_mfma_f32_16x16x32_bf16 v[94:97], v[158:161], v[182:185], v[94:97]
	v_mfma_f32_16x16x32_bf16 v[86:89], v[150:153], v[190:193], v[86:89]
	v_mfma_f32_16x16x32_bf16 v[78:81], v[158:161], v[190:193], v[78:81]
	v_mfma_f32_16x16x32_bf16 v[114:117], v[206:209], v[162:165], v[114:117]
	v_mfma_f32_16x16x32_bf16 v[106:109], v[214:217], v[162:165], v[106:109]
	v_mfma_f32_16x16x32_bf16 v[98:101], v[206:209], v[170:173], v[98:101]
	v_mfma_f32_16x16x32_bf16 v[90:93], v[214:217], v[170:173], v[90:93]
	v_mfma_f32_16x16x32_bf16 v[82:85], v[206:209], v[178:181], v[82:85]
	v_mfma_f32_16x16x32_bf16 v[74:77], v[214:217], v[178:181], v[74:77]
	v_mfma_f32_16x16x32_bf16 v[70:73], v[206:209], v[186:189], v[70:73]
	v_mfma_f32_16x16x32_bf16 v[66:69], v[214:217], v[186:189], v[66:69]
	v_mfma_f32_16x16x32_bf16 v[114:117], v[210:213], v[166:169], v[114:117]
	v_mfma_f32_16x16x32_bf16 v[106:109], v[218:221], v[166:169], v[106:109]
	v_mfma_f32_16x16x32_bf16 v[98:101], v[210:213], v[174:177], v[98:101]
	v_mfma_f32_16x16x32_bf16 v[90:93], v[218:221], v[174:177], v[90:93]
	v_mfma_f32_16x16x32_bf16 v[82:85], v[210:213], v[182:185], v[82:85]
	v_mfma_f32_16x16x32_bf16 v[74:77], v[218:221], v[182:185], v[74:77]
	v_mfma_f32_16x16x32_bf16 v[70:73], v[210:213], v[190:193], v[70:73]
	v_mfma_f32_16x16x32_bf16 v[66:69], v[218:221], v[190:193], v[66:69]
	s_setprio 0
	s_barrier
	ds_read_b128 v[162:165], v145 offset:16384
	ds_read_b128 v[166:169], v145 offset:17408
	ds_read_b128 v[170:173], v145 offset:18432
	ds_read_b128 v[174:177], v145 offset:19456
	ds_read_b128 v[178:181], v145 offset:20480
	ds_read_b128 v[182:185], v145 offset:21504
	ds_read_b128 v[186:189], v145 offset:22528
	ds_read_b128 v[190:193], v145 offset:23552
	s_mov_b32 m0, s83
	s_nop 0
	global_load_lds_dwordx4 v194, s[52:53]
	s_mov_b32 m0, s54
	s_nop 0
	global_load_lds_dwordx4 v134, s[52:53]
	s_mov_b32 m0, s55
	s_nop 0
	global_load_lds_dwordx4 v130, s[10:11]
	s_mov_b32 m0, s34
	s_nop 0
	global_load_lds_dwordx4 v132, s[10:11]
	s_add_u32 s58, s52, 0x80000
	s_addc_u32 s59, s53, 0
	s_mov_b32 m0, s4
	s_nop 0
	global_load_lds_dwordx4 v194, s[58:59]
	s_mov_b32 m0, s5
	s_nop 0
	global_load_lds_dwordx4 v134, s[58:59]
	s_waitcnt vmcnt(8)
	s_waitcnt lgkmcnt(0)
	s_setprio 1
	s_barrier
	v_mfma_f32_16x16x32_bf16 v[62:65], v[140:143], v[162:165], v[62:65]
	v_mfma_f32_16x16x32_bf16 v[58:61], v[154:157], v[162:165], v[58:61]
	v_mfma_f32_16x16x32_bf16 v[54:57], v[140:143], v[170:173], v[54:57]
	v_mfma_f32_16x16x32_bf16 v[46:49], v[154:157], v[170:173], v[46:49]
	v_mfma_f32_16x16x32_bf16 v[38:41], v[140:143], v[178:181], v[38:41]
	v_mfma_f32_16x16x32_bf16 v[30:33], v[154:157], v[178:181], v[30:33]
	v_mfma_f32_16x16x32_bf16 v[22:25], v[140:143], v[186:189], v[22:25]
	v_mfma_f32_16x16x32_bf16 v[14:17], v[154:157], v[186:189], v[14:17]
	v_mfma_f32_16x16x32_bf16 v[62:65], v[150:153], v[166:169], v[62:65]
	v_mfma_f32_16x16x32_bf16 v[58:61], v[158:161], v[166:169], v[58:61]
	v_mfma_f32_16x16x32_bf16 v[54:57], v[150:153], v[174:177], v[54:57]
	v_mfma_f32_16x16x32_bf16 v[46:49], v[158:161], v[174:177], v[46:49]
	v_mfma_f32_16x16x32_bf16 v[38:41], v[150:153], v[182:185], v[38:41]
	v_mfma_f32_16x16x32_bf16 v[30:33], v[158:161], v[182:185], v[30:33]
	v_mfma_f32_16x16x32_bf16 v[22:25], v[150:153], v[190:193], v[22:25]
	v_mfma_f32_16x16x32_bf16 v[14:17], v[158:161], v[190:193], v[14:17]
	v_mfma_f32_16x16x32_bf16 v[50:53], v[206:209], v[162:165], v[50:53]
	v_mfma_f32_16x16x32_bf16 v[42:45], v[214:217], v[162:165], v[42:45]
	v_mfma_f32_16x16x32_bf16 v[34:37], v[206:209], v[170:173], v[34:37]
	v_mfma_f32_16x16x32_bf16 v[26:29], v[214:217], v[170:173], v[26:29]
	v_mfma_f32_16x16x32_bf16 v[18:21], v[206:209], v[178:181], v[18:21]
	v_mfma_f32_16x16x32_bf16 v[10:13], v[214:217], v[178:181], v[10:13]
	v_mfma_f32_16x16x32_bf16 v[6:9], v[206:209], v[186:189], v[6:9]
	v_mfma_f32_16x16x32_bf16 v[2:5], v[214:217], v[186:189], v[2:5]
	v_mfma_f32_16x16x32_bf16 v[50:53], v[210:213], v[166:169], v[50:53]
	v_mfma_f32_16x16x32_bf16 v[42:45], v[218:221], v[166:169], v[42:45]
	v_mfma_f32_16x16x32_bf16 v[34:37], v[210:213], v[174:177], v[34:37]
	v_mfma_f32_16x16x32_bf16 v[26:29], v[218:221], v[174:177], v[26:29]
	v_mfma_f32_16x16x32_bf16 v[18:21], v[210:213], v[182:185], v[18:21]
	v_mfma_f32_16x16x32_bf16 v[10:13], v[218:221], v[182:185], v[10:13]
	v_mfma_f32_16x16x32_bf16 v[6:9], v[210:213], v[190:193], v[6:9]
	v_mfma_f32_16x16x32_bf16 v[2:5], v[218:221], v[190:193], v[2:5]
	s_setprio 0
	s_barrier
	ds_read_b128 v[140:143], v253 offset:32768
	ds_read_b128 v[150:153], v253 offset:33792
	ds_read_b128 v[154:157], v253 offset:34816
	ds_read_b128 v[158:161], v253 offset:35840
	ds_read_b128 v[162:165], v145 offset:32768
	ds_read_b128 v[166:169], v145 offset:33792
	ds_read_b128 v[170:173], v145 offset:34816
	ds_read_b128 v[174:177], v145 offset:35840
	ds_read_b128 v[178:181], v145 offset:36864
	ds_read_b128 v[182:185], v145 offset:37888
	ds_read_b128 v[186:189], v145 offset:38912
	ds_read_b128 v[190:193], v145 offset:39936
	ds_read_b128 v[206:209], v253 offset:49152
	ds_read_b128 v[210:213], v253 offset:50176
	ds_read_b128 v[214:217], v253 offset:51200
	ds_read_b128 v[218:221], v253 offset:52224
	s_add_u32 s10, s10, 0x80000
	s_addc_u32 s11, s11, 0
	s_mov_b32 m0, s56
	s_nop 0
	global_load_lds_dwordx4 v130, s[10:11]
	s_mov_b32 m0, s57
	s_nop 0
	global_load_lds_dwordx4 v132, s[10:11]
	s_waitcnt vmcnt(8)
	s_waitcnt lgkmcnt(0)
	s_setprio 1
	s_barrier
	v_mfma_f32_16x16x32_bf16 v[126:129], v[140:143], v[162:165], v[126:129]
	v_mfma_f32_16x16x32_bf16 v[122:125], v[154:157], v[162:165], v[122:125]
	v_mfma_f32_16x16x32_bf16 v[118:121], v[140:143], v[170:173], v[118:121]
	v_mfma_f32_16x16x32_bf16 v[110:113], v[154:157], v[170:173], v[110:113]
	v_mfma_f32_16x16x32_bf16 v[102:105], v[140:143], v[178:181], v[102:105]
	v_mfma_f32_16x16x32_bf16 v[94:97], v[154:157], v[178:181], v[94:97]
	v_mfma_f32_16x16x32_bf16 v[86:89], v[140:143], v[186:189], v[86:89]
	v_mfma_f32_16x16x32_bf16 v[78:81], v[154:157], v[186:189], v[78:81]
	v_mfma_f32_16x16x32_bf16 v[126:129], v[150:153], v[166:169], v[126:129]
	v_mfma_f32_16x16x32_bf16 v[122:125], v[158:161], v[166:169], v[122:125]
	v_mfma_f32_16x16x32_bf16 v[118:121], v[150:153], v[174:177], v[118:121]
	v_mfma_f32_16x16x32_bf16 v[110:113], v[158:161], v[174:177], v[110:113]
	v_mfma_f32_16x16x32_bf16 v[102:105], v[150:153], v[182:185], v[102:105]
	v_mfma_f32_16x16x32_bf16 v[94:97], v[158:161], v[182:185], v[94:97]
	v_mfma_f32_16x16x32_bf16 v[86:89], v[150:153], v[190:193], v[86:89]
	v_mfma_f32_16x16x32_bf16 v[78:81], v[158:161], v[190:193], v[78:81]
	v_mfma_f32_16x16x32_bf16 v[114:117], v[206:209], v[162:165], v[114:117]
	v_mfma_f32_16x16x32_bf16 v[106:109], v[214:217], v[162:165], v[106:109]
	v_mfma_f32_16x16x32_bf16 v[98:101], v[206:209], v[170:173], v[98:101]
	v_mfma_f32_16x16x32_bf16 v[90:93], v[214:217], v[170:173], v[90:93]
	v_mfma_f32_16x16x32_bf16 v[82:85], v[206:209], v[178:181], v[82:85]
	v_mfma_f32_16x16x32_bf16 v[74:77], v[214:217], v[178:181], v[74:77]
	v_mfma_f32_16x16x32_bf16 v[70:73], v[206:209], v[186:189], v[70:73]
	v_mfma_f32_16x16x32_bf16 v[66:69], v[214:217], v[186:189], v[66:69]
	v_mfma_f32_16x16x32_bf16 v[114:117], v[210:213], v[166:169], v[114:117]
	v_mfma_f32_16x16x32_bf16 v[106:109], v[218:221], v[166:169], v[106:109]
	v_mfma_f32_16x16x32_bf16 v[98:101], v[210:213], v[174:177], v[98:101]
	v_mfma_f32_16x16x32_bf16 v[90:93], v[218:221], v[174:177], v[90:93]
	v_mfma_f32_16x16x32_bf16 v[82:85], v[210:213], v[182:185], v[82:85]
	v_mfma_f32_16x16x32_bf16 v[74:77], v[218:221], v[182:185], v[74:77]
	v_mfma_f32_16x16x32_bf16 v[70:73], v[210:213], v[190:193], v[70:73]
	v_mfma_f32_16x16x32_bf16 v[66:69], v[218:221], v[190:193], v[66:69]
	s_setprio 0
	s_barrier
	ds_read_b128 v[162:165], v145 offset:49152
	ds_read_b128 v[166:169], v145 offset:50176
	ds_read_b128 v[170:173], v145 offset:51200
	ds_read_b128 v[174:177], v145 offset:52224
	ds_read_b128 v[178:181], v145 offset:53248
	ds_read_b128 v[182:185], v145 offset:54272
	ds_read_b128 v[186:189], v145 offset:55296
	ds_read_b128 v[190:193], v145 offset:56320
	s_mov_b32 m0, s70
	s_add_u32 s98, s52, 0x80
	s_addc_u32 s99, s53, 0
	global_load_lds_dwordx4 v194, s[98:99]
	s_mov_b32 m0, s71
	s_nop 0
	global_load_lds_dwordx4 v134, s[98:99]
	s_mov_b32 m0, s33
	s_add_u32 s100, s10, 0xfff80080
	s_addc_u32 s101, s11, -1
	global_load_lds_dwordx4 v130, s[100:101]
	s_mov_b32 m0, s35
	s_nop 0
	global_load_lds_dwordx4 v132, s[100:101]
	s_add_u32 s10, s52, 0x80080
	s_addc_u32 s11, s53, 0
	s_mov_b32 m0, s67
	s_nop 0
	global_load_lds_dwordx4 v194, s[10:11]
	s_mov_b32 m0, s17
	s_nop 0
	global_load_lds_dwordx4 v134, s[10:11]
	s_waitcnt vmcnt(8)
	s_waitcnt lgkmcnt(0)
	s_setprio 1
	s_barrier
	v_mfma_f32_16x16x32_bf16 v[62:65], v[140:143], v[162:165], v[62:65]
	v_mfma_f32_16x16x32_bf16 v[58:61], v[154:157], v[162:165], v[58:61]
	v_mfma_f32_16x16x32_bf16 v[54:57], v[140:143], v[170:173], v[54:57]
	v_mfma_f32_16x16x32_bf16 v[46:49], v[154:157], v[170:173], v[46:49]
	v_mfma_f32_16x16x32_bf16 v[38:41], v[140:143], v[178:181], v[38:41]
	v_mfma_f32_16x16x32_bf16 v[30:33], v[154:157], v[178:181], v[30:33]
	v_mfma_f32_16x16x32_bf16 v[22:25], v[140:143], v[186:189], v[22:25]
	v_mfma_f32_16x16x32_bf16 v[14:17], v[154:157], v[186:189], v[14:17]
	v_mfma_f32_16x16x32_bf16 v[62:65], v[150:153], v[166:169], v[62:65]
	v_mfma_f32_16x16x32_bf16 v[58:61], v[158:161], v[166:169], v[58:61]
	v_mfma_f32_16x16x32_bf16 v[54:57], v[150:153], v[174:177], v[54:57]
	v_mfma_f32_16x16x32_bf16 v[46:49], v[158:161], v[174:177], v[46:49]
	v_mfma_f32_16x16x32_bf16 v[38:41], v[150:153], v[182:185], v[38:41]
	v_mfma_f32_16x16x32_bf16 v[30:33], v[158:161], v[182:185], v[30:33]
	v_mfma_f32_16x16x32_bf16 v[22:25], v[150:153], v[190:193], v[22:25]
	v_mfma_f32_16x16x32_bf16 v[14:17], v[158:161], v[190:193], v[14:17]
	v_mfma_f32_16x16x32_bf16 v[50:53], v[206:209], v[162:165], v[50:53]
	v_mfma_f32_16x16x32_bf16 v[42:45], v[214:217], v[162:165], v[42:45]
	v_mfma_f32_16x16x32_bf16 v[34:37], v[206:209], v[170:173], v[34:37]
	v_mfma_f32_16x16x32_bf16 v[26:29], v[214:217], v[170:173], v[26:29]
	v_mfma_f32_16x16x32_bf16 v[18:21], v[206:209], v[178:181], v[18:21]
	v_mfma_f32_16x16x32_bf16 v[10:13], v[214:217], v[178:181], v[10:13]
	v_mfma_f32_16x16x32_bf16 v[6:9], v[206:209], v[186:189], v[6:9]
	v_mfma_f32_16x16x32_bf16 v[2:5], v[214:217], v[186:189], v[2:5]
	v_mfma_f32_16x16x32_bf16 v[50:53], v[210:213], v[166:169], v[50:53]
	v_mfma_f32_16x16x32_bf16 v[42:45], v[218:221], v[166:169], v[42:45]
	v_mfma_f32_16x16x32_bf16 v[34:37], v[210:213], v[174:177], v[34:37]
	v_mfma_f32_16x16x32_bf16 v[26:29], v[218:221], v[174:177], v[26:29]
	v_mfma_f32_16x16x32_bf16 v[18:21], v[210:213], v[182:185], v[18:21]
	v_mfma_f32_16x16x32_bf16 v[10:13], v[218:221], v[182:185], v[10:13]
	v_mfma_f32_16x16x32_bf16 v[6:9], v[210:213], v[190:193], v[6:9]
	v_mfma_f32_16x16x32_bf16 v[2:5], v[218:221], v[190:193], v[2:5]
	s_setprio 0
	s_add_i32 s41, s41, 2
	s_add_u32 s6, s6, 0x100
	s_addc_u32 s7, s7, 0
	s_add_u32 s28, s28, 0x100
	s_addc_u32 s29, s29, 0
	s_cmp_gt_u32 s41, 29
	s_barrier
	s_cbranch_scc0 .LBB0_139
	s_cmp_gt_i32 s79, 3
	s_mov_b64 s[6:7], -1
	s_cbranch_scc0 .LBB0_146
	s_lshl_b32 s10, s82, 8
	v_lshl_or_b32 v140, s80, 8, v149
	s_cmp_lg_u32 s79, 4
	v_ashrrev_i32_e32 v141, 31, v140
	s_cbranch_scc0 .LBB0_143
	v_readlane_b32 s6, v252, 55
	v_readlane_b32 s7, v252, 56
	v_add_u32_e32 v150, s10, v147
	s_nop 0
	v_mov_b64_e32 v[142:143], s[6:7]
	s_mov_b32 s6, 0x9000
	v_mad_i64_i32 v[142:143], s[6:7], v150, s6, v[142:143]
	v_lshl_add_u64 v[142:143], v[140:141], 1, v[142:143]
	v_cvt_pk_bf16_f32 v150, v126, v127
	v_cvt_pk_bf16_f32 v151, v128, v129
	v_cvt_pk_bf16_f32 v152, v122, v123
	v_cvt_pk_bf16_f32 v153, v124, v125
	global_store_dwordx4 v[142:143], v[150:153], off
	v_add_co_u32_e32 v154, vcc, s44, v142
	s_nop 0
	v_cvt_pk_bf16_f32 v150, v114, v115
	v_cvt_pk_bf16_f32 v151, v116, v117
	v_cvt_pk_bf16_f32 v152, v106, v107
	v_cvt_pk_bf16_f32 v153, v108, v109
	global_store_dwordx4 v[142:143], v[150:153], off offset:256
	v_addc_co_u32_e32 v155, vcc, 0, v143, vcc
	s_nop 0
	v_cvt_pk_bf16_f32 v150, v118, v119
	v_cvt_pk_bf16_f32 v151, v120, v121
	v_cvt_pk_bf16_f32 v152, v110, v111
	v_cvt_pk_bf16_f32 v153, v112, v113
	global_store_dwordx4 v[154:155], v[150:153], off
	s_mov_b64 s[6:7], 0
	s_nop 0
	v_cvt_pk_bf16_f32 v150, v98, v99
	v_cvt_pk_bf16_f32 v151, v100, v101
	v_cvt_pk_bf16_f32 v152, v90, v91
	v_cvt_pk_bf16_f32 v153, v92, v93
	global_store_dwordx4 v[154:155], v[150:153], off offset:256
	v_add_co_u32_e32 v154, vcc, s45, v142
	s_nop 0
	v_cvt_pk_bf16_f32 v150, v102, v103
	v_cvt_pk_bf16_f32 v151, v104, v105
	v_cvt_pk_bf16_f32 v152, v94, v95
	v_cvt_pk_bf16_f32 v153, v96, v97
	s_nop 0
	v_addc_co_u32_e32 v155, vcc, 0, v143, vcc
	global_store_dwordx4 v[154:155], v[150:153], off
	s_nop 1
	v_cvt_pk_bf16_f32 v150, v82, v83
	v_cvt_pk_bf16_f32 v151, v84, v85
	v_cvt_pk_bf16_f32 v152, v74, v75
	v_cvt_pk_bf16_f32 v153, v76, v77
	global_store_dwordx4 v[154:155], v[150:153], off offset:256
	v_add_co_u32_e32 v154, vcc, s90, v142
	s_nop 0
	v_cvt_pk_bf16_f32 v150, v86, v87
	v_cvt_pk_bf16_f32 v151, v88, v89
	v_cvt_pk_bf16_f32 v152, v78, v79
	v_cvt_pk_bf16_f32 v153, v80, v81
	s_nop 0
	v_addc_co_u32_e32 v155, vcc, 0, v143, vcc
	global_store_dwordx4 v[154:155], v[150:153], off
	s_nop 1
	v_cvt_pk_bf16_f32 v150, v70, v71
	v_cvt_pk_bf16_f32 v151, v72, v73
	v_cvt_pk_bf16_f32 v152, v66, v67
	v_cvt_pk_bf16_f32 v153, v68, v69
	global_store_dwordx4 v[154:155], v[150:153], off offset:256
	v_add_co_u32_e32 v154, vcc, s20, v142
	s_nop 0
	v_cvt_pk_bf16_f32 v150, v62, v63
	v_cvt_pk_bf16_f32 v151, v64, v65
	v_cvt_pk_bf16_f32 v152, v58, v59
	v_cvt_pk_bf16_f32 v153, v60, v61
	s_nop 0
	v_addc_co_u32_e32 v155, vcc, 0, v143, vcc
	global_store_dwordx4 v[154:155], v[150:153], off
	s_nop 1
	v_cvt_pk_bf16_f32 v150, v50, v51
	v_cvt_pk_bf16_f32 v151, v52, v53
	v_cvt_pk_bf16_f32 v152, v42, v43
	v_cvt_pk_bf16_f32 v153, v44, v45
	global_store_dwordx4 v[154:155], v[150:153], off offset:256
	v_add_co_u32_e32 v154, vcc, s21, v142
	s_nop 0
	v_cvt_pk_bf16_f32 v150, v54, v55
	v_cvt_pk_bf16_f32 v151, v56, v57
	v_cvt_pk_bf16_f32 v152, v46, v47
	v_cvt_pk_bf16_f32 v153, v48, v49
	s_nop 0
	v_addc_co_u32_e32 v155, vcc, 0, v143, vcc
	global_store_dwordx4 v[154:155], v[150:153], off
	s_nop 1
	v_cvt_pk_bf16_f32 v150, v34, v35
	v_cvt_pk_bf16_f32 v151, v36, v37
	v_cvt_pk_bf16_f32 v152, v26, v27
	v_cvt_pk_bf16_f32 v153, v28, v29
	global_store_dwordx4 v[154:155], v[150:153], off offset:256
	v_add_co_u32_e32 v154, vcc, s22, v142
	s_nop 0
	v_cvt_pk_bf16_f32 v150, v38, v39
	v_cvt_pk_bf16_f32 v151, v40, v41
	v_cvt_pk_bf16_f32 v152, v30, v31
	v_cvt_pk_bf16_f32 v153, v32, v33
	s_nop 0
	v_addc_co_u32_e32 v155, vcc, 0, v143, vcc
	global_store_dwordx4 v[154:155], v[150:153], off
	v_add_co_u32_e32 v142, vcc, s23, v142
	s_nop 0
	v_cvt_pk_bf16_f32 v150, v18, v19
	v_cvt_pk_bf16_f32 v151, v20, v21
	v_cvt_pk_bf16_f32 v152, v10, v11
	v_cvt_pk_bf16_f32 v153, v12, v13
	global_store_dwordx4 v[154:155], v[150:153], off offset:256
	v_addc_co_u32_e32 v143, vcc, 0, v143, vcc
	s_nop 0
	v_cvt_pk_bf16_f32 v150, v22, v23
	v_cvt_pk_bf16_f32 v151, v24, v25
	v_cvt_pk_bf16_f32 v152, v14, v15
	v_cvt_pk_bf16_f32 v153, v16, v17
	global_store_dwordx4 v[142:143], v[150:153], off
	s_nop 1
	v_cvt_pk_bf16_f32 v150, v6, v7
	v_cvt_pk_bf16_f32 v151, v8, v9
	v_cvt_pk_bf16_f32 v152, v2, v3
	v_cvt_pk_bf16_f32 v153, v4, v5
	global_store_dwordx4 v[142:143], v[150:153], off offset:256

.LBB0_204:
	s_add_u32 s80, s54, s62
	s_addc_u32 s81, s55, s63
	s_add_u32 s82, s80, 0x100
	s_addc_u32 s83, s81, 0
	s_and_b64 s[10:11], s[8:9], exec
	s_cselect_b32 s83, s1, s83
	s_cselect_b32 s82, s0, s82
	s_add_u32 s10, s52, s62
	s_addc_u32 s11, s53, s63
	s_add_u32 s10, s10, 0x100
	s_addc_u32 s11, s11, 0
	s_and_b64 s[8:9], s[8:9], exec
	s_cselect_b32 vcc_hi, s7, s11
	s_cselect_b32 vcc_lo, s6, s10
	s_add_u32 s10, s80, 0x10080
	v_add_u32_e32 v253, 0x10000, v142
	s_addc_u32 s11, s81, 0
	s_add_i32 m0, s5, 0xc000
	s_add_i32 s87, s5, 0xe000
	ds_read_b128 v[144:147], v253
	s_add_u32 s80, vcc_lo, 0x340000
	ds_read_b128 v[148:151], v253 offset:1024
	s_addc_u32 s81, vcc_hi, 0
	ds_read_b128 v[152:155], v253 offset:2048
	s_add_u32 s62, s82, 0x10000
	ds_read_b128 v[156:159], v253 offset:3072
	s_addc_u32 s63, s83, 0
	s_add_u32 s8, vcc_lo, 0x340080
	s_addc_u32 s9, vcc_hi, 0
	ds_read_b128 v[160:163], v141
	ds_read_b128 v[164:167], v141 offset:1024
	ds_read_b128 v[168:171], v141 offset:2048
	ds_read_b128 v[172:175], v141 offset:3072
	ds_read_b128 v[176:179], v141 offset:4096
	ds_read_b128 v[180:183], v141 offset:5120
	ds_read_b128 v[184:187], v141 offset:6144
	ds_read_b128 v[188:191], v141 offset:7168
	global_load_lds_dwordx4 v136, s[10:11]
	s_mov_b32 m0, s87
	s_nop 0
	global_load_lds_dwordx4 v132, s[10:11]
	s_waitcnt lgkmcnt(8)
	s_barrier
	s_waitcnt lgkmcnt(0)
	s_setprio 1
	v_mfma_f32_16x16x32_bf16 v[126:129], v[144:147], v[160:163], v[126:129]
	v_mfma_f32_16x16x32_bf16 v[122:125], v[152:155], v[160:163], v[122:125]
	v_mfma_f32_16x16x32_bf16 v[118:121], v[144:147], v[168:171], v[118:121]
	v_mfma_f32_16x16x32_bf16 v[110:113], v[152:155], v[168:171], v[110:113]
	v_mfma_f32_16x16x32_bf16 v[102:105], v[144:147], v[176:179], v[102:105]
	v_mfma_f32_16x16x32_bf16 v[94:97], v[152:155], v[176:179], v[94:97]
	v_mfma_f32_16x16x32_bf16 v[86:89], v[144:147], v[184:187], v[86:89]
	v_mfma_f32_16x16x32_bf16 v[78:81], v[152:155], v[184:187], v[78:81]
	v_mfma_f32_16x16x32_bf16 v[126:129], v[148:151], v[164:167], v[126:129]
	v_mfma_f32_16x16x32_bf16 v[122:125], v[156:159], v[164:167], v[122:125]
	v_mfma_f32_16x16x32_bf16 v[118:121], v[148:151], v[172:175], v[118:121]
	v_mfma_f32_16x16x32_bf16 v[110:113], v[156:159], v[172:175], v[110:113]
	v_mfma_f32_16x16x32_bf16 v[102:105], v[148:151], v[180:183], v[102:105]
	v_mfma_f32_16x16x32_bf16 v[94:97], v[156:159], v[180:183], v[94:97]
	v_mfma_f32_16x16x32_bf16 v[86:89], v[148:151], v[188:191], v[86:89]
	v_mfma_f32_16x16x32_bf16 v[78:81], v[156:159], v[188:191], v[78:81]
	s_setprio 0
	s_barrier
	ds_read_b128 v[206:209], v253 offset:16384
	ds_read_b128 v[210:213], v253 offset:17408
	s_mov_b32 m0, s12
	ds_read_b128 v[214:217], v253 offset:18432
	ds_read_b128 v[218:221], v253 offset:19456
	v_lshl_add_u64 v[138:139], vcc, 0, v[134:135]
	global_load_lds_dwordx4 v[138:139], off
	v_lshl_add_u64 v[192:193], vcc, 0, v[130:131]
	s_mov_b32 m0, s17
	s_nop 0
	global_load_lds_dwordx4 v[192:193], off
	s_barrier
	s_waitcnt lgkmcnt(0)
	s_setprio 1
	v_mfma_f32_16x16x32_bf16 v[114:117], v[206:209], v[160:163], v[114:117]
	v_mfma_f32_16x16x32_bf16 v[106:109], v[214:217], v[160:163], v[106:109]
	v_mfma_f32_16x16x32_bf16 v[98:101], v[206:209], v[168:171], v[98:101]
	v_mfma_f32_16x16x32_bf16 v[90:93], v[214:217], v[168:171], v[90:93]
	v_mfma_f32_16x16x32_bf16 v[82:85], v[206:209], v[176:179], v[82:85]
	v_mfma_f32_16x16x32_bf16 v[74:77], v[214:217], v[176:179], v[74:77]
	v_mfma_f32_16x16x32_bf16 v[70:73], v[206:209], v[184:187], v[70:73]
	v_mfma_f32_16x16x32_bf16 v[66:69], v[214:217], v[184:187], v[66:69]
	v_mfma_f32_16x16x32_bf16 v[114:117], v[210:213], v[164:167], v[114:117]
	v_mfma_f32_16x16x32_bf16 v[106:109], v[218:221], v[164:167], v[106:109]
	v_mfma_f32_16x16x32_bf16 v[98:101], v[210:213], v[172:175], v[98:101]
	v_mfma_f32_16x16x32_bf16 v[90:93], v[218:221], v[172:175], v[90:93]
	v_mfma_f32_16x16x32_bf16 v[82:85], v[210:213], v[180:183], v[82:85]
	v_mfma_f32_16x16x32_bf16 v[74:77], v[218:221], v[180:183], v[74:77]
	v_mfma_f32_16x16x32_bf16 v[70:73], v[210:213], v[188:191], v[70:73]
	v_mfma_f32_16x16x32_bf16 v[66:69], v[218:221], v[188:191], v[66:69]
	s_setprio 0
	s_mov_b32 m0, s5
	v_lshl_add_u64 v[222:223], s[82:83], 0, v[136:137]
	s_barrier
	ds_read_b128 v[160:163], v141 offset:16384
	ds_read_b128 v[164:167], v141 offset:17408
	ds_read_b128 v[168:171], v141 offset:18432
	ds_read_b128 v[172:175], v141 offset:19456
	ds_read_b128 v[176:179], v141 offset:20480
	ds_read_b128 v[180:183], v141 offset:21504
	ds_read_b128 v[184:187], v141 offset:22528
	ds_read_b128 v[188:191], v141 offset:23552
	global_load_lds_dwordx4 v[222:223], off
	v_lshl_add_u64 v[224:225], s[82:83], 0, v[132:133]
	s_mov_b32 m0, s26
	s_nop 0
	global_load_lds_dwordx4 v[224:225], off
	s_barrier
	s_waitcnt lgkmcnt(0)
	s_setprio 1
	v_mfma_f32_16x16x32_bf16 v[62:65], v[144:147], v[160:163], v[62:65]
	v_mfma_f32_16x16x32_bf16 v[58:61], v[152:155], v[160:163], v[58:61]
	v_mfma_f32_16x16x32_bf16 v[54:57], v[144:147], v[168:171], v[54:57]
	v_mfma_f32_16x16x32_bf16 v[46:49], v[152:155], v[168:171], v[46:49]
	v_mfma_f32_16x16x32_bf16 v[38:41], v[144:147], v[176:179], v[38:41]
	v_mfma_f32_16x16x32_bf16 v[30:33], v[152:155], v[176:179], v[30:33]
	v_mfma_f32_16x16x32_bf16 v[22:25], v[144:147], v[184:187], v[22:25]
	v_mfma_f32_16x16x32_bf16 v[14:17], v[152:155], v[184:187], v[14:17]
	v_mfma_f32_16x16x32_bf16 v[62:65], v[148:151], v[164:167], v[62:65]
	v_mfma_f32_16x16x32_bf16 v[58:61], v[156:159], v[164:167], v[58:61]
	v_mfma_f32_16x16x32_bf16 v[54:57], v[148:151], v[172:175], v[54:57]
	v_mfma_f32_16x16x32_bf16 v[46:49], v[156:159], v[172:175], v[46:49]
	v_mfma_f32_16x16x32_bf16 v[38:41], v[148:151], v[180:183], v[38:41]
	v_mfma_f32_16x16x32_bf16 v[30:33], v[156:159], v[180:183], v[30:33]
	v_mfma_f32_16x16x32_bf16 v[22:25], v[148:151], v[188:191], v[22:25]
	v_mfma_f32_16x16x32_bf16 v[14:17], v[156:159], v[188:191], v[14:17]
	s_setprio 0
	s_barrier
	s_mov_b32 m0, s34
	s_nop 0
	global_load_lds_dwordx4 v134, s[80:81]
	s_mov_b32 m0, s35
	s_nop 0
	global_load_lds_dwordx4 v130, s[80:81]
	s_waitcnt vmcnt(6)
	s_barrier
	s_setprio 1
	v_mfma_f32_16x16x32_bf16 v[50:53], v[206:209], v[160:163], v[50:53]
	v_mfma_f32_16x16x32_bf16 v[42:45], v[214:217], v[160:163], v[42:45]
	v_mfma_f32_16x16x32_bf16 v[34:37], v[206:209], v[168:171], v[34:37]
	v_mfma_f32_16x16x32_bf16 v[26:29], v[214:217], v[168:171], v[26:29]
	v_mfma_f32_16x16x32_bf16 v[18:21], v[206:209], v[176:179], v[18:21]
	v_mfma_f32_16x16x32_bf16 v[10:13], v[214:217], v[176:179], v[10:13]
	v_mfma_f32_16x16x32_bf16 v[6:9], v[206:209], v[184:187], v[6:9]
	v_mfma_f32_16x16x32_bf16 v[2:5], v[214:217], v[184:187], v[2:5]
	v_mfma_f32_16x16x32_bf16 v[50:53], v[210:213], v[164:167], v[50:53]
	v_mfma_f32_16x16x32_bf16 v[42:45], v[218:221], v[164:167], v[42:45]
	v_mfma_f32_16x16x32_bf16 v[34:37], v[210:213], v[172:175], v[34:37]
	v_mfma_f32_16x16x32_bf16 v[26:29], v[218:221], v[172:175], v[26:29]
	v_mfma_f32_16x16x32_bf16 v[18:21], v[210:213], v[180:183], v[18:21]
	v_mfma_f32_16x16x32_bf16 v[10:13], v[218:221], v[180:183], v[10:13]
	v_mfma_f32_16x16x32_bf16 v[6:9], v[210:213], v[188:191], v[6:9]
	v_mfma_f32_16x16x32_bf16 v[2:5], v[218:221], v[188:191], v[2:5]
	s_setprio 0
	s_barrier
	ds_read_b128 v[144:147], v253 offset:32768
	ds_read_b128 v[148:151], v253 offset:33792
	ds_read_b128 v[152:155], v253 offset:34816
	ds_read_b128 v[156:159], v253 offset:35840
	s_mov_b32 m0, s56
	ds_read_b128 v[160:163], v141 offset:32768
	ds_read_b128 v[164:167], v141 offset:33792
	ds_read_b128 v[168:171], v141 offset:34816
	ds_read_b128 v[172:175], v141 offset:35840
	ds_read_b128 v[176:179], v141 offset:36864
	ds_read_b128 v[180:183], v141 offset:37888
	ds_read_b128 v[184:187], v141 offset:38912
	ds_read_b128 v[188:191], v141 offset:39936
	global_load_lds_dwordx4 v136, s[62:63]
	s_mov_b32 m0, s57
	s_nop 0
	global_load_lds_dwordx4 v132, s[62:63]
	s_waitcnt lgkmcnt(8)
	s_barrier
	s_waitcnt lgkmcnt(0)
	s_setprio 1
	v_mfma_f32_16x16x32_bf16 v[126:129], v[144:147], v[160:163], v[126:129]
	v_mfma_f32_16x16x32_bf16 v[122:125], v[152:155], v[160:163], v[122:125]
	v_mfma_f32_16x16x32_bf16 v[118:121], v[144:147], v[168:171], v[118:121]
	v_mfma_f32_16x16x32_bf16 v[110:113], v[152:155], v[168:171], v[110:113]
	v_mfma_f32_16x16x32_bf16 v[102:105], v[144:147], v[176:179], v[102:105]
	v_mfma_f32_16x16x32_bf16 v[94:97], v[152:155], v[176:179], v[94:97]
	v_mfma_f32_16x16x32_bf16 v[86:89], v[144:147], v[184:187], v[86:89]
	v_mfma_f32_16x16x32_bf16 v[78:81], v[152:155], v[184:187], v[78:81]
	v_mfma_f32_16x16x32_bf16 v[126:129], v[148:151], v[164:167], v[126:129]
	v_mfma_f32_16x16x32_bf16 v[122:125], v[156:159], v[164:167], v[122:125]
	v_mfma_f32_16x16x32_bf16 v[118:121], v[148:151], v[172:175], v[118:121]
	v_mfma_f32_16x16x32_bf16 v[110:113], v[156:159], v[172:175], v[110:113]
	v_mfma_f32_16x16x32_bf16 v[102:105], v[148:151], v[180:183], v[102:105]
	v_mfma_f32_16x16x32_bf16 v[94:97], v[156:159], v[180:183], v[94:97]
	v_mfma_f32_16x16x32_bf16 v[86:89], v[148:151], v[188:191], v[86:89]
	v_mfma_f32_16x16x32_bf16 v[78:81], v[156:159], v[188:191], v[78:81]
	s_setprio 0
	s_barrier
	s_mov_b32 m0, s58
	ds_read_b128 v[206:209], v253 offset:49152
	ds_read_b128 v[210:213], v253 offset:50176
	v_lshl_add_u64 v[138:139], v[138:139], 0, s[76:77]
	ds_read_b128 v[214:217], v253 offset:51200
	ds_read_b128 v[218:221], v253 offset:52224
	global_load_lds_dwordx4 v[138:139], off
	v_lshl_add_u64 v[138:139], v[192:193], 0, s[76:77]
	s_mov_b32 m0, s59
	s_nop 0
	global_load_lds_dwordx4 v[138:139], off
	s_barrier
	s_waitcnt lgkmcnt(0)
	s_setprio 1
	v_mfma_f32_16x16x32_bf16 v[114:117], v[206:209], v[160:163], v[114:117]
	v_mfma_f32_16x16x32_bf16 v[106:109], v[214:217], v[160:163], v[106:109]
	v_mfma_f32_16x16x32_bf16 v[98:101], v[206:209], v[168:171], v[98:101]
	v_mfma_f32_16x16x32_bf16 v[90:93], v[214:217], v[168:171], v[90:93]
	v_mfma_f32_16x16x32_bf16 v[82:85], v[206:209], v[176:179], v[82:85]
	v_mfma_f32_16x16x32_bf16 v[74:77], v[214:217], v[176:179], v[74:77]
	v_mfma_f32_16x16x32_bf16 v[70:73], v[206:209], v[184:187], v[70:73]
	v_mfma_f32_16x16x32_bf16 v[66:69], v[214:217], v[184:187], v[66:69]
	v_mfma_f32_16x16x32_bf16 v[114:117], v[210:213], v[164:167], v[114:117]
	v_mfma_f32_16x16x32_bf16 v[106:109], v[218:221], v[164:167], v[106:109]
	v_mfma_f32_16x16x32_bf16 v[98:101], v[210:213], v[172:175], v[98:101]
	v_mfma_f32_16x16x32_bf16 v[90:93], v[218:221], v[172:175], v[90:93]
	v_mfma_f32_16x16x32_bf16 v[82:85], v[210:213], v[180:183], v[82:85]
	v_mfma_f32_16x16x32_bf16 v[74:77], v[218:221], v[180:183], v[74:77]
	v_mfma_f32_16x16x32_bf16 v[70:73], v[210:213], v[188:191], v[70:73]
	v_mfma_f32_16x16x32_bf16 v[66:69], v[218:221], v[188:191], v[66:69]
	s_setprio 0
	s_mov_b32 m0, s67
	v_lshl_add_u64 v[138:139], v[222:223], 0, s[76:77]
	s_barrier
	ds_read_b128 v[160:163], v141 offset:49152
	ds_read_b128 v[164:167], v141 offset:50176
	ds_read_b128 v[168:171], v141 offset:51200
	ds_read_b128 v[172:175], v141 offset:52224
	ds_read_b128 v[176:179], v141 offset:53248
	ds_read_b128 v[180:183], v141 offset:54272
	ds_read_b128 v[184:187], v141 offset:55296
	ds_read_b128 v[188:191], v141 offset:56320
	global_load_lds_dwordx4 v[138:139], off
	v_lshl_add_u64 v[138:139], v[224:225], 0, s[76:77]
	s_mov_b32 m0, s70
	s_nop 0
	global_load_lds_dwordx4 v[138:139], off
	s_barrier
	s_waitcnt lgkmcnt(0)
	s_setprio 1
	v_mfma_f32_16x16x32_bf16 v[62:65], v[144:147], v[160:163], v[62:65]
	v_mfma_f32_16x16x32_bf16 v[58:61], v[152:155], v[160:163], v[58:61]
	v_mfma_f32_16x16x32_bf16 v[54:57], v[144:147], v[168:171], v[54:57]
	v_mfma_f32_16x16x32_bf16 v[46:49], v[152:155], v[168:171], v[46:49]
	v_mfma_f32_16x16x32_bf16 v[38:41], v[144:147], v[176:179], v[38:41]
	v_mfma_f32_16x16x32_bf16 v[30:33], v[152:155], v[176:179], v[30:33]
	v_mfma_f32_16x16x32_bf16 v[22:25], v[144:147], v[184:187], v[22:25]
	v_mfma_f32_16x16x32_bf16 v[14:17], v[152:155], v[184:187], v[14:17]
	v_mfma_f32_16x16x32_bf16 v[62:65], v[148:151], v[164:167], v[62:65]
	v_mfma_f32_16x16x32_bf16 v[58:61], v[156:159], v[164:167], v[58:61]
	v_mfma_f32_16x16x32_bf16 v[54:57], v[148:151], v[172:175], v[54:57]
	v_mfma_f32_16x16x32_bf16 v[46:49], v[156:159], v[172:175], v[46:49]
	v_mfma_f32_16x16x32_bf16 v[38:41], v[148:151], v[180:183], v[38:41]
	v_mfma_f32_16x16x32_bf16 v[30:33], v[156:159], v[180:183], v[30:33]
	v_mfma_f32_16x16x32_bf16 v[22:25], v[148:151], v[188:191], v[22:25]
	v_mfma_f32_16x16x32_bf16 v[14:17], v[156:159], v[188:191], v[14:17]
	s_setprio 0
	s_barrier
	s_mov_b32 m0, s71
	s_nop 0
	global_load_lds_dwordx4 v134, s[8:9]
	s_mov_b32 m0, s78
	s_nop 0
	global_load_lds_dwordx4 v130, s[8:9]
	s_waitcnt vmcnt(6)
	s_barrier
	s_setprio 1
	v_mfma_f32_16x16x32_bf16 v[50:53], v[206:209], v[160:163], v[50:53]
	v_mfma_f32_16x16x32_bf16 v[42:45], v[214:217], v[160:163], v[42:45]
	v_mfma_f32_16x16x32_bf16 v[34:37], v[206:209], v[168:171], v[34:37]
	v_mfma_f32_16x16x32_bf16 v[26:29], v[214:217], v[168:171], v[26:29]
	v_mfma_f32_16x16x32_bf16 v[18:21], v[206:209], v[176:179], v[18:21]
	v_mfma_f32_16x16x32_bf16 v[10:13], v[214:217], v[176:179], v[10:13]
	v_mfma_f32_16x16x32_bf16 v[6:9], v[206:209], v[184:187], v[6:9]
	v_mfma_f32_16x16x32_bf16 v[2:5], v[214:217], v[184:187], v[2:5]
	v_mfma_f32_16x16x32_bf16 v[50:53], v[210:213], v[164:167], v[50:53]
	v_mfma_f32_16x16x32_bf16 v[42:45], v[218:221], v[164:167], v[42:45]
	v_mfma_f32_16x16x32_bf16 v[34:37], v[210:213], v[172:175], v[34:37]
	v_mfma_f32_16x16x32_bf16 v[26:29], v[218:221], v[172:175], v[26:29]
	v_mfma_f32_16x16x32_bf16 v[18:21], v[210:213], v[180:183], v[18:21]
	v_mfma_f32_16x16x32_bf16 v[10:13], v[218:221], v[180:183], v[10:13]
	v_mfma_f32_16x16x32_bf16 v[6:9], v[210:213], v[188:191], v[6:9]
	v_mfma_f32_16x16x32_bf16 v[2:5], v[218:221], v[188:191], v[2:5]
	s_setprio 0
	s_andn2_b64 vcc, exec, s[60:61]
	s_mov_b64 s[8:9], -1
	s_mov_b64 s[60:61], 0
	s_mov_b64 s[62:63], 0x100
	s_barrier
	s_cbranch_vccz .LBB0_204
	s_cmp_gt_i32 s29, 63
	s_cbranch_scc0 .LBB0_207
	s_lshl_b32 s8, s29, 10
	s_lshl_b32 s9, s94, 8
	s_add_i32 s9, s9, s8
	v_add_u32_e32 v138, s9, v143
	v_ashrrev_i32_e32 v139, 31, v138
	v_lshlrev_b64 v[138:139], 10, v[138:139]
	s_lshl_b32 s8, s42, 8
	v_lshl_add_u64 v[138:139], s[64:65], 0, v[138:139]
	s_ashr_i32 s9, s8, 31
	v_lshl_add_u64 v[138:139], s[8:9], 1, v[138:139]
	s_mov_b64 s[8:9], 0

.LBB0_251:
	v_lshrrev_b32_e32 v18, 1, v8
	v_and_b32_e32 v18, 24, v18
	v_readlane_b32 s8, v251, 27
	v_and_b32_e32 v9, 15, v8
	v_lshlrev_b32_e32 v19, 1, v18
	v_lshlrev_b32_e32 v8, 2, v8
	s_lshl_b32 s0, s0, 5
	v_mov_b32_e32 v163, v195
	v_readlane_b32 s9, v251, 28
	v_lshl_or_b32 v180, s1, 6, v9
	v_lshl_or_b32 v9, v9, 6, v19
	s_lshl_b32 s1, s1, 13
	v_and_b32_e32 v8, 32, v8
	s_and_b32 s0, s0, 0x60
	v_lshl_add_u64 v[10:11], s[8:9], 0, v[162:163]
	v_mov_b32_e32 v159, v195
	v_readlane_b32 s6, v251, 23
	v_bitop3_b32 v181, v9, s1, v8 bitop3:0xde
	s_lshl_b32 s1, s0, 7
	s_add_i32 s55, s5, 0x18000
	v_lshl_add_u64 v[12:13], s[8:9], 0, v[158:159]
	v_mov_b32_e32 v165, v195
	v_readlane_b32 s7, v251, 24
	v_bitop3_b32 v182, v9, s1, v8 bitop3:0xde
	v_lshl_add_u64 v[8:9], v[10:11], 0, s[76:77]
	s_mov_b32 m0, s55
	s_add_i32 s56, s5, 0x1a000
	v_lshl_add_u64 v[14:15], s[6:7], 0, v[164:165]
	v_mov_b32_e32 v161, v195
	s_waitcnt vmcnt(0)
	s_barrier
	global_load_lds_dwordx4 v[8:9], off
	v_lshl_add_u64 v[8:9], v[12:13], 0, s[76:77]
	s_mov_b32 m0, s56
	s_add_i32 s57, s5, 0x8000
	v_lshl_add_u64 v[16:17], s[6:7], 0, v[160:161]
	global_load_lds_dwordx4 v[8:9], off
	v_lshl_add_u64 v[8:9], v[14:15], 0, s[76:77]
	s_mov_b32 m0, s57
	s_add_i32 s58, s5, 0xa000
	v_readlane_b32 s10, v251, 29
	global_load_lds_dwordx4 v[8:9], off
	v_lshl_add_u64 v[8:9], v[16:17], 0, s[76:77]
	s_mov_b32 m0, s58
	s_add_i32 s59, s5, 0x1c000
	v_readlane_b32 s11, v251, 30
	global_load_lds_dwordx4 v[8:9], off
	s_nop 0
	v_lshl_add_u64 v[8:9], s[10:11], 0, v[162:163]
	s_mov_b32 m0, s59
	s_add_i32 s67, s5, 0x1e000
	global_load_lds_dwordx4 v[8:9], off
	v_lshl_add_u64 v[8:9], s[10:11], 0, v[158:159]
	s_mov_b32 m0, s67
	v_or_b32_e32 v183, s0, v18
	global_load_lds_dwordx4 v[8:9], off
	v_lshlrev_b32_e32 v8, 16, v5
	v_and_b32_e32 v8, 0xfffe0000, v8
	v_lshl_add_u32 v6, v6, 13, v8
	v_and_b32_e32 v5, 1, v5
	v_lshl_or_b32 v5, v5, 6, v6
	v_lshl_add_u32 v166, v7, 1, v5
	v_lshlrev_b32_e32 v5, 16, v2
	v_and_b32_e32 v5, 0xfffe0000, v5
	s_waitcnt vmcnt(6)
	v_lshl_add_u32 v3, v3, 13, v5
	v_and_b32_e32 v2, 1, v2
	v_lshl_or_b32 v2, v2, 6, v3
	v_readlane_b32 s0, v251, 19
	v_mov_b32_e32 v167, v195
	v_lshl_add_u32 v168, v4, 1, v2
	v_mov_b32_e32 v169, v195
	s_mov_b32 s70, 0
	v_readlane_b32 s29, v251, 17
	s_mov_b32 s28, s0
	s_mov_b64 s[60:61], s[8:9]
	s_mov_b64 s[52:53], s[6:7]
	s_barrier
	v_readlane_b32 s1, v251, 20

.LBB0_255:
	v_add_u32_e32 v253, 0x10000, v182
	ds_read_b128 v[130:133], v253
	ds_read_b128 v[134:137], v253 offset:1024
	ds_read_b128 v[138:141], v253 offset:2048
	ds_read_b128 v[142:145], v253 offset:3072
	ds_read_b128 v[146:149], v181
	ds_read_b128 v[150:153], v181 offset:1024
	ds_read_b128 v[154:157], v181 offset:2048
	ds_read_b128 v[170:173], v181 offset:3072
	ds_read_b128 v[174:177], v181 offset:4096
	ds_read_b128 v[184:187], v181 offset:5120
	ds_read_b128 v[188:191], v181 offset:6144
	ds_read_b128 v[206:209], v181 offset:7168
	ds_read_b128 v[210:213], v253 offset:16384
	ds_read_b128 v[214:217], v253 offset:17408
	ds_read_b128 v[218:221], v253 offset:18432
	ds_read_b128 v[222:225], v253 offset:19456
	s_add_u32 s8, s6, 0xfff00080
	s_addc_u32 s9, s7, -1
	s_cmp_eq_u32 s79, 60
	s_cselect_b32 s11, s53, s9
	s_cselect_b32 s10, s52, s8
	s_cselect_b32 s9, s61, s78
	s_cselect_b32 s8, s60, s1
	s_add_i32 m0, s5, 0xc000
	s_nop 0
	global_load_lds_dwordx4 v166, s[6:7]
	s_add_i32 m0, s5, 0xe000
	s_nop 0
	global_load_lds_dwordx4 v168, s[6:7]
	s_waitcnt vmcnt(8)
	s_waitcnt lgkmcnt(0)
	s_setprio 1
	s_barrier
	v_mfma_f32_16x16x32_bf16 v[126:129], v[130:133], v[146:149], v[126:129]
	v_mfma_f32_16x16x32_bf16 v[122:125], v[138:141], v[146:149], v[122:125]
	v_mfma_f32_16x16x32_bf16 v[110:113], v[130:133], v[154:157], v[110:113]
	v_mfma_f32_16x16x32_bf16 v[106:109], v[138:141], v[154:157], v[106:109]
	v_mfma_f32_16x16x32_bf16 v[94:97], v[130:133], v[174:177], v[94:97]
	v_mfma_f32_16x16x32_bf16 v[90:93], v[138:141], v[174:177], v[90:93]
	v_mfma_f32_16x16x32_bf16 v[78:81], v[130:133], v[188:191], v[78:81]
	v_mfma_f32_16x16x32_bf16 v[74:77], v[138:141], v[188:191], v[74:77]
	v_mfma_f32_16x16x32_bf16 v[126:129], v[134:137], v[150:153], v[126:129]
	v_mfma_f32_16x16x32_bf16 v[122:125], v[142:145], v[150:153], v[122:125]
	v_mfma_f32_16x16x32_bf16 v[110:113], v[134:137], v[170:173], v[110:113]
	v_mfma_f32_16x16x32_bf16 v[106:109], v[142:145], v[170:173], v[106:109]
	v_mfma_f32_16x16x32_bf16 v[94:97], v[134:137], v[184:187], v[94:97]
	v_mfma_f32_16x16x32_bf16 v[90:93], v[142:145], v[184:187], v[90:93]
	v_mfma_f32_16x16x32_bf16 v[78:81], v[134:137], v[206:209], v[78:81]
	v_mfma_f32_16x16x32_bf16 v[74:77], v[142:145], v[206:209], v[74:77]
	v_mfma_f32_16x16x32_bf16 v[118:121], v[210:213], v[146:149], v[118:121]
	v_mfma_f32_16x16x32_bf16 v[114:117], v[218:221], v[146:149], v[114:117]
	v_mfma_f32_16x16x32_bf16 v[102:105], v[210:213], v[154:157], v[102:105]
	v_mfma_f32_16x16x32_bf16 v[98:101], v[218:221], v[154:157], v[98:101]
	v_mfma_f32_16x16x32_bf16 v[86:89], v[210:213], v[174:177], v[86:89]
	v_mfma_f32_16x16x32_bf16 v[82:85], v[218:221], v[174:177], v[82:85]
	v_mfma_f32_16x16x32_bf16 v[70:73], v[210:213], v[188:191], v[70:73]
	v_mfma_f32_16x16x32_bf16 v[66:69], v[218:221], v[188:191], v[66:69]
	v_mfma_f32_16x16x32_bf16 v[118:121], v[214:217], v[150:153], v[118:121]
	v_mfma_f32_16x16x32_bf16 v[114:117], v[222:225], v[150:153], v[114:117]
	v_mfma_f32_16x16x32_bf16 v[102:105], v[214:217], v[170:173], v[102:105]
	v_mfma_f32_16x16x32_bf16 v[98:101], v[222:225], v[170:173], v[98:101]
	v_mfma_f32_16x16x32_bf16 v[86:89], v[214:217], v[184:187], v[86:89]
	v_mfma_f32_16x16x32_bf16 v[82:85], v[222:225], v[184:187], v[82:85]
	v_mfma_f32_16x16x32_bf16 v[70:73], v[214:217], v[206:209], v[70:73]
	v_mfma_f32_16x16x32_bf16 v[66:69], v[222:225], v[206:209], v[66:69]
	s_setprio 0
	s_barrier
	ds_read_b128 v[146:149], v181 offset:16384
	ds_read_b128 v[150:153], v181 offset:17408
	ds_read_b128 v[154:157], v181 offset:18432
	ds_read_b128 v[170:173], v181 offset:19456
	ds_read_b128 v[174:177], v181 offset:20480
	ds_read_b128 v[184:187], v181 offset:21504
	ds_read_b128 v[188:191], v181 offset:22528
	ds_read_b128 v[206:209], v181 offset:23552
	s_mov_b32 m0, s12
	s_nop 0
	global_load_lds_dwordx4 v162, s[8:9]
	s_mov_b32 m0, s17
	s_nop 0
	global_load_lds_dwordx4 v158, s[8:9]
	s_mov_b32 m0, s5
	s_nop 0
	global_load_lds_dwordx4 v164, s[10:11]
	s_mov_b32 m0, s26
	s_nop 0
	global_load_lds_dwordx4 v160, s[10:11]
	s_add_u32 s80, s8, 0x100000
	s_addc_u32 s81, s9, 0
	s_mov_b32 m0, s34
	s_nop 0
	global_load_lds_dwordx4 v162, s[80:81]
	s_mov_b32 m0, s35
	s_nop 0
	global_load_lds_dwordx4 v158, s[80:81]
	s_waitcnt vmcnt(8)
	s_waitcnt lgkmcnt(0)
	s_setprio 1
	s_barrier
	v_mfma_f32_16x16x32_bf16 v[62:65], v[130:133], v[146:149], v[62:65]
	v_mfma_f32_16x16x32_bf16 v[58:61], v[138:141], v[146:149], v[58:61]
	v_mfma_f32_16x16x32_bf16 v[46:49], v[130:133], v[154:157], v[46:49]
	v_mfma_f32_16x16x32_bf16 v[42:45], v[138:141], v[154:157], v[42:45]
	v_mfma_f32_16x16x32_bf16 v[30:33], v[130:133], v[174:177], v[30:33]
	v_mfma_f32_16x16x32_bf16 v[26:29], v[138:141], v[174:177], v[26:29]
	v_mfma_f32_16x16x32_bf16 v[14:17], v[130:133], v[188:191], v[14:17]
	v_mfma_f32_16x16x32_bf16 v[10:13], v[138:141], v[188:191], v[10:13]
	v_mfma_f32_16x16x32_bf16 v[62:65], v[134:137], v[150:153], v[62:65]
	v_mfma_f32_16x16x32_bf16 v[58:61], v[142:145], v[150:153], v[58:61]
	v_mfma_f32_16x16x32_bf16 v[46:49], v[134:137], v[170:173], v[46:49]
	v_mfma_f32_16x16x32_bf16 v[42:45], v[142:145], v[170:173], v[42:45]
	v_mfma_f32_16x16x32_bf16 v[30:33], v[134:137], v[184:187], v[30:33]
	v_mfma_f32_16x16x32_bf16 v[26:29], v[142:145], v[184:187], v[26:29]
	v_mfma_f32_16x16x32_bf16 v[14:17], v[134:137], v[206:209], v[14:17]
	v_mfma_f32_16x16x32_bf16 v[10:13], v[142:145], v[206:209], v[10:13]
	v_mfma_f32_16x16x32_bf16 v[54:57], v[210:213], v[146:149], v[54:57]
	v_mfma_f32_16x16x32_bf16 v[50:53], v[218:221], v[146:149], v[50:53]
	v_mfma_f32_16x16x32_bf16 v[38:41], v[210:213], v[154:157], v[38:41]
	v_mfma_f32_16x16x32_bf16 v[34:37], v[218:221], v[154:157], v[34:37]
	v_mfma_f32_16x16x32_bf16 v[22:25], v[210:213], v[174:177], v[22:25]
	v_mfma_f32_16x16x32_bf16 v[18:21], v[218:221], v[174:177], v[18:21]
	v_mfma_f32_16x16x32_bf16 v[6:9], v[210:213], v[188:191], v[6:9]
	v_mfma_f32_16x16x32_bf16 v[2:5], v[218:221], v[188:191], v[2:5]
	v_mfma_f32_16x16x32_bf16 v[54:57], v[214:217], v[150:153], v[54:57]
	v_mfma_f32_16x16x32_bf16 v[50:53], v[222:225], v[150:153], v[50:53]
	v_mfma_f32_16x16x32_bf16 v[38:41], v[214:217], v[170:173], v[38:41]
	v_mfma_f32_16x16x32_bf16 v[34:37], v[222:225], v[170:173], v[34:37]
	v_mfma_f32_16x16x32_bf16 v[22:25], v[214:217], v[184:187], v[22:25]
	v_mfma_f32_16x16x32_bf16 v[18:21], v[222:225], v[184:187], v[18:21]
	v_mfma_f32_16x16x32_bf16 v[6:9], v[214:217], v[206:209], v[6:9]
	v_mfma_f32_16x16x32_bf16 v[2:5], v[222:225], v[206:209], v[2:5]
	s_setprio 0
	s_barrier
	ds_read_b128 v[130:133], v253 offset:32768
	ds_read_b128 v[134:137], v253 offset:33792
	ds_read_b128 v[138:141], v253 offset:34816
	ds_read_b128 v[142:145], v253 offset:35840
	ds_read_b128 v[146:149], v181 offset:32768
	ds_read_b128 v[150:153], v181 offset:33792
	ds_read_b128 v[154:157], v181 offset:34816
	ds_read_b128 v[170:173], v181 offset:35840
	ds_read_b128 v[174:177], v181 offset:36864
	ds_read_b128 v[184:187], v181 offset:37888
	ds_read_b128 v[188:191], v181 offset:38912
	ds_read_b128 v[206:209], v181 offset:39936
	ds_read_b128 v[210:213], v253 offset:49152
	ds_read_b128 v[214:217], v253 offset:50176
	ds_read_b128 v[218:221], v253 offset:51200
	ds_read_b128 v[222:225], v253 offset:52224
	s_add_u32 s10, s10, 0x100000
	s_addc_u32 s11, s11, 0
	s_mov_b32 m0, s42
	s_nop 0
	global_load_lds_dwordx4 v164, s[10:11]
	s_mov_b32 m0, s54
	s_nop 0
	global_load_lds_dwordx4 v160, s[10:11]
	s_waitcnt vmcnt(8)
	s_waitcnt lgkmcnt(0)
	s_setprio 1
	s_barrier
	v_mfma_f32_16x16x32_bf16 v[126:129], v[130:133], v[146:149], v[126:129]
	v_mfma_f32_16x16x32_bf16 v[122:125], v[138:141], v[146:149], v[122:125]
	v_mfma_f32_16x16x32_bf16 v[110:113], v[130:133], v[154:157], v[110:113]
	v_mfma_f32_16x16x32_bf16 v[106:109], v[138:141], v[154:157], v[106:109]
	v_mfma_f32_16x16x32_bf16 v[94:97], v[130:133], v[174:177], v[94:97]
	v_mfma_f32_16x16x32_bf16 v[90:93], v[138:141], v[174:177], v[90:93]
	v_mfma_f32_16x16x32_bf16 v[78:81], v[130:133], v[188:191], v[78:81]
	v_mfma_f32_16x16x32_bf16 v[74:77], v[138:141], v[188:191], v[74:77]
	v_mfma_f32_16x16x32_bf16 v[126:129], v[134:137], v[150:153], v[126:129]
	v_mfma_f32_16x16x32_bf16 v[122:125], v[142:145], v[150:153], v[122:125]
	v_mfma_f32_16x16x32_bf16 v[110:113], v[134:137], v[170:173], v[110:113]
	v_mfma_f32_16x16x32_bf16 v[106:109], v[142:145], v[170:173], v[106:109]
	v_mfma_f32_16x16x32_bf16 v[94:97], v[134:137], v[184:187], v[94:97]
	v_mfma_f32_16x16x32_bf16 v[90:93], v[142:145], v[184:187], v[90:93]
	v_mfma_f32_16x16x32_bf16 v[78:81], v[134:137], v[206:209], v[78:81]
	v_mfma_f32_16x16x32_bf16 v[74:77], v[142:145], v[206:209], v[74:77]
	v_mfma_f32_16x16x32_bf16 v[118:121], v[210:213], v[146:149], v[118:121]
	v_mfma_f32_16x16x32_bf16 v[114:117], v[218:221], v[146:149], v[114:117]
	v_mfma_f32_16x16x32_bf16 v[102:105], v[210:213], v[154:157], v[102:105]
	v_mfma_f32_16x16x32_bf16 v[98:101], v[218:221], v[154:157], v[98:101]
	v_mfma_f32_16x16x32_bf16 v[86:89], v[210:213], v[174:177], v[86:89]
	v_mfma_f32_16x16x32_bf16 v[82:85], v[218:221], v[174:177], v[82:85]
	v_mfma_f32_16x16x32_bf16 v[70:73], v[210:213], v[188:191], v[70:73]
	v_mfma_f32_16x16x32_bf16 v[66:69], v[218:221], v[188:191], v[66:69]
	v_mfma_f32_16x16x32_bf16 v[118:121], v[214:217], v[150:153], v[118:121]
	v_mfma_f32_16x16x32_bf16 v[114:117], v[222:225], v[150:153], v[114:117]
	v_mfma_f32_16x16x32_bf16 v[102:105], v[214:217], v[170:173], v[102:105]
	v_mfma_f32_16x16x32_bf16 v[98:101], v[222:225], v[170:173], v[98:101]
	v_mfma_f32_16x16x32_bf16 v[86:89], v[214:217], v[184:187], v[86:89]
	v_mfma_f32_16x16x32_bf16 v[82:85], v[222:225], v[184:187], v[82:85]
	v_mfma_f32_16x16x32_bf16 v[70:73], v[214:217], v[206:209], v[70:73]
	v_mfma_f32_16x16x32_bf16 v[66:69], v[222:225], v[206:209], v[66:69]
	s_setprio 0
	s_barrier
	ds_read_b128 v[146:149], v181 offset:49152
	ds_read_b128 v[150:153], v181 offset:50176
	ds_read_b128 v[154:157], v181 offset:51200
	ds_read_b128 v[170:173], v181 offset:52224
	ds_read_b128 v[174:177], v181 offset:53248
	ds_read_b128 v[184:187], v181 offset:54272
	ds_read_b128 v[188:191], v181 offset:55296
	ds_read_b128 v[206:209], v181 offset:56320
	s_mov_b32 m0, s55
	s_add_u32 s98, s8, 0x80
	s_addc_u32 s99, s9, 0
	global_load_lds_dwordx4 v162, s[98:99]
	s_mov_b32 m0, s56
	s_nop 0
	global_load_lds_dwordx4 v158, s[98:99]
	s_mov_b32 m0, s57
	s_add_u32 s100, s10, 0xfff00080
	s_addc_u32 s101, s11, -1
	global_load_lds_dwordx4 v164, s[100:101]
	s_mov_b32 m0, s58
	s_nop 0
	global_load_lds_dwordx4 v160, s[100:101]
	s_add_u32 s8, s8, 0x100080
	s_addc_u32 s9, s9, 0
	s_mov_b32 m0, s59
	s_nop 0
	global_load_lds_dwordx4 v162, s[8:9]
	s_mov_b32 m0, s67
	s_nop 0
	global_load_lds_dwordx4 v158, s[8:9]
	s_waitcnt vmcnt(8)
	s_waitcnt lgkmcnt(0)
	s_setprio 1
	s_barrier
	v_mfma_f32_16x16x32_bf16 v[62:65], v[130:133], v[146:149], v[62:65]
	v_mfma_f32_16x16x32_bf16 v[58:61], v[138:141], v[146:149], v[58:61]
	v_mfma_f32_16x16x32_bf16 v[46:49], v[130:133], v[154:157], v[46:49]
	v_mfma_f32_16x16x32_bf16 v[42:45], v[138:141], v[154:157], v[42:45]
	v_mfma_f32_16x16x32_bf16 v[30:33], v[130:133], v[174:177], v[30:33]
	v_mfma_f32_16x16x32_bf16 v[26:29], v[138:141], v[174:177], v[26:29]
	v_mfma_f32_16x16x32_bf16 v[14:17], v[130:133], v[188:191], v[14:17]
	v_mfma_f32_16x16x32_bf16 v[10:13], v[138:141], v[188:191], v[10:13]
	v_mfma_f32_16x16x32_bf16 v[62:65], v[134:137], v[150:153], v[62:65]
	v_mfma_f32_16x16x32_bf16 v[58:61], v[142:145], v[150:153], v[58:61]
	v_mfma_f32_16x16x32_bf16 v[46:49], v[134:137], v[170:173], v[46:49]
	v_mfma_f32_16x16x32_bf16 v[42:45], v[142:145], v[170:173], v[42:45]
	v_mfma_f32_16x16x32_bf16 v[30:33], v[134:137], v[184:187], v[30:33]
	v_mfma_f32_16x16x32_bf16 v[26:29], v[142:145], v[184:187], v[26:29]
	v_mfma_f32_16x16x32_bf16 v[14:17], v[134:137], v[206:209], v[14:17]
	v_mfma_f32_16x16x32_bf16 v[10:13], v[142:145], v[206:209], v[10:13]
	v_mfma_f32_16x16x32_bf16 v[54:57], v[210:213], v[146:149], v[54:57]
	v_mfma_f32_16x16x32_bf16 v[50:53], v[218:221], v[146:149], v[50:53]
	v_mfma_f32_16x16x32_bf16 v[38:41], v[210:213], v[154:157], v[38:41]
	v_mfma_f32_16x16x32_bf16 v[34:37], v[218:221], v[154:157], v[34:37]
	v_mfma_f32_16x16x32_bf16 v[22:25], v[210:213], v[174:177], v[22:25]
	v_mfma_f32_16x16x32_bf16 v[18:21], v[218:221], v[174:177], v[18:21]
	v_mfma_f32_16x16x32_bf16 v[6:9], v[210:213], v[188:191], v[6:9]
	v_mfma_f32_16x16x32_bf16 v[2:5], v[218:221], v[188:191], v[2:5]
	v_mfma_f32_16x16x32_bf16 v[54:57], v[214:217], v[150:153], v[54:57]
	v_mfma_f32_16x16x32_bf16 v[50:53], v[222:225], v[150:153], v[50:53]
	v_mfma_f32_16x16x32_bf16 v[38:41], v[214:217], v[170:173], v[38:41]
	v_mfma_f32_16x16x32_bf16 v[34:37], v[222:225], v[170:173], v[34:37]
	v_mfma_f32_16x16x32_bf16 v[22:25], v[214:217], v[184:187], v[22:25]
	v_mfma_f32_16x16x32_bf16 v[18:21], v[222:225], v[184:187], v[18:21]
	v_mfma_f32_16x16x32_bf16 v[6:9], v[214:217], v[206:209], v[6:9]
	v_mfma_f32_16x16x32_bf16 v[2:5], v[222:225], v[206:209], v[2:5]
	s_setprio 0
	s_add_i32 s79, s79, 2
	s_add_u32 s6, s6, 0x100
	s_addc_u32 s7, s7, 0
	s_add_u32 s1, s1, 0x100
	s_addc_u32 s78, s78, 0
	s_cmp_gt_u32 s79, 61
	s_barrier
	s_cbranch_scc0 .LBB0_255
	s_lshl_b32 s1, s28, 9
	s_and_b32 s1, s1, 0xfffff800
	s_lshl_b32 s6, s29, 8
	s_add_i32 s1, s1, s6
	v_add_u32_e32 v172, s1, v180
	s_lshl_b32 s1, s28, 8
	s_and_b32 s1, s1, 0x300
	v_or_b32_e32 v132, s1, v183
	v_mov_b64_e32 v[170:171], s[50:51]
	v_mad_i64_i32 v[130:131], s[6:7], v172, s37, v[170:171]
	v_lshlrev_b32_e32 v194, 1, v132
	v_lshl_add_u64 v[130:131], v[130:131], 0, v[194:195]
	v_lshl_add_u64 v[132:133], v[130:131], 0, s[84:85]
	v_add_co_u32_e32 v130, vcc, s16, v130
	v_or_b32_e32 v178, 16, v172
	s_nop 0
	v_addc_co_u32_e32 v131, vcc, 0, v131, vcc
	global_load_dwordx4 v[184:187], v[130:131], off offset:2048
	global_load_dwordx4 v[154:157], v[132:133], off offset:256
	v_mad_i64_i32 v[130:131], s[6:7], v178, s37, v[170:171]
	v_lshl_add_u64 v[130:131], v[130:131], 0, v[194:195]
	v_lshl_add_u64 v[132:133], v[130:131], 0, s[84:85]
	v_add_co_u32_e32 v130, vcc, s16, v130
	v_or_b32_e32 v176, 32, v172
	s_nop 0
	v_addc_co_u32_e32 v131, vcc, 0, v131, vcc
	global_load_dwordx4 v[150:153], v[130:131], off offset:2048
	global_load_dwordx4 v[146:149], v[132:133], off offset:256
	v_mad_i64_i32 v[130:131], s[6:7], v176, s37, v[170:171]
	v_lshl_add_u64 v[130:131], v[130:131], 0, v[194:195]
	v_lshl_add_u64 v[132:133], v[130:131], 0, s[84:85]
	v_add_co_u32_e32 v130, vcc, s16, v130
	v_or_b32_e32 v174, 48, v172
	s_nop 0
	v_addc_co_u32_e32 v131, vcc, 0, v131, vcc
	global_load_dwordx4 v[142:145], v[130:131], off offset:2048
	global_load_dwordx4 v[138:141], v[132:133], off offset:256
	v_mad_i64_i32 v[130:131], s[6:7], v174, s37, v[170:171]
	v_lshl_add_u64 v[130:131], v[130:131], 0, v[194:195]
	v_lshl_add_u64 v[132:133], v[130:131], 0, s[84:85]
	v_add_co_u32_e32 v130, vcc, s16, v130
	v_pk_mul_f32 v[126:127], v[126:127], s[72:73] op_sel_hi:[1,0]
	s_nop 0
	v_addc_co_u32_e32 v131, vcc, 0, v131, vcc
	global_load_dwordx4 v[134:137], v[130:131], off offset:2048
	s_nop 0
	global_load_dwordx4 v[130:133], v[132:133], off offset:256
	v_pk_mul_f32 v[190:191], v[124:125], s[72:73] op_sel_hi:[1,0]
	v_pk_mul_f32 v[128:129], v[128:129], s[72:73] op_sel_hi:[1,0]
	v_pk_mul_f32 v[122:123], v[122:123], s[72:73] op_sel_hi:[1,0]
	v_ashrrev_i32_e32 v173, 31, v172
	v_lshlrev_b64 v[188:189], 11, v[172:173]
	v_pk_mul_f32 v[118:119], v[118:119], s[72:73] op_sel_hi:[1,0]
	v_pk_mul_f32 v[120:121], v[120:121], s[72:73] op_sel_hi:[1,0]
	v_pk_mul_f32 v[110:111], v[110:111], s[72:73] op_sel_hi:[1,0]
	v_pk_mul_f32 v[112:113], v[112:113], s[72:73] op_sel_hi:[1,0]
	v_ashrrev_i32_e32 v179, 31, v178
	v_pk_mul_f32 v[102:103], v[102:103], s[72:73] op_sel_hi:[1,0]
	v_pk_mul_f32 v[104:105], v[104:105], s[72:73] op_sel_hi:[1,0]
	v_pk_mul_f32 v[94:95], v[94:95], s[72:73] op_sel_hi:[1,0]
	v_pk_mul_f32 v[96:97], v[96:97], s[72:73] op_sel_hi:[1,0]
	v_ashrrev_i32_e32 v177, 31, v176
	v_pk_mul_f32 v[86:87], v[86:87], s[72:73] op_sel_hi:[1,0]
	v_pk_mul_f32 v[88:89], v[88:89], s[72:73] op_sel_hi:[1,0]
	v_pk_mul_f32 v[78:79], v[78:79], s[72:73] op_sel_hi:[1,0]
	v_pk_mul_f32 v[80:81], v[80:81], s[72:73] op_sel_hi:[1,0]
	v_ashrrev_i32_e32 v175, 31, v174
	v_pk_mul_f32 v[70:71], v[70:71], s[72:73] op_sel_hi:[1,0]
	v_pk_mul_f32 v[72:73], v[72:73], s[72:73] op_sel_hi:[1,0]
	s_waitcnt vmcnt(0)
	v_lshlrev_b32_e32 v124, 16, v184
	v_and_b32_e32 v125, 0xffff0000, v184
	v_mul_f32_e32 v124, v126, v124
	v_mul_f32_e32 v125, v127, v125
	v_cvt_pk_bf16_f32 v124, v124, v125
	v_lshlrev_b32_e32 v125, 16, v185
	v_and_b32_e32 v126, 0xffff0000, v185
	v_mul_f32_e32 v125, v128, v125
	v_mul_f32_e32 v126, v129, v126
	v_cvt_pk_bf16_f32 v125, v125, v126
	v_lshlrev_b32_e32 v126, 16, v186
	v_mul_f32_e32 v122, v122, v126
	v_and_b32_e32 v126, 0xffff0000, v186
	v_mul_f32_e32 v123, v123, v126
	v_cvt_pk_bf16_f32 v126, v122, v123
	v_lshlrev_b32_e32 v122, 16, v187
	v_and_b32_e32 v123, 0xffff0000, v187
	v_mul_f32_e32 v122, v190, v122
	v_mul_f32_e32 v123, v191, v123
	v_cvt_pk_bf16_f32 v127, v122, v123
	v_lshl_add_u64 v[122:123], s[74:75], 0, v[188:189]
	v_lshl_add_u64 v[122:123], v[122:123], 0, v[194:195]
	global_store_dwordx4 v[122:123], v[124:127], off
	s_nop 1
	v_pk_mul_f32 v[124:125], v[116:117], s[72:73] op_sel_hi:[1,0]
	v_pk_mul_f32 v[116:117], v[114:115], s[72:73] op_sel_hi:[1,0]
	v_lshlrev_b32_e32 v114, 16, v154
	v_and_b32_e32 v115, 0xffff0000, v154
	v_mul_f32_e32 v114, v118, v114
	v_mul_f32_e32 v115, v119, v115
	v_cvt_pk_bf16_f32 v114, v114, v115
	v_lshlrev_b32_e32 v115, 16, v155
	v_and_b32_e32 v118, 0xffff0000, v155
	v_mul_f32_e32 v115, v120, v115
	v_mul_f32_e32 v118, v121, v118
	v_cvt_pk_bf16_f32 v115, v115, v118
	v_lshlrev_b32_e32 v118, 16, v156
	v_mul_f32_e32 v116, v116, v118
	v_and_b32_e32 v118, 0xffff0000, v156
	v_mul_f32_e32 v117, v117, v118
	v_cvt_pk_bf16_f32 v116, v116, v117
	v_lshlrev_b32_e32 v117, 16, v157
	v_mul_f32_e32 v117, v124, v117
	v_and_b32_e32 v118, 0xffff0000, v157
	v_mul_f32_e32 v118, v125, v118
	v_cvt_pk_bf16_f32 v117, v117, v118
	global_store_dwordx4 v[122:123], v[114:117], off offset:256
	s_nop 1
	v_pk_mul_f32 v[116:117], v[108:109], s[72:73] op_sel_hi:[1,0]
	v_pk_mul_f32 v[108:109], v[106:107], s[72:73] op_sel_hi:[1,0]
	v_lshlrev_b32_e32 v106, 16, v150
	v_and_b32_e32 v107, 0xffff0000, v150
	v_mul_f32_e32 v106, v110, v106
	v_mul_f32_e32 v107, v111, v107
	v_cvt_pk_bf16_f32 v106, v106, v107
	v_lshlrev_b32_e32 v107, 16, v151
	v_and_b32_e32 v110, 0xffff0000, v151
	v_mul_f32_e32 v107, v112, v107
	v_mul_f32_e32 v110, v113, v110
	v_cvt_pk_bf16_f32 v107, v107, v110
	v_lshlrev_b32_e32 v110, 16, v152
	v_mul_f32_e32 v108, v108, v110
	v_and_b32_e32 v110, 0xffff0000, v152
	v_mul_f32_e32 v109, v109, v110
	v_cvt_pk_bf16_f32 v108, v108, v109
	v_lshlrev_b32_e32 v109, 16, v153
	v_and_b32_e32 v110, 0xffff0000, v153
	v_lshlrev_b64 v[114:115], 11, v[178:179]
	v_mul_f32_e32 v109, v116, v109
	v_mul_f32_e32 v110, v117, v110
	v_cvt_pk_bf16_f32 v109, v109, v110
	v_lshl_add_u64 v[110:111], s[74:75], 0, v[114:115]
	v_lshl_add_u64 v[110:111], v[110:111], 0, v[194:195]
	global_store_dwordx4 v[110:111], v[106:109], off
	s_nop 1
	v_pk_mul_f32 v[106:107], v[100:101], s[72:73] op_sel_hi:[1,0]
	v_pk_mul_f32 v[100:101], v[98:99], s[72:73] op_sel_hi:[1,0]
	v_lshlrev_b32_e32 v98, 16, v146
	v_and_b32_e32 v99, 0xffff0000, v146
	v_mul_f32_e32 v98, v102, v98
	v_mul_f32_e32 v99, v103, v99
	v_cvt_pk_bf16_f32 v98, v98, v99
	v_lshlrev_b32_e32 v99, 16, v147
	v_and_b32_e32 v102, 0xffff0000, v147
	v_mul_f32_e32 v99, v104, v99
	v_mul_f32_e32 v102, v105, v102
	v_cvt_pk_bf16_f32 v99, v99, v102
	v_lshlrev_b32_e32 v102, 16, v148
	v_mul_f32_e32 v100, v100, v102
	v_and_b32_e32 v102, 0xffff0000, v148
	v_mul_f32_e32 v101, v101, v102
	v_cvt_pk_bf16_f32 v100, v100, v101
	v_lshlrev_b32_e32 v101, 16, v149
	v_mul_f32_e32 v101, v106, v101
	v_and_b32_e32 v102, 0xffff0000, v149
	v_mul_f32_e32 v102, v107, v102
	v_cvt_pk_bf16_f32 v101, v101, v102
	global_store_dwordx4 v[110:111], v[98:101], off offset:256
	s_nop 1
	v_pk_mul_f32 v[100:101], v[92:93], s[72:73] op_sel_hi:[1,0]
	v_pk_mul_f32 v[92:93], v[90:91], s[72:73] op_sel_hi:[1,0]
	v_lshlrev_b32_e32 v90, 16, v142
	v_and_b32_e32 v91, 0xffff0000, v142
	v_mul_f32_e32 v90, v94, v90
	v_mul_f32_e32 v91, v95, v91
	v_cvt_pk_bf16_f32 v90, v90, v91
	v_lshlrev_b32_e32 v91, 16, v143
	v_and_b32_e32 v94, 0xffff0000, v143
	v_mul_f32_e32 v91, v96, v91
	v_mul_f32_e32 v94, v97, v94
	v_cvt_pk_bf16_f32 v91, v91, v94
	v_lshlrev_b32_e32 v94, 16, v144
	v_mul_f32_e32 v92, v92, v94
	v_and_b32_e32 v94, 0xffff0000, v144
	v_mul_f32_e32 v93, v93, v94
	v_cvt_pk_bf16_f32 v92, v92, v93
	v_lshlrev_b32_e32 v93, 16, v145
	v_and_b32_e32 v94, 0xffff0000, v145
	v_lshlrev_b64 v[98:99], 11, v[176:177]
	v_mul_f32_e32 v93, v100, v93
	v_mul_f32_e32 v94, v101, v94
	v_cvt_pk_bf16_f32 v93, v93, v94
	v_lshl_add_u64 v[94:95], s[74:75], 0, v[98:99]
	v_lshl_add_u64 v[94:95], v[94:95], 0, v[194:195]
	global_store_dwordx4 v[94:95], v[90:93], off
	s_nop 1
	v_pk_mul_f32 v[90:91], v[84:85], s[72:73] op_sel_hi:[1,0]
	v_pk_mul_f32 v[84:85], v[82:83], s[72:73] op_sel_hi:[1,0]
	v_lshlrev_b32_e32 v82, 16, v138
	v_and_b32_e32 v83, 0xffff0000, v138
	v_mul_f32_e32 v82, v86, v82
	v_mul_f32_e32 v83, v87, v83
	v_cvt_pk_bf16_f32 v82, v82, v83
	v_lshlrev_b32_e32 v83, 16, v139
	v_and_b32_e32 v86, 0xffff0000, v139
	v_mul_f32_e32 v83, v88, v83
	v_mul_f32_e32 v86, v89, v86
	v_cvt_pk_bf16_f32 v83, v83, v86
	v_lshlrev_b32_e32 v86, 16, v140
	v_mul_f32_e32 v84, v84, v86
	v_and_b32_e32 v86, 0xffff0000, v140
	v_mul_f32_e32 v85, v85, v86
	v_cvt_pk_bf16_f32 v84, v84, v85
	v_lshlrev_b32_e32 v85, 16, v141
	v_mul_f32_e32 v85, v90, v85
	v_and_b32_e32 v86, 0xffff0000, v141
	v_mul_f32_e32 v86, v91, v86
	v_cvt_pk_bf16_f32 v85, v85, v86
	global_store_dwordx4 v[94:95], v[82:85], off offset:256
	s_nop 1
	v_pk_mul_f32 v[84:85], v[76:77], s[72:73] op_sel_hi:[1,0]
	v_pk_mul_f32 v[76:77], v[74:75], s[72:73] op_sel_hi:[1,0]
	v_lshlrev_b32_e32 v74, 16, v134
	v_and_b32_e32 v75, 0xffff0000, v134
	v_mul_f32_e32 v74, v78, v74
	v_mul_f32_e32 v75, v79, v75
	v_cvt_pk_bf16_f32 v74, v74, v75
	v_lshlrev_b32_e32 v75, 16, v135
	v_and_b32_e32 v78, 0xffff0000, v135
	v_mul_f32_e32 v75, v80, v75
	v_mul_f32_e32 v78, v81, v78
	v_cvt_pk_bf16_f32 v75, v75, v78
	v_lshlrev_b32_e32 v78, 16, v136
	v_mul_f32_e32 v76, v76, v78
	v_and_b32_e32 v78, 0xffff0000, v136
	v_mul_f32_e32 v77, v77, v78
	v_cvt_pk_bf16_f32 v76, v76, v77
	v_lshlrev_b32_e32 v77, 16, v137
	v_and_b32_e32 v78, 0xffff0000, v137
	v_lshlrev_b64 v[82:83], 11, v[174:175]
	v_mul_f32_e32 v77, v84, v77
	v_mul_f32_e32 v78, v85, v78
	v_cvt_pk_bf16_f32 v77, v77, v78
	v_lshl_add_u64 v[78:79], s[74:75], 0, v[82:83]
	v_lshl_add_u64 v[78:79], v[78:79], 0, v[194:195]
	global_store_dwordx4 v[78:79], v[74:77], off
	s_nop 1
	v_pk_mul_f32 v[74:75], v[68:69], s[72:73] op_sel_hi:[1,0]
	v_pk_mul_f32 v[68:69], v[66:67], s[72:73] op_sel_hi:[1,0]
	v_lshlrev_b32_e32 v66, 16, v130
	v_and_b32_e32 v67, 0xffff0000, v130
	v_mul_f32_e32 v66, v70, v66
	v_mul_f32_e32 v67, v71, v67
	v_cvt_pk_bf16_f32 v66, v66, v67
	v_lshlrev_b32_e32 v67, 16, v131
	v_and_b32_e32 v70, 0xffff0000, v131
	v_mul_f32_e32 v67, v72, v67
	v_mul_f32_e32 v70, v73, v70
	v_cvt_pk_bf16_f32 v67, v67, v70
	v_lshlrev_b32_e32 v70, 16, v132
	v_mul_f32_e32 v68, v68, v70
	v_and_b32_e32 v70, 0xffff0000, v132
	v_mul_f32_e32 v69, v69, v70
	v_cvt_pk_bf16_f32 v68, v68, v69
	v_lshlrev_b32_e32 v69, 16, v133
	v_mul_f32_e32 v69, v74, v69
	v_and_b32_e32 v70, 0xffff0000, v133
	v_mul_f32_e32 v70, v75, v70
	v_cvt_pk_bf16_f32 v69, v69, v70
	global_store_dwordx4 v[78:79], v[66:69], off offset:256
	v_add_u32_e32 v78, 0x80, v172
	s_nop 0
	v_mad_i64_i32 v[66:67], s[6:7], v78, s37, v[170:171]
	v_lshl_add_u64 v[66:67], v[66:67], 0, v[194:195]
	v_add_co_u32_e32 v68, vcc, s16, v66
	v_add_u32_e32 v86, 0x90, v172
	s_nop 0
	v_addc_co_u32_e32 v69, vcc, 0, v67, vcc
	global_load_dwordx4 v[70:73], v[68:69], off offset:2048
	v_lshl_add_u64 v[66:67], v[66:67], 0, s[84:85]
	global_load_dwordx4 v[74:77], v[66:67], off offset:256
	v_pk_mul_f32 v[96:97], v[56:57], s[72:73] op_sel_hi:[1,0]
	v_mad_i64_i32 v[56:57], s[6:7], v86, s37, v[170:171]
	v_lshl_add_u64 v[56:57], v[56:57], 0, v[194:195]
	v_pk_mul_f32 v[94:95], v[58:59], s[72:73] op_sel_hi:[1,0]
	v_add_co_u32_e32 v58, vcc, s16, v56
	v_pk_mul_f32 v[92:93], v[60:61], s[72:73] op_sel_hi:[1,0]
	s_nop 0
	v_addc_co_u32_e32 v59, vcc, 0, v57, vcc
	global_load_dwordx4 v[58:61], v[58:59], off offset:2048
	v_add_u32_e32 v68, 0xa0, v172
	v_pk_mul_f32 v[102:103], v[50:51], s[72:73] op_sel_hi:[1,0]
	v_mad_i64_i32 v[50:51], s[6:7], v68, s37, v[170:171]
	v_add_u32_e32 v66, 0xb0, v172
	v_lshl_add_u64 v[50:51], v[50:51], 0, v[194:195]
	v_pk_mul_f32 v[100:101], v[52:53], s[72:73] op_sel_hi:[1,0]
	v_mad_i64_i32 v[52:53], s[6:7], v66, s37, v[170:171]
	v_lshl_add_u64 v[82:83], v[50:51], 0, s[84:85]
	v_add_co_u32_e32 v50, vcc, s16, v50
	v_lshl_add_u64 v[52:53], v[52:53], 0, v[194:195]
	s_nop 0
	v_addc_co_u32_e32 v51, vcc, 0, v51, vcc
	v_ashrrev_i32_e32 v79, 31, v78
	v_lshl_add_u64 v[104:105], v[52:53], 0, s[84:85]
	v_add_co_u32_e32 v52, vcc, s16, v52
	v_pk_mul_f32 v[98:99], v[54:55], s[72:73] op_sel_hi:[1,0]
	v_lshlrev_b64 v[54:55], 11, v[78:79]
	v_lshl_add_u64 v[56:57], v[56:57], 0, s[84:85]
	v_addc_co_u32_e32 v53, vcc, 0, v53, vcc
	v_pk_mul_f32 v[88:89], v[64:65], s[72:73] op_sel_hi:[1,0]
	v_pk_mul_f32 v[90:91], v[62:63], s[72:73] op_sel_hi:[1,0]
	v_lshl_add_u64 v[106:107], s[74:75], 0, v[54:55]
	global_load_dwordx4 v[62:65], v[56:57], off offset:256
	global_load_dwordx4 v[78:81], v[50:51], off offset:2048
	s_nop 0
	global_load_dwordx4 v[82:85], v[82:83], off offset:256
	s_nop 0
	global_load_dwordx4 v[54:57], v[52:53], off offset:2048
	s_nop 0
	global_load_dwordx4 v[50:53], v[104:105], off offset:256
	v_lshl_add_u64 v[104:105], v[106:107], 0, v[194:195]
	v_pk_mul_f32 v[46:47], v[46:47], s[72:73] op_sel_hi:[1,0]
	v_pk_mul_f32 v[48:49], v[48:49], s[72:73] op_sel_hi:[1,0]
	v_ashrrev_i32_e32 v87, 31, v86
	v_pk_mul_f32 v[38:39], v[38:39], s[72:73] op_sel_hi:[1,0]
	v_pk_mul_f32 v[40:41], v[40:41], s[72:73] op_sel_hi:[1,0]
	v_pk_mul_f32 v[30:31], v[30:31], s[72:73] op_sel_hi:[1,0]
	v_pk_mul_f32 v[32:33], v[32:33], s[72:73] op_sel_hi:[1,0]
	v_ashrrev_i32_e32 v69, 31, v68
	v_pk_mul_f32 v[22:23], v[22:23], s[72:73] op_sel_hi:[1,0]
	v_pk_mul_f32 v[24:25], v[24:25], s[72:73] op_sel_hi:[1,0]
	v_pk_mul_f32 v[14:15], v[14:15], s[72:73] op_sel_hi:[1,0]
	v_pk_mul_f32 v[16:17], v[16:17], s[72:73] op_sel_hi:[1,0]
	v_ashrrev_i32_e32 v67, 31, v66
	v_pk_mul_f32 v[6:7], v[6:7], s[72:73] op_sel_hi:[1,0]
	v_pk_mul_f32 v[8:9], v[8:9], s[72:73] op_sel_hi:[1,0]
	s_waitcnt vmcnt(0)
	v_lshlrev_b32_e32 v106, 16, v70
	v_and_b32_e32 v70, 0xffff0000, v70
	v_lshlrev_b32_e32 v107, 16, v71
	v_and_b32_e32 v71, 0xffff0000, v71
	v_lshlrev_b32_e32 v108, 16, v72
	v_and_b32_e32 v72, 0xffff0000, v72
	v_lshlrev_b32_e32 v109, 16, v73
	v_and_b32_e32 v73, 0xffff0000, v73
	v_mul_f32_e32 v70, v91, v70
	v_mul_f32_e32 v71, v89, v71
	v_mul_f32_e32 v72, v95, v72
	v_mul_f32_e32 v73, v93, v73
	v_mul_f32_e32 v90, v90, v106
	v_mul_f32_e32 v88, v88, v107
	v_mul_f32_e32 v89, v94, v108
	v_mul_f32_e32 v91, v92, v109
	v_cvt_pk_bf16_f32 v70, v90, v70
	v_cvt_pk_bf16_f32 v71, v88, v71
	v_cvt_pk_bf16_f32 v72, v89, v72
	v_cvt_pk_bf16_f32 v73, v91, v73
	v_lshlrev_b32_e32 v111, 16, v75
	v_and_b32_e32 v75, 0xffff0000, v75
	global_store_dwordx4 v[104:105], v[70:73], off
	v_lshlrev_b32_e32 v110, 16, v74
	v_and_b32_e32 v74, 0xffff0000, v74
	v_lshlrev_b32_e32 v72, 16, v76
	v_and_b32_e32 v73, 0xffff0000, v76
	v_mul_f32_e32 v71, v97, v75
	v_mul_f32_e32 v72, v102, v72
	v_mul_f32_e32 v73, v103, v73
	v_mul_f32_e32 v92, v98, v110
	v_mul_f32_e32 v74, v99, v74
	v_mul_f32_e32 v93, v96, v111
	v_cvt_pk_bf16_f32 v70, v92, v74
	v_cvt_pk_bf16_f32 v71, v93, v71
	v_cvt_pk_bf16_f32 v72, v72, v73
	v_lshlrev_b32_e32 v73, 16, v77
	v_mul_f32_e32 v73, v100, v73
	v_and_b32_e32 v74, 0xffff0000, v77
	v_mul_f32_e32 v74, v101, v74
	v_cvt_pk_bf16_f32 v73, v73, v74
	global_store_dwordx4 v[104:105], v[70:73], off offset:256
	s_nop 1
	v_pk_mul_f32 v[72:73], v[44:45], s[72:73] op_sel_hi:[1,0]
	v_pk_mul_f32 v[44:45], v[42:43], s[72:73] op_sel_hi:[1,0]
	v_lshlrev_b32_e32 v42, 16, v58
	v_and_b32_e32 v43, 0xffff0000, v58
	v_mul_f32_e32 v42, v46, v42
	v_mul_f32_e32 v43, v47, v43
	v_cvt_pk_bf16_f32 v42, v42, v43
	v_lshlrev_b32_e32 v43, 16, v59
	v_and_b32_e32 v46, 0xffff0000, v59
	v_mul_f32_e32 v43, v48, v43
	v_mul_f32_e32 v46, v49, v46
	v_cvt_pk_bf16_f32 v43, v43, v46
	v_lshlrev_b32_e32 v46, 16, v60
	v_mul_f32_e32 v44, v44, v46
	v_and_b32_e32 v46, 0xffff0000, v60
	v_mul_f32_e32 v45, v45, v46
	v_cvt_pk_bf16_f32 v44, v44, v45
	v_lshlrev_b32_e32 v45, 16, v61
	v_and_b32_e32 v46, 0xffff0000, v61
	v_lshlrev_b64 v[70:71], 11, v[86:87]
	v_mul_f32_e32 v45, v72, v45
	v_mul_f32_e32 v46, v73, v46
	v_cvt_pk_bf16_f32 v45, v45, v46
	v_lshl_add_u64 v[46:47], s[74:75], 0, v[70:71]
	v_lshl_add_u64 v[46:47], v[46:47], 0, v[194:195]
	global_store_dwordx4 v[46:47], v[42:45], off
	s_nop 1
	v_pk_mul_f32 v[42:43], v[36:37], s[72:73] op_sel_hi:[1,0]
	v_pk_mul_f32 v[36:37], v[34:35], s[72:73] op_sel_hi:[1,0]
	v_lshlrev_b32_e32 v34, 16, v62
	v_and_b32_e32 v35, 0xffff0000, v62
	v_mul_f32_e32 v34, v38, v34
	v_mul_f32_e32 v35, v39, v35
	v_cvt_pk_bf16_f32 v34, v34, v35
	v_lshlrev_b32_e32 v35, 16, v63
	v_and_b32_e32 v38, 0xffff0000, v63
	v_mul_f32_e32 v35, v40, v35
	v_mul_f32_e32 v38, v41, v38
	v_cvt_pk_bf16_f32 v35, v35, v38
	v_lshlrev_b32_e32 v38, 16, v64
	v_mul_f32_e32 v36, v36, v38
	v_and_b32_e32 v38, 0xffff0000, v64
	v_mul_f32_e32 v37, v37, v38
	v_cvt_pk_bf16_f32 v36, v36, v37
	v_lshlrev_b32_e32 v37, 16, v65
	v_mul_f32_e32 v37, v42, v37
	v_and_b32_e32 v38, 0xffff0000, v65
	v_mul_f32_e32 v38, v43, v38
	v_cvt_pk_bf16_f32 v37, v37, v38
	global_store_dwordx4 v[46:47], v[34:37], off offset:256
	s_nop 1
	v_pk_mul_f32 v[36:37], v[28:29], s[72:73] op_sel_hi:[1,0]
	v_pk_mul_f32 v[28:29], v[26:27], s[72:73] op_sel_hi:[1,0]
	v_lshlrev_b32_e32 v26, 16, v78
	v_and_b32_e32 v27, 0xffff0000, v78
	v_mul_f32_e32 v26, v30, v26
	v_mul_f32_e32 v27, v31, v27
	v_cvt_pk_bf16_f32 v26, v26, v27
	v_lshlrev_b32_e32 v27, 16, v79
	v_and_b32_e32 v30, 0xffff0000, v79
	v_mul_f32_e32 v27, v32, v27
	v_mul_f32_e32 v30, v33, v30
	v_cvt_pk_bf16_f32 v27, v27, v30
	v_lshlrev_b32_e32 v30, 16, v80
	v_mul_f32_e32 v28, v28, v30
	v_and_b32_e32 v30, 0xffff0000, v80
	v_mul_f32_e32 v29, v29, v30
	v_cvt_pk_bf16_f32 v28, v28, v29
	v_lshlrev_b32_e32 v29, 16, v81
	v_and_b32_e32 v30, 0xffff0000, v81
	v_lshlrev_b64 v[34:35], 11, v[68:69]
	v_mul_f32_e32 v29, v36, v29
	v_mul_f32_e32 v30, v37, v30
	v_cvt_pk_bf16_f32 v29, v29, v30
	v_lshl_add_u64 v[30:31], s[74:75], 0, v[34:35]
	v_lshl_add_u64 v[30:31], v[30:31], 0, v[194:195]
	global_store_dwordx4 v[30:31], v[26:29], off
	s_nop 1
	v_pk_mul_f32 v[26:27], v[20:21], s[72:73] op_sel_hi:[1,0]
	v_pk_mul_f32 v[20:21], v[18:19], s[72:73] op_sel_hi:[1,0]
	v_lshlrev_b32_e32 v18, 16, v82
	v_and_b32_e32 v19, 0xffff0000, v82
	v_mul_f32_e32 v18, v22, v18
	v_mul_f32_e32 v19, v23, v19
	v_cvt_pk_bf16_f32 v18, v18, v19
	v_lshlrev_b32_e32 v19, 16, v83
	v_and_b32_e32 v22, 0xffff0000, v83
	v_mul_f32_e32 v19, v24, v19
	v_mul_f32_e32 v22, v25, v22
	v_cvt_pk_bf16_f32 v19, v19, v22
	v_lshlrev_b32_e32 v22, 16, v84
	v_mul_f32_e32 v20, v20, v22
	v_and_b32_e32 v22, 0xffff0000, v84
	v_mul_f32_e32 v21, v21, v22
	v_cvt_pk_bf16_f32 v20, v20, v21
	v_lshlrev_b32_e32 v21, 16, v85
	v_mul_f32_e32 v21, v26, v21
	v_and_b32_e32 v22, 0xffff0000, v85
	v_mul_f32_e32 v22, v27, v22
	v_cvt_pk_bf16_f32 v21, v21, v22
	global_store_dwordx4 v[30:31], v[18:21], off offset:256
	s_nop 1
	v_pk_mul_f32 v[20:21], v[12:13], s[72:73] op_sel_hi:[1,0]
	v_pk_mul_f32 v[12:13], v[10:11], s[72:73] op_sel_hi:[1,0]
	v_lshlrev_b32_e32 v10, 16, v54
	v_and_b32_e32 v11, 0xffff0000, v54
	v_mul_f32_e32 v10, v14, v10
	v_mul_f32_e32 v11, v15, v11
	v_cvt_pk_bf16_f32 v10, v10, v11
	v_lshlrev_b32_e32 v11, 16, v55
	v_and_b32_e32 v14, 0xffff0000, v55
	v_mul_f32_e32 v11, v16, v11
	v_mul_f32_e32 v14, v17, v14
	v_cvt_pk_bf16_f32 v11, v11, v14
	v_lshlrev_b32_e32 v14, 16, v56
	v_mul_f32_e32 v12, v12, v14
	v_and_b32_e32 v14, 0xffff0000, v56
	v_mul_f32_e32 v13, v13, v14
	v_cvt_pk_bf16_f32 v12, v12, v13
	v_lshlrev_b32_e32 v13, 16, v57
	v_and_b32_e32 v14, 0xffff0000, v57
	v_lshlrev_b64 v[18:19], 11, v[66:67]
	v_mul_f32_e32 v13, v20, v13
	v_mul_f32_e32 v14, v21, v14
	v_cvt_pk_bf16_f32 v13, v13, v14
	v_lshl_add_u64 v[14:15], s[74:75], 0, v[18:19]
	v_lshl_add_u64 v[14:15], v[14:15], 0, v[194:195]
	global_store_dwordx4 v[14:15], v[10:13], off
	s_nop 1
	v_pk_mul_f32 v[10:11], v[4:5], s[72:73] op_sel_hi:[1,0]
	v_pk_mul_f32 v[4:5], v[2:3], s[72:73] op_sel_hi:[1,0]
	v_lshlrev_b32_e32 v2, 16, v50
	v_and_b32_e32 v3, 0xffff0000, v50
	v_mul_f32_e32 v2, v6, v2
	v_mul_f32_e32 v3, v7, v3
	v_cvt_pk_bf16_f32 v2, v2, v3
	v_lshlrev_b32_e32 v3, 16, v51
	v_and_b32_e32 v6, 0xffff0000, v51
	v_mul_f32_e32 v3, v8, v3
	v_mul_f32_e32 v6, v9, v6
	v_cvt_pk_bf16_f32 v3, v3, v6
	v_lshlrev_b32_e32 v6, 16, v52
	v_mul_f32_e32 v4, v4, v6
	v_and_b32_e32 v6, 0xffff0000, v52
	v_mul_f32_e32 v5, v5, v6
	v_cvt_pk_bf16_f32 v4, v4, v5
	v_lshlrev_b32_e32 v5, 16, v53
	v_mul_f32_e32 v5, v10, v5
	v_and_b32_e32 v6, 0xffff0000, v53
	v_mul_f32_e32 v6, v11, v6
	v_cvt_pk_bf16_f32 v5, v5, v6
	global_store_dwordx4 v[14:15], v[2:5], off offset:256
	s_and_b64 vcc, exec, s[62:63]
	s_mov_b32 s29, s71
	s_mov_b32 s28, s0
	s_mov_b64 s[8:9], s[60:61]
	s_mov_b64 s[6:7], s[52:53]
	s_cbranch_vccz .LBB0_252
	s_waitcnt vmcnt(0)
	v_readlane_b32 s28, v250, 12
	s_cmpk_gt_u32 s4, 0xff
	v_readlane_b32 s29, v250, 13
	s_mov_b32 s70, 0x800000
	s_cbranch_scc1 .LBB0_259
	s_barrier

.LBB0_266:
	s_add_u32 s8, s6, 0x100
	s_addc_u32 s9, s7, 0
	v_add_u32_e32 v253, 0x10000, v147
	s_add_u32 s10, s71, s6
	ds_read_b128 v[142:145], v253
	ds_read_b128 v[150:153], v253 offset:1024
	ds_read_b128 v[154:157], v253 offset:2048
	ds_read_b128 v[158:161], v253 offset:3072
	s_addc_u32 s11, s78, s7
	s_cmp_eq_u32 s79, 4
	s_cselect_b32 s81, 0, s8
	s_cselect_b32 s80, 0, s9
	s_cselect_b32 s54, s29, s10
	s_cselect_b32 s55, s5, s11
	s_add_u32 s10, s18, s81
	s_addc_u32 s11, s19, s80
	v_lshl_add_u64 v[206:207], v[138:139], 0, s[6:7]
	s_add_i32 m0, s17, 0xc000
	ds_read_b128 v[162:165], v146
	ds_read_b128 v[166:169], v146 offset:1024
	ds_read_b128 v[170:173], v146 offset:2048
	ds_read_b128 v[174:177], v146 offset:3072
	ds_read_b128 v[178:181], v146 offset:4096
	ds_read_b128 v[182:185], v146 offset:5120
	ds_read_b128 v[186:189], v146 offset:6144
	ds_read_b128 v[190:193], v146 offset:7168
	global_load_lds_dwordx4 v[206:207], off
	v_lshl_add_u64 v[206:207], v[140:141], 0, s[6:7]
	s_add_i32 m0, s17, 0xe000
	s_nop 0
	global_load_lds_dwordx4 v[206:207], off
	s_waitcnt lgkmcnt(8)
	s_barrier
	s_waitcnt lgkmcnt(0)
	s_setprio 1
	v_mfma_f32_16x16x32_bf16 v[126:129], v[142:145], v[162:165], v[126:129]
	v_mfma_f32_16x16x32_bf16 v[122:125], v[154:157], v[162:165], v[122:125]
	v_mfma_f32_16x16x32_bf16 v[110:113], v[142:145], v[170:173], v[110:113]
	v_mfma_f32_16x16x32_bf16 v[106:109], v[154:157], v[170:173], v[106:109]
	v_mfma_f32_16x16x32_bf16 v[94:97], v[142:145], v[178:181], v[94:97]
	v_mfma_f32_16x16x32_bf16 v[90:93], v[154:157], v[178:181], v[90:93]
	v_mfma_f32_16x16x32_bf16 v[78:81], v[142:145], v[186:189], v[78:81]
	v_mfma_f32_16x16x32_bf16 v[74:77], v[154:157], v[186:189], v[74:77]
	v_mfma_f32_16x16x32_bf16 v[126:129], v[150:153], v[166:169], v[126:129]
	v_mfma_f32_16x16x32_bf16 v[122:125], v[158:161], v[166:169], v[122:125]
	v_mfma_f32_16x16x32_bf16 v[110:113], v[150:153], v[174:177], v[110:113]
	v_mfma_f32_16x16x32_bf16 v[106:109], v[158:161], v[174:177], v[106:109]
	v_mfma_f32_16x16x32_bf16 v[94:97], v[150:153], v[182:185], v[94:97]
	v_mfma_f32_16x16x32_bf16 v[90:93], v[158:161], v[182:185], v[90:93]
	v_mfma_f32_16x16x32_bf16 v[78:81], v[150:153], v[190:193], v[78:81]
	v_mfma_f32_16x16x32_bf16 v[74:77], v[158:161], v[190:193], v[74:77]
	s_setprio 0
	s_barrier
	s_mov_b32 m0, s26
	ds_read_b128 v[206:209], v253 offset:16384
	ds_read_b128 v[210:213], v253 offset:17408
	v_lshl_add_u64 v[222:223], s[54:55], 0, v[134:135]
	ds_read_b128 v[214:217], v253 offset:18432
	ds_read_b128 v[218:221], v253 offset:19456
	global_load_lds_dwordx4 v[222:223], off
	v_lshl_add_u64 v[224:225], s[54:55], 0, v[130:131]
	s_mov_b32 m0, s34
	s_nop 0
	global_load_lds_dwordx4 v[224:225], off
	s_barrier
	s_waitcnt lgkmcnt(0)
	s_setprio 1
	v_mfma_f32_16x16x32_bf16 v[118:121], v[206:209], v[162:165], v[118:121]
	v_mfma_f32_16x16x32_bf16 v[114:117], v[214:217], v[162:165], v[114:117]
	v_mfma_f32_16x16x32_bf16 v[102:105], v[206:209], v[170:173], v[102:105]
	v_mfma_f32_16x16x32_bf16 v[98:101], v[214:217], v[170:173], v[98:101]
	v_mfma_f32_16x16x32_bf16 v[86:89], v[206:209], v[178:181], v[86:89]
	v_mfma_f32_16x16x32_bf16 v[82:85], v[214:217], v[178:181], v[82:85]
	v_mfma_f32_16x16x32_bf16 v[70:73], v[206:209], v[186:189], v[70:73]
	v_mfma_f32_16x16x32_bf16 v[66:69], v[214:217], v[186:189], v[66:69]
	v_mfma_f32_16x16x32_bf16 v[118:121], v[210:213], v[166:169], v[118:121]
	v_mfma_f32_16x16x32_bf16 v[114:117], v[218:221], v[166:169], v[114:117]
	v_mfma_f32_16x16x32_bf16 v[102:105], v[210:213], v[174:177], v[102:105]
	v_mfma_f32_16x16x32_bf16 v[98:101], v[218:221], v[174:177], v[98:101]
	v_mfma_f32_16x16x32_bf16 v[86:89], v[210:213], v[182:185], v[86:89]
	v_mfma_f32_16x16x32_bf16 v[82:85], v[218:221], v[182:185], v[82:85]
	v_mfma_f32_16x16x32_bf16 v[70:73], v[210:213], v[190:193], v[70:73]
	v_mfma_f32_16x16x32_bf16 v[66:69], v[218:221], v[190:193], v[66:69]
	s_setprio 0
	s_mov_b32 m0, s17
	v_lshl_add_u64 v[226:227], s[10:11], 0, v[136:137]
	s_barrier
	ds_read_b128 v[162:165], v146 offset:16384
	ds_read_b128 v[166:169], v146 offset:17408
	ds_read_b128 v[170:173], v146 offset:18432
	ds_read_b128 v[174:177], v146 offset:19456
	ds_read_b128 v[178:181], v146 offset:20480
	ds_read_b128 v[182:185], v146 offset:21504
	ds_read_b128 v[186:189], v146 offset:22528
	ds_read_b128 v[190:193], v146 offset:23552
	global_load_lds_dwordx4 v[226:227], off
	v_lshl_add_u64 v[228:229], s[10:11], 0, v[132:133]
	s_mov_b32 m0, s35
	s_nop 0
	global_load_lds_dwordx4 v[228:229], off
	s_barrier
	s_waitcnt lgkmcnt(0)
	s_setprio 1
	v_mfma_f32_16x16x32_bf16 v[62:65], v[142:145], v[162:165], v[62:65]
	v_mfma_f32_16x16x32_bf16 v[58:61], v[154:157], v[162:165], v[58:61]
	v_mfma_f32_16x16x32_bf16 v[46:49], v[142:145], v[170:173], v[46:49]
	v_mfma_f32_16x16x32_bf16 v[42:45], v[154:157], v[170:173], v[42:45]
	v_mfma_f32_16x16x32_bf16 v[30:33], v[142:145], v[178:181], v[30:33]
	v_mfma_f32_16x16x32_bf16 v[26:29], v[154:157], v[178:181], v[26:29]
	v_mfma_f32_16x16x32_bf16 v[14:17], v[142:145], v[186:189], v[14:17]
	v_mfma_f32_16x16x32_bf16 v[10:13], v[154:157], v[186:189], v[10:13]
	v_mfma_f32_16x16x32_bf16 v[62:65], v[150:153], v[166:169], v[62:65]
	v_mfma_f32_16x16x32_bf16 v[58:61], v[158:161], v[166:169], v[58:61]
	v_mfma_f32_16x16x32_bf16 v[46:49], v[150:153], v[174:177], v[46:49]
	v_mfma_f32_16x16x32_bf16 v[42:45], v[158:161], v[174:177], v[42:45]
	v_mfma_f32_16x16x32_bf16 v[30:33], v[150:153], v[182:185], v[30:33]
	v_mfma_f32_16x16x32_bf16 v[26:29], v[158:161], v[182:185], v[26:29]
	v_mfma_f32_16x16x32_bf16 v[14:17], v[150:153], v[190:193], v[14:17]
	v_mfma_f32_16x16x32_bf16 v[10:13], v[158:161], v[190:193], v[10:13]
	s_setprio 0
	s_barrier
	s_add_u32 s6, s54, 0x20000
	s_addc_u32 s7, s55, 0
	s_mov_b32 m0, s42
	s_nop 0
	global_load_lds_dwordx4 v134, s[6:7]
	s_mov_b32 m0, s56
	s_nop 0
	global_load_lds_dwordx4 v130, s[6:7]
	s_waitcnt vmcnt(6)
	s_barrier
	s_setprio 1
	v_mfma_f32_16x16x32_bf16 v[54:57], v[206:209], v[162:165], v[54:57]
	v_mfma_f32_16x16x32_bf16 v[50:53], v[214:217], v[162:165], v[50:53]
	v_mfma_f32_16x16x32_bf16 v[38:41], v[206:209], v[170:173], v[38:41]
	v_mfma_f32_16x16x32_bf16 v[34:37], v[214:217], v[170:173], v[34:37]
	v_mfma_f32_16x16x32_bf16 v[22:25], v[206:209], v[178:181], v[22:25]
	v_mfma_f32_16x16x32_bf16 v[18:21], v[214:217], v[178:181], v[18:21]
	v_mfma_f32_16x16x32_bf16 v[6:9], v[206:209], v[186:189], v[6:9]
	v_mfma_f32_16x16x32_bf16 v[2:5], v[214:217], v[186:189], v[2:5]
	v_mfma_f32_16x16x32_bf16 v[54:57], v[210:213], v[166:169], v[54:57]
	v_mfma_f32_16x16x32_bf16 v[50:53], v[218:221], v[166:169], v[50:53]
	v_mfma_f32_16x16x32_bf16 v[38:41], v[210:213], v[174:177], v[38:41]
	v_mfma_f32_16x16x32_bf16 v[34:37], v[218:221], v[174:177], v[34:37]
	v_mfma_f32_16x16x32_bf16 v[22:25], v[210:213], v[182:185], v[22:25]
	v_mfma_f32_16x16x32_bf16 v[18:21], v[218:221], v[182:185], v[18:21]
	v_mfma_f32_16x16x32_bf16 v[6:9], v[210:213], v[190:193], v[6:9]
	v_mfma_f32_16x16x32_bf16 v[2:5], v[218:221], v[190:193], v[2:5]
	s_setprio 0
	s_barrier
	ds_read_b128 v[142:145], v253 offset:32768
	ds_read_b128 v[150:153], v253 offset:33792
	ds_read_b128 v[154:157], v253 offset:34816
	ds_read_b128 v[158:161], v253 offset:35840
	s_add_u32 s6, s10, 0x20000
	s_addc_u32 s7, s11, 0
	s_mov_b32 m0, s57
	ds_read_b128 v[162:165], v146 offset:32768
	ds_read_b128 v[166:169], v146 offset:33792
	ds_read_b128 v[170:173], v146 offset:34816
	ds_read_b128 v[174:177], v146 offset:35840
	ds_read_b128 v[178:181], v146 offset:36864
	ds_read_b128 v[182:185], v146 offset:37888
	ds_read_b128 v[186:189], v146 offset:38912
	ds_read_b128 v[190:193], v146 offset:39936
	global_load_lds_dwordx4 v136, s[6:7]
	s_mov_b32 m0, s58
	s_nop 0
	global_load_lds_dwordx4 v132, s[6:7]
	s_waitcnt lgkmcnt(8)
	s_barrier
	s_waitcnt lgkmcnt(0)
	s_setprio 1
	v_mfma_f32_16x16x32_bf16 v[126:129], v[142:145], v[162:165], v[126:129]
	v_mfma_f32_16x16x32_bf16 v[122:125], v[154:157], v[162:165], v[122:125]
	v_mfma_f32_16x16x32_bf16 v[110:113], v[142:145], v[170:173], v[110:113]
	v_mfma_f32_16x16x32_bf16 v[106:109], v[154:157], v[170:173], v[106:109]
	v_mfma_f32_16x16x32_bf16 v[94:97], v[142:145], v[178:181], v[94:97]
	v_mfma_f32_16x16x32_bf16 v[90:93], v[154:157], v[178:181], v[90:93]
	v_mfma_f32_16x16x32_bf16 v[78:81], v[142:145], v[186:189], v[78:81]
	v_mfma_f32_16x16x32_bf16 v[74:77], v[154:157], v[186:189], v[74:77]
	v_mfma_f32_16x16x32_bf16 v[126:129], v[150:153], v[166:169], v[126:129]
	v_mfma_f32_16x16x32_bf16 v[122:125], v[158:161], v[166:169], v[122:125]
	v_mfma_f32_16x16x32_bf16 v[110:113], v[150:153], v[174:177], v[110:113]
	v_mfma_f32_16x16x32_bf16 v[106:109], v[158:161], v[174:177], v[106:109]
	v_mfma_f32_16x16x32_bf16 v[94:97], v[150:153], v[182:185], v[94:97]
	v_mfma_f32_16x16x32_bf16 v[90:93], v[158:161], v[182:185], v[90:93]
	v_mfma_f32_16x16x32_bf16 v[78:81], v[150:153], v[190:193], v[78:81]
	v_mfma_f32_16x16x32_bf16 v[74:77], v[158:161], v[190:193], v[74:77]
	s_setprio 0
	s_barrier
	s_mov_b32 m0, s59
	ds_read_b128 v[206:209], v253 offset:49152
	ds_read_b128 v[210:213], v253 offset:50176
	v_lshl_add_u64 v[222:223], v[222:223], 0, s[76:77]
	ds_read_b128 v[214:217], v253 offset:51200
	ds_read_b128 v[218:221], v253 offset:52224
	global_load_lds_dwordx4 v[222:223], off
	v_lshl_add_u64 v[222:223], v[224:225], 0, s[76:77]
	s_mov_b32 m0, s60
	s_nop 0
	global_load_lds_dwordx4 v[222:223], off
	s_barrier
	s_waitcnt lgkmcnt(0)
	s_setprio 1
	v_mfma_f32_16x16x32_bf16 v[118:121], v[206:209], v[162:165], v[118:121]
	v_mfma_f32_16x16x32_bf16 v[114:117], v[214:217], v[162:165], v[114:117]
	v_mfma_f32_16x16x32_bf16 v[102:105], v[206:209], v[170:173], v[102:105]
	v_mfma_f32_16x16x32_bf16 v[98:101], v[214:217], v[170:173], v[98:101]
	v_mfma_f32_16x16x32_bf16 v[86:89], v[206:209], v[178:181], v[86:89]
	v_mfma_f32_16x16x32_bf16 v[82:85], v[214:217], v[178:181], v[82:85]
	v_mfma_f32_16x16x32_bf16 v[70:73], v[206:209], v[186:189], v[70:73]
	v_mfma_f32_16x16x32_bf16 v[66:69], v[214:217], v[186:189], v[66:69]
	v_mfma_f32_16x16x32_bf16 v[118:121], v[210:213], v[166:169], v[118:121]
	v_mfma_f32_16x16x32_bf16 v[114:117], v[218:221], v[166:169], v[114:117]
	v_mfma_f32_16x16x32_bf16 v[102:105], v[210:213], v[174:177], v[102:105]
	v_mfma_f32_16x16x32_bf16 v[98:101], v[218:221], v[174:177], v[98:101]
	v_mfma_f32_16x16x32_bf16 v[86:89], v[210:213], v[182:185], v[86:89]
	v_mfma_f32_16x16x32_bf16 v[82:85], v[218:221], v[182:185], v[82:85]
	v_mfma_f32_16x16x32_bf16 v[70:73], v[210:213], v[190:193], v[70:73]
	v_mfma_f32_16x16x32_bf16 v[66:69], v[218:221], v[190:193], v[66:69]
	s_setprio 0
	s_mov_b32 m0, s61
	v_lshl_add_u64 v[222:223], v[226:227], 0, s[76:77]
	s_barrier
	ds_read_b128 v[162:165], v146 offset:49152
	ds_read_b128 v[166:169], v146 offset:50176
	ds_read_b128 v[170:173], v146 offset:51200
	ds_read_b128 v[174:177], v146 offset:52224
	ds_read_b128 v[178:181], v146 offset:53248
	ds_read_b128 v[182:185], v146 offset:54272
	ds_read_b128 v[186:189], v146 offset:55296
	ds_read_b128 v[190:193], v146 offset:56320
	global_load_lds_dwordx4 v[222:223], off
	v_lshl_add_u64 v[222:223], v[228:229], 0, s[76:77]
	s_mov_b32 m0, s62
	s_nop 0
	global_load_lds_dwordx4 v[222:223], off
	s_barrier
	s_waitcnt lgkmcnt(0)
	s_setprio 1
	v_mfma_f32_16x16x32_bf16 v[62:65], v[142:145], v[162:165], v[62:65]
	v_mfma_f32_16x16x32_bf16 v[58:61], v[154:157], v[162:165], v[58:61]
	v_mfma_f32_16x16x32_bf16 v[46:49], v[142:145], v[170:173], v[46:49]
	v_mfma_f32_16x16x32_bf16 v[42:45], v[154:157], v[170:173], v[42:45]
	v_mfma_f32_16x16x32_bf16 v[30:33], v[142:145], v[178:181], v[30:33]
	v_mfma_f32_16x16x32_bf16 v[26:29], v[154:157], v[178:181], v[26:29]
	v_mfma_f32_16x16x32_bf16 v[14:17], v[142:145], v[186:189], v[14:17]
	v_mfma_f32_16x16x32_bf16 v[10:13], v[154:157], v[186:189], v[10:13]
	v_mfma_f32_16x16x32_bf16 v[62:65], v[150:153], v[166:169], v[62:65]
	v_mfma_f32_16x16x32_bf16 v[58:61], v[158:161], v[166:169], v[58:61]
	v_mfma_f32_16x16x32_bf16 v[46:49], v[150:153], v[174:177], v[46:49]
	v_mfma_f32_16x16x32_bf16 v[42:45], v[158:161], v[174:177], v[42:45]
	v_mfma_f32_16x16x32_bf16 v[30:33], v[150:153], v[182:185], v[30:33]
	v_mfma_f32_16x16x32_bf16 v[26:29], v[158:161], v[182:185], v[26:29]
	v_mfma_f32_16x16x32_bf16 v[14:17], v[150:153], v[190:193], v[14:17]
	v_mfma_f32_16x16x32_bf16 v[10:13], v[158:161], v[190:193], v[10:13]
	s_setprio 0
	s_barrier
	s_add_u32 s6, s54, 0x20080
	s_addc_u32 s7, s55, 0
	s_mov_b32 m0, s63
	s_nop 0
	global_load_lds_dwordx4 v134, s[6:7]
	s_mov_b32 m0, s67
	s_nop 0
	global_load_lds_dwordx4 v130, s[6:7]
	s_waitcnt vmcnt(6)
	s_barrier
	s_setprio 1
	v_mfma_f32_16x16x32_bf16 v[54:57], v[206:209], v[162:165], v[54:57]
	v_mfma_f32_16x16x32_bf16 v[50:53], v[214:217], v[162:165], v[50:53]
	v_mfma_f32_16x16x32_bf16 v[38:41], v[206:209], v[170:173], v[38:41]
	v_mfma_f32_16x16x32_bf16 v[34:37], v[214:217], v[170:173], v[34:37]
	v_mfma_f32_16x16x32_bf16 v[22:25], v[206:209], v[178:181], v[22:25]
	v_mfma_f32_16x16x32_bf16 v[18:21], v[214:217], v[178:181], v[18:21]
	v_mfma_f32_16x16x32_bf16 v[6:9], v[206:209], v[186:189], v[6:9]
	v_mfma_f32_16x16x32_bf16 v[2:5], v[214:217], v[186:189], v[2:5]
	v_mfma_f32_16x16x32_bf16 v[54:57], v[210:213], v[166:169], v[54:57]
	v_mfma_f32_16x16x32_bf16 v[50:53], v[218:221], v[166:169], v[50:53]
	v_mfma_f32_16x16x32_bf16 v[38:41], v[210:213], v[174:177], v[38:41]
	v_mfma_f32_16x16x32_bf16 v[34:37], v[218:221], v[174:177], v[34:37]
	v_mfma_f32_16x16x32_bf16 v[22:25], v[210:213], v[182:185], v[22:25]
	v_mfma_f32_16x16x32_bf16 v[18:21], v[218:221], v[182:185], v[18:21]
	v_mfma_f32_16x16x32_bf16 v[6:9], v[210:213], v[190:193], v[6:9]
	v_mfma_f32_16x16x32_bf16 v[2:5], v[218:221], v[190:193], v[2:5]
	s_setprio 0
	s_add_i32 s79, s79, 2
	s_cmp_gt_u32 s79, 5
	s_mov_b64 s[6:7], s[8:9]
	s_barrier
	s_cbranch_scc0 .LBB0_266
	s_lshl_b32 s5, s28, 6
	s_and_b32 s5, s5, 0xffffff00
	v_add_u32_e32 v144, s5, v148
	s_lshl_b32 s5, s28, 8
	s_and_b32 s5, s5, 0x300
	v_or_b32_e32 v145, s5, v149
	v_mov_b64_e32 v[142:143], s[50:51]
	v_mad_i64_i32 v[150:151], s[6:7], v144, s37, v[142:143]
	v_lshlrev_b32_e32 v194, 1, v145
	v_lshl_add_u64 v[154:155], v[150:151], 0, v[194:195]
	v_add_co_u32_e32 v150, vcc, 0x1000, v154
	v_or_b32_e32 v184, 16, v144
	s_nop 0
	v_addc_co_u32_e32 v151, vcc, 0, v155, vcc
	global_load_dwordx4 v[150:153], v[150:151], off offset:2048
	v_lshl_add_u64 v[154:155], v[154:155], 0, s[84:85]
	global_load_dwordx4 v[154:157], v[154:155], off offset:256
	v_pk_mul_f32 v[182:183], v[114:115], s[36:37] op_sel_hi:[1,0]
	v_mad_i64_i32 v[114:115], s[6:7], v184, s37, v[142:143]
	v_lshl_add_u64 v[114:115], v[114:115], 0, v[194:195]
	v_pk_mul_f32 v[180:181], v[116:117], s[36:37] op_sel_hi:[1,0]
	v_add_co_u32_e32 v116, vcc, 0x1000, v114
	v_pk_mul_f32 v[170:171], v[126:127], s[36:37] op_sel_hi:[1,0]
	s_nop 0
	v_addc_co_u32_e32 v117, vcc, 0, v115, vcc
	v_pk_mul_f32 v[172:173], v[124:125], s[36:37] op_sel_hi:[1,0]
	global_load_dwordx4 v[124:127], v[116:117], off offset:2048
	v_lshl_add_u64 v[114:115], v[114:115], 0, s[84:85]
	global_load_dwordx4 v[158:161], v[114:115], off offset:256
	v_or_b32_e32 v186, 32, v144
	v_mad_i64_i32 v[116:117], s[6:7], v186, s37, v[142:143]
	v_lshl_add_u64 v[116:117], v[116:117], 0, v[194:195]
	v_lshl_add_u64 v[166:167], v[116:117], 0, s[84:85]
	v_add_co_u32_e32 v116, vcc, 0x1000, v116
	v_pk_mul_f32 v[174:175], v[122:123], s[36:37] op_sel_hi:[1,0]
	s_nop 0
	v_addc_co_u32_e32 v117, vcc, 0, v117, vcc
	global_load_dwordx4 v[162:165], v[116:117], off offset:2048
	s_nop 0
	global_load_dwordx4 v[166:169], v[166:167], off offset:256
	v_or_b32_e32 v122, 48, v144
	v_pk_mul_f32 v[178:179], v[118:119], s[36:37] op_sel_hi:[1,0]
	v_mad_i64_i32 v[118:119], s[6:7], v122, s37, v[142:143]
	v_ashrrev_i32_e32 v145, 31, v144
	v_lshl_add_u64 v[118:119], v[118:119], 0, v[194:195]
	v_pk_mul_f32 v[176:177], v[120:121], s[36:37] op_sel_hi:[1,0]
	v_lshlrev_b64 v[120:121], 11, v[144:145]
	v_add_co_u32_e32 v114, vcc, 0x1000, v118
	v_lshl_add_u64 v[120:121], s[74:75], 0, v[120:121]
	s_nop 0
	v_addc_co_u32_e32 v115, vcc, 0, v119, vcc
	v_lshl_add_u64 v[188:189], v[118:119], 0, s[84:85]
	v_lshl_add_u64 v[190:191], v[120:121], 0, v[194:195]
	global_load_dwordx4 v[118:121], v[114:115], off offset:2048
	s_nop 0
	global_load_dwordx4 v[114:117], v[188:189], off offset:256
	v_pk_mul_f32 v[128:129], v[128:129], s[36:37] op_sel_hi:[1,0]
	v_pk_mul_f32 v[110:111], v[110:111], s[36:37] op_sel_hi:[1,0]
	v_pk_mul_f32 v[112:113], v[112:113], s[36:37] op_sel_hi:[1,0]
	v_ashrrev_i32_e32 v185, 31, v184
	v_pk_mul_f32 v[102:103], v[102:103], s[36:37] op_sel_hi:[1,0]
	v_pk_mul_f32 v[104:105], v[104:105], s[36:37] op_sel_hi:[1,0]
	v_pk_mul_f32 v[94:95], v[94:95], s[36:37] op_sel_hi:[1,0]
	v_pk_mul_f32 v[96:97], v[96:97], s[36:37] op_sel_hi:[1,0]
	v_ashrrev_i32_e32 v187, 31, v186
	v_pk_mul_f32 v[86:87], v[86:87], s[36:37] op_sel_hi:[1,0]
	v_pk_mul_f32 v[88:89], v[88:89], s[36:37] op_sel_hi:[1,0]
	v_pk_mul_f32 v[78:79], v[78:79], s[36:37] op_sel_hi:[1,0]
	v_pk_mul_f32 v[80:81], v[80:81], s[36:37] op_sel_hi:[1,0]
	v_ashrrev_i32_e32 v123, 31, v122
	v_pk_mul_f32 v[70:71], v[70:71], s[36:37] op_sel_hi:[1,0]
	v_pk_mul_f32 v[72:73], v[72:73], s[36:37] op_sel_hi:[1,0]
	s_waitcnt vmcnt(0)
	v_lshlrev_b32_e32 v145, 16, v150
	v_and_b32_e32 v150, 0xffff0000, v150
	v_lshlrev_b32_e32 v188, 16, v151
	v_and_b32_e32 v151, 0xffff0000, v151
	v_mul_f32_e32 v150, v171, v150
	v_mul_f32_e32 v128, v128, v188
	v_mul_f32_e32 v129, v129, v151
	v_lshlrev_b32_e32 v189, 16, v152
	v_and_b32_e32 v152, 0xffff0000, v152
	v_lshlrev_b32_e32 v192, 16, v153
	v_and_b32_e32 v153, 0xffff0000, v153
	v_mul_f32_e32 v145, v170, v145
	v_cvt_pk_bf16_f32 v150, v145, v150
	v_cvt_pk_bf16_f32 v151, v128, v129
	v_lshlrev_b32_e32 v128, 16, v154
	v_and_b32_e32 v129, 0xffff0000, v154
	v_mul_f32_e32 v152, v175, v152
	v_mul_f32_e32 v153, v173, v153
	v_mul_f32_e32 v128, v178, v128
	v_mul_f32_e32 v129, v179, v129
	v_mul_f32_e32 v170, v174, v189
	v_mul_f32_e32 v171, v172, v192
	v_cvt_pk_bf16_f32 v152, v170, v152
	v_cvt_pk_bf16_f32 v153, v171, v153
	global_store_dwordx4 v[190:191], v[150:153], off
	s_nop 1
	v_cvt_pk_bf16_f32 v150, v128, v129
	v_lshlrev_b32_e32 v128, 16, v155
	v_and_b32_e32 v129, 0xffff0000, v155
	v_mul_f32_e32 v128, v176, v128
	v_mul_f32_e32 v129, v177, v129
	v_cvt_pk_bf16_f32 v151, v128, v129
	v_lshlrev_b32_e32 v128, 16, v156
	v_and_b32_e32 v129, 0xffff0000, v156
	v_mul_f32_e32 v128, v182, v128
	v_mul_f32_e32 v129, v183, v129
	v_cvt_pk_bf16_f32 v152, v128, v129
	v_lshlrev_b32_e32 v128, 16, v157
	v_and_b32_e32 v129, 0xffff0000, v157
	v_mul_f32_e32 v128, v180, v128
	v_mul_f32_e32 v129, v181, v129
	v_cvt_pk_bf16_f32 v153, v128, v129
	global_store_dwordx4 v[190:191], v[150:153], off offset:256
	v_lshlrev_b64 v[128:129], 11, v[184:185]
	s_nop 0
	v_pk_mul_f32 v[150:151], v[108:109], s[36:37] op_sel_hi:[1,0]
	v_pk_mul_f32 v[108:109], v[106:107], s[36:37] op_sel_hi:[1,0]
	v_lshlrev_b32_e32 v106, 16, v124
	v_and_b32_e32 v107, 0xffff0000, v124
	v_mul_f32_e32 v106, v110, v106
	v_mul_f32_e32 v107, v111, v107
	v_cvt_pk_bf16_f32 v106, v106, v107
	v_lshlrev_b32_e32 v107, 16, v125
	v_and_b32_e32 v110, 0xffff0000, v125
	v_mul_f32_e32 v107, v112, v107
	v_mul_f32_e32 v110, v113, v110
	v_cvt_pk_bf16_f32 v107, v107, v110
	v_lshlrev_b32_e32 v110, 16, v126
	v_mul_f32_e32 v108, v108, v110
	v_and_b32_e32 v110, 0xffff0000, v126
	v_mul_f32_e32 v109, v109, v110
	v_cvt_pk_bf16_f32 v108, v108, v109
	v_lshlrev_b32_e32 v109, 16, v127
	v_and_b32_e32 v110, 0xffff0000, v127
	v_mul_f32_e32 v109, v150, v109
	v_mul_f32_e32 v110, v151, v110
	v_cvt_pk_bf16_f32 v109, v109, v110
	v_lshl_add_u64 v[110:111], s[74:75], 0, v[128:129]
	v_lshl_add_u64 v[110:111], v[110:111], 0, v[194:195]
	global_store_dwordx4 v[110:111], v[106:109], off
	s_nop 1
	v_pk_mul_f32 v[106:107], v[100:101], s[36:37] op_sel_hi:[1,0]
	v_pk_mul_f32 v[100:101], v[98:99], s[36:37] op_sel_hi:[1,0]
	v_lshlrev_b32_e32 v98, 16, v158
	v_and_b32_e32 v99, 0xffff0000, v158
	v_mul_f32_e32 v98, v102, v98
	v_mul_f32_e32 v99, v103, v99
	v_cvt_pk_bf16_f32 v98, v98, v99
	v_lshlrev_b32_e32 v99, 16, v159
	v_and_b32_e32 v102, 0xffff0000, v159
	v_mul_f32_e32 v99, v104, v99
	v_mul_f32_e32 v102, v105, v102
	v_cvt_pk_bf16_f32 v99, v99, v102
	v_lshlrev_b32_e32 v102, 16, v160
	v_mul_f32_e32 v100, v100, v102
	v_and_b32_e32 v102, 0xffff0000, v160
	v_mul_f32_e32 v101, v101, v102
	v_cvt_pk_bf16_f32 v100, v100, v101
	v_lshlrev_b32_e32 v101, 16, v161
	v_mul_f32_e32 v101, v106, v101
	v_and_b32_e32 v102, 0xffff0000, v161
	v_mul_f32_e32 v102, v107, v102
	v_cvt_pk_bf16_f32 v101, v101, v102
	global_store_dwordx4 v[110:111], v[98:101], off offset:256
	s_nop 1
	v_pk_mul_f32 v[100:101], v[92:93], s[36:37] op_sel_hi:[1,0]
	v_pk_mul_f32 v[92:93], v[90:91], s[36:37] op_sel_hi:[1,0]
	v_lshlrev_b32_e32 v90, 16, v162
	v_and_b32_e32 v91, 0xffff0000, v162
	v_mul_f32_e32 v90, v94, v90
	v_mul_f32_e32 v91, v95, v91
	v_cvt_pk_bf16_f32 v90, v90, v91
	v_lshlrev_b32_e32 v91, 16, v163
	v_and_b32_e32 v94, 0xffff0000, v163
	v_mul_f32_e32 v91, v96, v91
	v_mul_f32_e32 v94, v97, v94
	v_cvt_pk_bf16_f32 v91, v91, v94
	v_lshlrev_b32_e32 v94, 16, v164
	v_mul_f32_e32 v92, v92, v94
	v_and_b32_e32 v94, 0xffff0000, v164
	v_mul_f32_e32 v93, v93, v94
	v_cvt_pk_bf16_f32 v92, v92, v93
	v_lshlrev_b32_e32 v93, 16, v165
	v_and_b32_e32 v94, 0xffff0000, v165
	v_lshlrev_b64 v[98:99], 11, v[186:187]
	v_mul_f32_e32 v93, v100, v93
	v_mul_f32_e32 v94, v101, v94
	v_cvt_pk_bf16_f32 v93, v93, v94
	v_lshl_add_u64 v[94:95], s[74:75], 0, v[98:99]
	v_lshl_add_u64 v[94:95], v[94:95], 0, v[194:195]
	global_store_dwordx4 v[94:95], v[90:93], off
	s_nop 1
	v_pk_mul_f32 v[90:91], v[84:85], s[36:37] op_sel_hi:[1,0]
	v_pk_mul_f32 v[84:85], v[82:83], s[36:37] op_sel_hi:[1,0]
	v_lshlrev_b32_e32 v82, 16, v166
	v_and_b32_e32 v83, 0xffff0000, v166
	v_mul_f32_e32 v82, v86, v82
	v_mul_f32_e32 v83, v87, v83
	v_cvt_pk_bf16_f32 v82, v82, v83
	v_lshlrev_b32_e32 v83, 16, v167
	v_and_b32_e32 v86, 0xffff0000, v167
	v_mul_f32_e32 v83, v88, v83
	v_mul_f32_e32 v86, v89, v86
	v_cvt_pk_bf16_f32 v83, v83, v86
	v_lshlrev_b32_e32 v86, 16, v168
	v_mul_f32_e32 v84, v84, v86
	v_and_b32_e32 v86, 0xffff0000, v168
	v_mul_f32_e32 v85, v85, v86
	v_cvt_pk_bf16_f32 v84, v84, v85
	v_lshlrev_b32_e32 v85, 16, v169
	v_mul_f32_e32 v85, v90, v85
	v_and_b32_e32 v86, 0xffff0000, v169
	v_mul_f32_e32 v86, v91, v86
	v_cvt_pk_bf16_f32 v85, v85, v86
	global_store_dwordx4 v[94:95], v[82:85], off offset:256
	s_nop 1
	v_pk_mul_f32 v[84:85], v[76:77], s[36:37] op_sel_hi:[1,0]
	v_pk_mul_f32 v[76:77], v[74:75], s[36:37] op_sel_hi:[1,0]
	v_lshlrev_b32_e32 v74, 16, v118
	v_and_b32_e32 v75, 0xffff0000, v118
	v_mul_f32_e32 v74, v78, v74
	v_mul_f32_e32 v75, v79, v75
	v_cvt_pk_bf16_f32 v74, v74, v75
	v_lshlrev_b32_e32 v75, 16, v119
	v_and_b32_e32 v78, 0xffff0000, v119
	v_mul_f32_e32 v75, v80, v75
	v_mul_f32_e32 v78, v81, v78
	v_cvt_pk_bf16_f32 v75, v75, v78
	v_lshlrev_b32_e32 v78, 16, v120
	v_mul_f32_e32 v76, v76, v78
	v_and_b32_e32 v78, 0xffff0000, v120
	v_mul_f32_e32 v77, v77, v78
	v_cvt_pk_bf16_f32 v76, v76, v77
	v_lshlrev_b32_e32 v77, 16, v121
	v_and_b32_e32 v78, 0xffff0000, v121
	v_lshlrev_b64 v[82:83], 11, v[122:123]
	v_mul_f32_e32 v77, v84, v77
	v_mul_f32_e32 v78, v85, v78
	v_cvt_pk_bf16_f32 v77, v77, v78
	v_lshl_add_u64 v[78:79], s[74:75], 0, v[82:83]
	v_lshl_add_u64 v[78:79], v[78:79], 0, v[194:195]
	global_store_dwordx4 v[78:79], v[74:77], off
	s_nop 1
	v_pk_mul_f32 v[74:75], v[68:69], s[36:37] op_sel_hi:[1,0]
	v_pk_mul_f32 v[68:69], v[66:67], s[36:37] op_sel_hi:[1,0]
	v_lshlrev_b32_e32 v66, 16, v114
	v_and_b32_e32 v67, 0xffff0000, v114
	v_mul_f32_e32 v66, v70, v66
	v_mul_f32_e32 v67, v71, v67
	v_cvt_pk_bf16_f32 v66, v66, v67
	v_lshlrev_b32_e32 v67, 16, v115
	v_and_b32_e32 v70, 0xffff0000, v115
	v_mul_f32_e32 v67, v72, v67
	v_mul_f32_e32 v70, v73, v70
	v_cvt_pk_bf16_f32 v67, v67, v70
	v_lshlrev_b32_e32 v70, 16, v116
	v_mul_f32_e32 v68, v68, v70
	v_and_b32_e32 v70, 0xffff0000, v116
	v_mul_f32_e32 v69, v69, v70
	v_cvt_pk_bf16_f32 v68, v68, v69
	v_lshlrev_b32_e32 v69, 16, v117
	v_mul_f32_e32 v69, v74, v69
	v_and_b32_e32 v70, 0xffff0000, v117
	v_mul_f32_e32 v70, v75, v70
	v_cvt_pk_bf16_f32 v69, v69, v70
	global_store_dwordx4 v[78:79], v[66:69], off offset:256
	v_add_u32_e32 v78, 0x80, v144
	s_nop 0
	v_mad_i64_i32 v[66:67], s[6:7], v78, s37, v[142:143]
	v_lshl_add_u64 v[66:67], v[66:67], 0, v[194:195]
	v_add_co_u32_e32 v68, vcc, s16, v66
	v_add_u32_e32 v86, 0x90, v144
	s_nop 0
	v_addc_co_u32_e32 v69, vcc, 0, v67, vcc
	global_load_dwordx4 v[70:73], v[68:69], off offset:2048
	v_lshl_add_u64 v[66:67], v[66:67], 0, s[84:85]
	global_load_dwordx4 v[74:77], v[66:67], off offset:256
	v_pk_mul_f32 v[96:97], v[56:57], s[36:37] op_sel_hi:[1,0]
	v_mad_i64_i32 v[56:57], s[6:7], v86, s37, v[142:143]
	v_lshl_add_u64 v[56:57], v[56:57], 0, v[194:195]
	v_pk_mul_f32 v[94:95], v[58:59], s[36:37] op_sel_hi:[1,0]
	v_add_co_u32_e32 v58, vcc, s16, v56
	v_pk_mul_f32 v[92:93], v[60:61], s[36:37] op_sel_hi:[1,0]
	s_nop 0
	v_addc_co_u32_e32 v59, vcc, 0, v57, vcc
	global_load_dwordx4 v[58:61], v[58:59], off offset:2048
	v_add_u32_e32 v68, 0xa0, v144
	v_pk_mul_f32 v[102:103], v[50:51], s[36:37] op_sel_hi:[1,0]
	v_mad_i64_i32 v[50:51], s[6:7], v68, s37, v[142:143]
	v_add_u32_e32 v66, 0xb0, v144
	v_lshl_add_u64 v[50:51], v[50:51], 0, v[194:195]
	v_pk_mul_f32 v[100:101], v[52:53], s[36:37] op_sel_hi:[1,0]
	v_mad_i64_i32 v[52:53], s[6:7], v66, s37, v[142:143]
	v_lshl_add_u64 v[82:83], v[50:51], 0, s[84:85]
	v_add_co_u32_e32 v50, vcc, s16, v50
	v_lshl_add_u64 v[52:53], v[52:53], 0, v[194:195]
	s_nop 0
	v_addc_co_u32_e32 v51, vcc, 0, v51, vcc
	v_ashrrev_i32_e32 v79, 31, v78
	v_lshl_add_u64 v[104:105], v[52:53], 0, s[84:85]
	v_add_co_u32_e32 v52, vcc, s16, v52
	v_pk_mul_f32 v[98:99], v[54:55], s[36:37] op_sel_hi:[1,0]
	v_lshlrev_b64 v[54:55], 11, v[78:79]
	v_lshl_add_u64 v[56:57], v[56:57], 0, s[84:85]
	v_addc_co_u32_e32 v53, vcc, 0, v53, vcc
	v_pk_mul_f32 v[88:89], v[64:65], s[36:37] op_sel_hi:[1,0]
	v_pk_mul_f32 v[90:91], v[62:63], s[36:37] op_sel_hi:[1,0]
	v_lshl_add_u64 v[106:107], s[74:75], 0, v[54:55]
	global_load_dwordx4 v[62:65], v[56:57], off offset:256
	global_load_dwordx4 v[78:81], v[50:51], off offset:2048
	s_nop 0
	global_load_dwordx4 v[82:85], v[82:83], off offset:256
	s_nop 0
	global_load_dwordx4 v[54:57], v[52:53], off offset:2048
	s_nop 0
	global_load_dwordx4 v[50:53], v[104:105], off offset:256
	v_lshl_add_u64 v[104:105], v[106:107], 0, v[194:195]
	v_pk_mul_f32 v[46:47], v[46:47], s[36:37] op_sel_hi:[1,0]
	v_pk_mul_f32 v[48:49], v[48:49], s[36:37] op_sel_hi:[1,0]
	v_ashrrev_i32_e32 v87, 31, v86
	v_pk_mul_f32 v[38:39], v[38:39], s[36:37] op_sel_hi:[1,0]
	v_pk_mul_f32 v[40:41], v[40:41], s[36:37] op_sel_hi:[1,0]
	v_pk_mul_f32 v[30:31], v[30:31], s[36:37] op_sel_hi:[1,0]
	v_pk_mul_f32 v[32:33], v[32:33], s[36:37] op_sel_hi:[1,0]
	v_ashrrev_i32_e32 v69, 31, v68
	v_pk_mul_f32 v[22:23], v[22:23], s[36:37] op_sel_hi:[1,0]
	v_pk_mul_f32 v[24:25], v[24:25], s[36:37] op_sel_hi:[1,0]
	v_pk_mul_f32 v[14:15], v[14:15], s[36:37] op_sel_hi:[1,0]
	v_pk_mul_f32 v[16:17], v[16:17], s[36:37] op_sel_hi:[1,0]
	v_ashrrev_i32_e32 v67, 31, v66
	v_pk_mul_f32 v[6:7], v[6:7], s[36:37] op_sel_hi:[1,0]
	v_pk_mul_f32 v[8:9], v[8:9], s[36:37] op_sel_hi:[1,0]
	s_waitcnt vmcnt(0)
	v_lshlrev_b32_e32 v106, 16, v70
	v_and_b32_e32 v70, 0xffff0000, v70
	v_lshlrev_b32_e32 v107, 16, v71
	v_and_b32_e32 v71, 0xffff0000, v71
	v_lshlrev_b32_e32 v108, 16, v72
	v_and_b32_e32 v72, 0xffff0000, v72
	v_lshlrev_b32_e32 v109, 16, v73
	v_and_b32_e32 v73, 0xffff0000, v73
	v_mul_f32_e32 v70, v91, v70
	v_mul_f32_e32 v71, v89, v71
	v_mul_f32_e32 v72, v95, v72
	v_mul_f32_e32 v73, v93, v73
	v_mul_f32_e32 v90, v90, v106
	v_mul_f32_e32 v88, v88, v107
	v_mul_f32_e32 v89, v94, v108
	v_mul_f32_e32 v91, v92, v109
	v_cvt_pk_bf16_f32 v70, v90, v70
	v_cvt_pk_bf16_f32 v71, v88, v71
	v_cvt_pk_bf16_f32 v72, v89, v72
	v_cvt_pk_bf16_f32 v73, v91, v73
	v_lshlrev_b32_e32 v111, 16, v75
	v_and_b32_e32 v75, 0xffff0000, v75
	global_store_dwordx4 v[104:105], v[70:73], off
	v_lshlrev_b32_e32 v110, 16, v74
	v_and_b32_e32 v74, 0xffff0000, v74
	v_lshlrev_b32_e32 v72, 16, v76
	v_and_b32_e32 v73, 0xffff0000, v76
	v_mul_f32_e32 v71, v97, v75
	v_mul_f32_e32 v72, v102, v72
	v_mul_f32_e32 v73, v103, v73
	v_mul_f32_e32 v92, v98, v110
	v_mul_f32_e32 v74, v99, v74
	v_mul_f32_e32 v93, v96, v111
	v_cvt_pk_bf16_f32 v70, v92, v74
	v_cvt_pk_bf16_f32 v71, v93, v71
	v_cvt_pk_bf16_f32 v72, v72, v73
	v_lshlrev_b32_e32 v73, 16, v77
	v_mul_f32_e32 v73, v100, v73
	v_and_b32_e32 v74, 0xffff0000, v77
	v_mul_f32_e32 v74, v101, v74
	v_cvt_pk_bf16_f32 v73, v73, v74
	global_store_dwordx4 v[104:105], v[70:73], off offset:256
	s_nop 1
	v_pk_mul_f32 v[72:73], v[44:45], s[36:37] op_sel_hi:[1,0]
	v_pk_mul_f32 v[44:45], v[42:43], s[36:37] op_sel_hi:[1,0]
	v_lshlrev_b32_e32 v42, 16, v58
	v_and_b32_e32 v43, 0xffff0000, v58
	v_mul_f32_e32 v42, v46, v42
	v_mul_f32_e32 v43, v47, v43
	v_cvt_pk_bf16_f32 v42, v42, v43
	v_lshlrev_b32_e32 v43, 16, v59
	v_and_b32_e32 v46, 0xffff0000, v59
	v_mul_f32_e32 v43, v48, v43
	v_mul_f32_e32 v46, v49, v46
	v_cvt_pk_bf16_f32 v43, v43, v46
	v_lshlrev_b32_e32 v46, 16, v60
	v_mul_f32_e32 v44, v44, v46
	v_and_b32_e32 v46, 0xffff0000, v60
	v_mul_f32_e32 v45, v45, v46
	v_cvt_pk_bf16_f32 v44, v44, v45
	v_lshlrev_b32_e32 v45, 16, v61
	v_and_b32_e32 v46, 0xffff0000, v61
	v_lshlrev_b64 v[70:71], 11, v[86:87]
	v_mul_f32_e32 v45, v72, v45
	v_mul_f32_e32 v46, v73, v46
	v_cvt_pk_bf16_f32 v45, v45, v46
	v_lshl_add_u64 v[46:47], s[74:75], 0, v[70:71]
	v_lshl_add_u64 v[46:47], v[46:47], 0, v[194:195]
	global_store_dwordx4 v[46:47], v[42:45], off
	s_nop 1
	v_pk_mul_f32 v[42:43], v[36:37], s[36:37] op_sel_hi:[1,0]
	v_pk_mul_f32 v[36:37], v[34:35], s[36:37] op_sel_hi:[1,0]
	v_lshlrev_b32_e32 v34, 16, v62
	v_and_b32_e32 v35, 0xffff0000, v62
	v_mul_f32_e32 v34, v38, v34
	v_mul_f32_e32 v35, v39, v35
	v_cvt_pk_bf16_f32 v34, v34, v35
	v_lshlrev_b32_e32 v35, 16, v63
	v_and_b32_e32 v38, 0xffff0000, v63
	v_mul_f32_e32 v35, v40, v35
	v_mul_f32_e32 v38, v41, v38
	v_cvt_pk_bf16_f32 v35, v35, v38
	v_lshlrev_b32_e32 v38, 16, v64
	v_mul_f32_e32 v36, v36, v38
	v_and_b32_e32 v38, 0xffff0000, v64
	v_mul_f32_e32 v37, v37, v38
	v_cvt_pk_bf16_f32 v36, v36, v37
	v_lshlrev_b32_e32 v37, 16, v65
	v_mul_f32_e32 v37, v42, v37
	v_and_b32_e32 v38, 0xffff0000, v65
	v_mul_f32_e32 v38, v43, v38
	v_cvt_pk_bf16_f32 v37, v37, v38
	global_store_dwordx4 v[46:47], v[34:37], off offset:256
	s_nop 1
	v_pk_mul_f32 v[36:37], v[28:29], s[36:37] op_sel_hi:[1,0]
	v_pk_mul_f32 v[28:29], v[26:27], s[36:37] op_sel_hi:[1,0]
	v_lshlrev_b32_e32 v26, 16, v78
	v_and_b32_e32 v27, 0xffff0000, v78
	v_mul_f32_e32 v26, v30, v26
	v_mul_f32_e32 v27, v31, v27
	v_cvt_pk_bf16_f32 v26, v26, v27
	v_lshlrev_b32_e32 v27, 16, v79
	v_and_b32_e32 v30, 0xffff0000, v79
	v_mul_f32_e32 v27, v32, v27
	v_mul_f32_e32 v30, v33, v30
	v_cvt_pk_bf16_f32 v27, v27, v30
	v_lshlrev_b32_e32 v30, 16, v80
	v_mul_f32_e32 v28, v28, v30
	v_and_b32_e32 v30, 0xffff0000, v80
	v_mul_f32_e32 v29, v29, v30
	v_cvt_pk_bf16_f32 v28, v28, v29
	v_lshlrev_b32_e32 v29, 16, v81
	v_and_b32_e32 v30, 0xffff0000, v81
	v_lshlrev_b64 v[34:35], 11, v[68:69]
	v_mul_f32_e32 v29, v36, v29
	v_mul_f32_e32 v30, v37, v30
	v_cvt_pk_bf16_f32 v29, v29, v30
	v_lshl_add_u64 v[30:31], s[74:75], 0, v[34:35]
	v_lshl_add_u64 v[30:31], v[30:31], 0, v[194:195]
	global_store_dwordx4 v[30:31], v[26:29], off
	s_nop 1
	v_pk_mul_f32 v[26:27], v[20:21], s[36:37] op_sel_hi:[1,0]
	v_pk_mul_f32 v[20:21], v[18:19], s[36:37] op_sel_hi:[1,0]
	v_lshlrev_b32_e32 v18, 16, v82
	v_and_b32_e32 v19, 0xffff0000, v82
	v_mul_f32_e32 v18, v22, v18
	v_mul_f32_e32 v19, v23, v19
	v_cvt_pk_bf16_f32 v18, v18, v19
	v_lshlrev_b32_e32 v19, 16, v83
	v_and_b32_e32 v22, 0xffff0000, v83
	v_mul_f32_e32 v19, v24, v19
	v_mul_f32_e32 v22, v25, v22
	v_cvt_pk_bf16_f32 v19, v19, v22
	v_lshlrev_b32_e32 v22, 16, v84
	v_mul_f32_e32 v20, v20, v22
	v_and_b32_e32 v22, 0xffff0000, v84
	v_mul_f32_e32 v21, v21, v22
	v_cvt_pk_bf16_f32 v20, v20, v21
	v_lshlrev_b32_e32 v21, 16, v85
	v_mul_f32_e32 v21, v26, v21
	v_and_b32_e32 v22, 0xffff0000, v85
	v_mul_f32_e32 v22, v27, v22
	v_cvt_pk_bf16_f32 v21, v21, v22
	global_store_dwordx4 v[30:31], v[18:21], off offset:256
	s_nop 1
	v_pk_mul_f32 v[20:21], v[12:13], s[36:37] op_sel_hi:[1,0]
	v_pk_mul_f32 v[12:13], v[10:11], s[36:37] op_sel_hi:[1,0]
	v_lshlrev_b32_e32 v10, 16, v54
	v_and_b32_e32 v11, 0xffff0000, v54
	v_mul_f32_e32 v10, v14, v10
	v_mul_f32_e32 v11, v15, v11
	v_cvt_pk_bf16_f32 v10, v10, v11
	v_lshlrev_b32_e32 v11, 16, v55
	v_and_b32_e32 v14, 0xffff0000, v55
	v_mul_f32_e32 v11, v16, v11
	v_mul_f32_e32 v14, v17, v14
	v_cvt_pk_bf16_f32 v11, v11, v14
	v_lshlrev_b32_e32 v14, 16, v56
	v_mul_f32_e32 v12, v12, v14
	v_and_b32_e32 v14, 0xffff0000, v56
	v_mul_f32_e32 v13, v13, v14
	v_cvt_pk_bf16_f32 v12, v12, v13
	v_lshlrev_b32_e32 v13, 16, v57
	v_and_b32_e32 v14, 0xffff0000, v57
	v_lshlrev_b64 v[18:19], 11, v[66:67]
	v_mul_f32_e32 v13, v20, v13
	v_mul_f32_e32 v14, v21, v14
	v_cvt_pk_bf16_f32 v13, v13, v14
	v_lshl_add_u64 v[14:15], s[74:75], 0, v[18:19]
	v_lshl_add_u64 v[14:15], v[14:15], 0, v[194:195]
	global_store_dwordx4 v[14:15], v[10:13], off
	s_nop 1
	v_pk_mul_f32 v[10:11], v[4:5], s[36:37] op_sel_hi:[1,0]
	v_pk_mul_f32 v[4:5], v[2:3], s[36:37] op_sel_hi:[1,0]
	v_lshlrev_b32_e32 v2, 16, v50
	v_and_b32_e32 v3, 0xffff0000, v50
	v_mul_f32_e32 v2, v6, v2
	v_mul_f32_e32 v3, v7, v3
	v_cvt_pk_bf16_f32 v2, v2, v3
	v_lshlrev_b32_e32 v3, 16, v51
	v_and_b32_e32 v6, 0xffff0000, v51
	v_mul_f32_e32 v3, v8, v3
	v_mul_f32_e32 v6, v9, v6
	v_cvt_pk_bf16_f32 v3, v3, v6
	v_lshlrev_b32_e32 v6, 16, v52
	v_mul_f32_e32 v4, v4, v6
	v_and_b32_e32 v6, 0xffff0000, v52
	v_mul_f32_e32 v5, v5, v6
	v_cvt_pk_bf16_f32 v4, v4, v5
	v_lshlrev_b32_e32 v5, 16, v53
	v_mul_f32_e32 v5, v10, v5
	v_and_b32_e32 v6, 0xffff0000, v53
	v_mul_f32_e32 v6, v11, v6
	v_cvt_pk_bf16_f32 v5, v5, v6
	global_store_dwordx4 v[14:15], v[2:5], off offset:256
	s_and_b64 vcc, exec, s[52:53]
	s_mov_b32 s28, s4
	s_cbranch_vccz .LBB0_265
	s_waitcnt vmcnt(0)
	v_readlane_b32 s28, v250, 12
	s_cmpk_gt_u32 s12, 0xff
	v_readlane_b32 s29, v250, 13
	s_mov_b32 s70, 0x800000
	s_cbranch_scc1 .LBB0_270
	s_barrier

.LBB0_362:
	v_lshrrev_b32_e32 v18, 1, v2
	v_and_b32_e32 v18, 24, v18
	v_and_b32_e32 v9, 15, v2
	v_lshlrev_b32_e32 v19, 1, v18
	v_lshlrev_b32_e32 v2, 2, v2
	v_lshl_or_b32 v197, s0, 6, v9
	v_lshl_or_b32 v9, v9, 6, v19
	s_lshl_b32 s0, s0, 13
	v_and_b32_e32 v2, 32, v2
	v_lshl_add_u64 v[10:11], s[52:53], 0, v[194:195]
	v_mov_b32_e32 v211, v195
	v_bitop3_b32 v199, v9, s0, v2 bitop3:0xde
	s_lshl_b32 s0, s1, 5
	s_add_i32 s78, s34, 0x18000
	v_lshl_add_u64 v[12:13], s[52:53], 0, v[210:211]
	v_mov_b32_e32 v207, v195
	s_and_b32 s7, s0, 0x60
	v_lshl_add_u64 v[10:11], v[10:11], 0, s[76:77]
	s_mov_b32 m0, s78
	s_add_i32 s79, s34, 0x1a000
	v_lshl_add_u64 v[14:15], s[8:9], 0, v[206:207]
	v_mov_b32_e32 v209, v195
	s_lshl_b32 s0, s7, 7
	s_waitcnt vmcnt(0)
	s_barrier
	global_load_lds_dwordx4 v[10:11], off
	v_lshl_add_u64 v[10:11], v[12:13], 0, s[76:77]
	s_mov_b32 m0, s79
	s_add_i32 s26, s34, 0x8000
	s_add_i32 s4, s34, 0xa000
	v_lshl_add_u64 v[16:17], s[8:9], 0, v[208:209]
	v_bitop3_b32 v201, v9, s0, v2 bitop3:0xde
	global_load_lds_dwordx4 v[10:11], off
	v_lshl_add_u64 v[10:11], v[14:15], 0, s[76:77]
	s_mov_b32 m0, s26
	s_add_u32 s0, s52, 0x40080
	global_load_lds_dwordx4 v[10:11], off
	v_lshl_add_u64 v[10:11], v[16:17], 0, s[76:77]
	s_mov_b32 m0, s4
	s_addc_u32 s1, s53, 0
	s_add_i32 s5, s34, 0x1c000
	global_load_lds_dwordx4 v[10:11], off
	v_lshl_add_u64 v[10:11], s[0:1], 0, v[194:195]
	s_mov_b32 m0, s5
	s_add_i32 s58, s34, 0x1e000
	global_load_lds_dwordx4 v[10:11], off
	v_lshl_add_u64 v[10:11], s[0:1], 0, v[210:211]
	s_mov_b32 m0, s58
	v_lshlrev_b32_e32 v2, 14, v3
	global_load_lds_dwordx4 v[10:11], off
	v_and_b32_e32 v2, 0xffff8000, v2
	v_lshl_add_u32 v2, v4, 11, v2
	v_and_b32_e32 v3, 1, v3
	v_lshl_or_b32 v2, v3, 6, v2
	v_lshl_add_u32 v212, v5, 1, v2
	v_lshlrev_b32_e32 v2, 14, v6
	v_and_b32_e32 v2, 0xffff8000, v2
	v_lshl_add_u32 v2, v7, 11, v2
	v_and_b32_e32 v3, 1, v6
	s_waitcnt vmcnt(6)
	v_lshl_or_b32 v2, v3, 6, v2
	v_lshl_add_u32 v214, v8, 1, v2
	v_mov_b32_e32 v2, 0
	s_lshr_b32 s59, s33, 3
	v_or_b32_e32 v203, s7, v18
	v_mov_b32_e32 v213, v195
	v_mov_b32_e32 v215, v195
	s_mov_b32 s95, 0
	s_mov_b32 s94, 0
	v_mov_b32_e32 v3, v2
	v_mov_b32_e32 v4, v2
	v_mov_b32_e32 v5, v2
	v_mov_b32_e32 v6, v2
	v_mov_b32_e32 v7, v2
	v_mov_b32_e32 v8, v2
	v_mov_b32_e32 v9, v2
	v_mov_b32_e32 v10, v2
	v_mov_b32_e32 v11, v2
	v_mov_b32_e32 v12, v2
	v_mov_b32_e32 v13, v2
	v_mov_b32_e32 v14, v2
	v_mov_b32_e32 v15, v2
	v_mov_b32_e32 v16, v2
	v_mov_b32_e32 v17, v2
	v_mov_b32_e32 v18, v2
	v_mov_b32_e32 v19, v2
	v_mov_b32_e32 v20, v2
	v_mov_b32_e32 v21, v2
	v_mov_b32_e32 v22, v2
	v_mov_b32_e32 v23, v2
	v_mov_b32_e32 v24, v2
	v_mov_b32_e32 v25, v2
	v_mov_b32_e32 v26, v2
	v_mov_b32_e32 v27, v2
	v_mov_b32_e32 v28, v2
	v_mov_b32_e32 v29, v2
	v_mov_b32_e32 v30, v2
	v_mov_b32_e32 v31, v2
	v_mov_b32_e32 v32, v2
	v_mov_b32_e32 v33, v2
	v_mov_b32_e32 v34, v2
	v_mov_b32_e32 v35, v2
	v_mov_b32_e32 v36, v2
	v_mov_b32_e32 v37, v2
	v_mov_b32_e32 v38, v2
	v_mov_b32_e32 v39, v2
	v_mov_b32_e32 v40, v2
	v_mov_b32_e32 v41, v2
	v_mov_b32_e32 v42, v2
	v_mov_b32_e32 v43, v2
	v_mov_b32_e32 v44, v2
	v_mov_b32_e32 v45, v2
	v_mov_b32_e32 v46, v2
	v_mov_b32_e32 v47, v2
	v_mov_b32_e32 v48, v2
	v_mov_b32_e32 v49, v2
	v_mov_b32_e32 v50, v2
	v_mov_b32_e32 v51, v2
	v_mov_b32_e32 v52, v2
	v_mov_b32_e32 v53, v2
	v_mov_b32_e32 v54, v2
	v_mov_b32_e32 v55, v2
	v_mov_b32_e32 v56, v2
	v_mov_b32_e32 v57, v2
	v_mov_b32_e32 v58, v2
	v_mov_b32_e32 v59, v2
	v_mov_b32_e32 v60, v2
	v_mov_b32_e32 v61, v2
	v_mov_b32_e32 v62, v2
	v_mov_b32_e32 v63, v2
	v_mov_b32_e32 v64, v2
	v_mov_b32_e32 v65, v2
	v_mov_b32_e32 v66, v2
	v_mov_b32_e32 v67, v2
	v_mov_b32_e32 v68, v2
	v_mov_b32_e32 v69, v2
	v_mov_b32_e32 v70, v2
	v_mov_b32_e32 v71, v2
	v_mov_b32_e32 v72, v2
	v_mov_b32_e32 v73, v2
	v_mov_b32_e32 v74, v2
	v_mov_b32_e32 v75, v2
	v_mov_b32_e32 v76, v2
	v_mov_b32_e32 v77, v2
	v_mov_b32_e32 v78, v2
	v_mov_b32_e32 v79, v2
	v_mov_b32_e32 v80, v2
	v_mov_b32_e32 v81, v2
	v_mov_b32_e32 v82, v2
	v_mov_b32_e32 v83, v2
	v_mov_b32_e32 v84, v2
	v_mov_b32_e32 v85, v2
	v_mov_b32_e32 v86, v2
	v_mov_b32_e32 v87, v2
	v_mov_b32_e32 v88, v2
	v_mov_b32_e32 v89, v2
	v_mov_b32_e32 v90, v2
	v_mov_b32_e32 v91, v2
	v_mov_b32_e32 v92, v2
	v_mov_b32_e32 v93, v2
	v_mov_b32_e32 v94, v2
	v_mov_b32_e32 v95, v2
	v_mov_b32_e32 v96, v2
	v_mov_b32_e32 v97, v2
	v_mov_b32_e32 v98, v2
	v_mov_b32_e32 v99, v2
	v_mov_b32_e32 v100, v2
	v_mov_b32_e32 v101, v2
	v_mov_b32_e32 v102, v2
	v_mov_b32_e32 v103, v2
	v_mov_b32_e32 v104, v2
	v_mov_b32_e32 v105, v2
	v_mov_b32_e32 v106, v2
	v_mov_b32_e32 v107, v2
	v_mov_b32_e32 v108, v2
	v_mov_b32_e32 v109, v2
	v_mov_b32_e32 v110, v2
	v_mov_b32_e32 v111, v2
	v_mov_b32_e32 v112, v2
	v_mov_b32_e32 v113, v2
	v_mov_b32_e32 v114, v2
	v_mov_b32_e32 v115, v2
	v_mov_b32_e32 v116, v2
	v_mov_b32_e32 v117, v2
	v_mov_b32_e32 v118, v2
	v_mov_b32_e32 v119, v2
	v_mov_b32_e32 v120, v2
	v_mov_b32_e32 v121, v2
	v_mov_b32_e32 v122, v2
	v_mov_b32_e32 v123, v2
	v_mov_b32_e32 v124, v2
	v_mov_b32_e32 v125, v2
	v_mov_b32_e32 v126, v2
	v_mov_b32_e32 v127, v2
	v_mov_b32_e32 v128, v2
	v_mov_b32_e32 v129, v2
	s_mov_b64 s[82:83], s[52:53]
	s_mov_b64 s[80:81], s[8:9]
	s_barrier
	s_branch .LBB0_365

.LBB0_368:
	v_add_u32_e32 v253, 0x10000, v201
	ds_read_b128 v[130:133], v253
	ds_read_b128 v[134:137], v253 offset:1024
	ds_read_b128 v[138:141], v253 offset:2048
	ds_read_b128 v[142:145], v253 offset:3072
	ds_read_b128 v[146:149], v199
	ds_read_b128 v[150:153], v199 offset:1024
	ds_read_b128 v[154:157], v199 offset:2048
	ds_read_b128 v[158:161], v199 offset:3072
	ds_read_b128 v[162:165], v199 offset:4096
	ds_read_b128 v[166:169], v199 offset:5120
	ds_read_b128 v[170:173], v199 offset:6144
	ds_read_b128 v[174:177], v199 offset:7168
	ds_read_b128 v[178:181], v253 offset:16384
	ds_read_b128 v[182:185], v253 offset:17408
	ds_read_b128 v[186:189], v253 offset:18432
	ds_read_b128 v[190:193], v253 offset:19456
	s_add_u32 s10, s8, 0xfffc0080
	s_addc_u32 s11, s9, -1
	s_cmp_eq_u32 s29, 12
	s_cselect_b32 s11, s81, s11
	s_cselect_b32 s10, s80, s10
	s_cselect_b32 s53, s83, s28
	s_cselect_b32 s52, s82, s7
	s_add_i32 m0, s34, 0xc000
	s_nop 0
	global_load_lds_dwordx4 v212, s[8:9]
	s_add_i32 m0, s34, 0xe000
	s_nop 0
	global_load_lds_dwordx4 v214, s[8:9]
	s_waitcnt vmcnt(8)
	s_waitcnt lgkmcnt(0)
	s_setprio 1
	s_barrier
	v_mfma_f32_16x16x32_bf16 v[126:129], v[130:133], v[146:149], v[126:129]
	v_mfma_f32_16x16x32_bf16 v[122:125], v[138:141], v[146:149], v[122:125]
	v_mfma_f32_16x16x32_bf16 v[118:121], v[130:133], v[154:157], v[118:121]
	v_mfma_f32_16x16x32_bf16 v[114:117], v[138:141], v[154:157], v[114:117]
	v_mfma_f32_16x16x32_bf16 v[110:113], v[130:133], v[162:165], v[110:113]
	v_mfma_f32_16x16x32_bf16 v[106:109], v[138:141], v[162:165], v[106:109]
	v_mfma_f32_16x16x32_bf16 v[102:105], v[130:133], v[170:173], v[102:105]
	v_mfma_f32_16x16x32_bf16 v[98:101], v[138:141], v[170:173], v[98:101]
	v_mfma_f32_16x16x32_bf16 v[126:129], v[134:137], v[150:153], v[126:129]
	v_mfma_f32_16x16x32_bf16 v[122:125], v[142:145], v[150:153], v[122:125]
	v_mfma_f32_16x16x32_bf16 v[118:121], v[134:137], v[158:161], v[118:121]
	v_mfma_f32_16x16x32_bf16 v[114:117], v[142:145], v[158:161], v[114:117]
	v_mfma_f32_16x16x32_bf16 v[110:113], v[134:137], v[166:169], v[110:113]
	v_mfma_f32_16x16x32_bf16 v[106:109], v[142:145], v[166:169], v[106:109]
	v_mfma_f32_16x16x32_bf16 v[102:105], v[134:137], v[174:177], v[102:105]
	v_mfma_f32_16x16x32_bf16 v[98:101], v[142:145], v[174:177], v[98:101]
	v_mfma_f32_16x16x32_bf16 v[94:97], v[178:181], v[146:149], v[94:97]
	v_mfma_f32_16x16x32_bf16 v[90:93], v[186:189], v[146:149], v[90:93]
	v_mfma_f32_16x16x32_bf16 v[86:89], v[178:181], v[154:157], v[86:89]
	v_mfma_f32_16x16x32_bf16 v[82:85], v[186:189], v[154:157], v[82:85]
	v_mfma_f32_16x16x32_bf16 v[78:81], v[178:181], v[162:165], v[78:81]
	v_mfma_f32_16x16x32_bf16 v[74:77], v[186:189], v[162:165], v[74:77]
	v_mfma_f32_16x16x32_bf16 v[70:73], v[178:181], v[170:173], v[70:73]
	v_mfma_f32_16x16x32_bf16 v[66:69], v[186:189], v[170:173], v[66:69]
	v_mfma_f32_16x16x32_bf16 v[94:97], v[182:185], v[150:153], v[94:97]
	v_mfma_f32_16x16x32_bf16 v[90:93], v[190:193], v[150:153], v[90:93]
	v_mfma_f32_16x16x32_bf16 v[86:89], v[182:185], v[158:161], v[86:89]
	v_mfma_f32_16x16x32_bf16 v[82:85], v[190:193], v[158:161], v[82:85]
	v_mfma_f32_16x16x32_bf16 v[78:81], v[182:185], v[166:169], v[78:81]
	v_mfma_f32_16x16x32_bf16 v[74:77], v[190:193], v[166:169], v[74:77]
	v_mfma_f32_16x16x32_bf16 v[70:73], v[182:185], v[174:177], v[70:73]
	v_mfma_f32_16x16x32_bf16 v[66:69], v[190:193], v[174:177], v[66:69]
	s_setprio 0
	s_barrier
	ds_read_b128 v[146:149], v199 offset:16384
	ds_read_b128 v[150:153], v199 offset:17408
	ds_read_b128 v[154:157], v199 offset:18432
	ds_read_b128 v[158:161], v199 offset:19456
	ds_read_b128 v[162:165], v199 offset:20480
	ds_read_b128 v[166:169], v199 offset:21504
	ds_read_b128 v[170:173], v199 offset:22528
	ds_read_b128 v[174:177], v199 offset:23552
	s_mov_b32 m0, s35
	s_nop 0
	global_load_lds_dwordx4 v194, s[52:53]
	s_mov_b32 m0, s42
	s_nop 0
	global_load_lds_dwordx4 v210, s[52:53]
	s_mov_b32 m0, s34
	s_nop 0
	global_load_lds_dwordx4 v206, s[10:11]
	s_mov_b32 m0, s56
	s_nop 0
	global_load_lds_dwordx4 v208, s[10:11]
	s_add_u32 s86, s52, 0x40000
	s_addc_u32 s87, s53, 0
	s_mov_b32 m0, s57
	s_nop 0
	global_load_lds_dwordx4 v194, s[86:87]
	s_mov_b32 m0, s67
	s_nop 0
	global_load_lds_dwordx4 v210, s[86:87]
	s_waitcnt vmcnt(8)
	s_waitcnt lgkmcnt(0)
	s_setprio 1
	s_barrier
	v_mfma_f32_16x16x32_bf16 v[62:65], v[130:133], v[146:149], v[62:65]
	v_mfma_f32_16x16x32_bf16 v[58:61], v[138:141], v[146:149], v[58:61]
	v_mfma_f32_16x16x32_bf16 v[54:57], v[130:133], v[154:157], v[54:57]
	v_mfma_f32_16x16x32_bf16 v[50:53], v[138:141], v[154:157], v[50:53]
	v_mfma_f32_16x16x32_bf16 v[46:49], v[130:133], v[162:165], v[46:49]
	v_mfma_f32_16x16x32_bf16 v[42:45], v[138:141], v[162:165], v[42:45]
	v_mfma_f32_16x16x32_bf16 v[38:41], v[130:133], v[170:173], v[38:41]
	v_mfma_f32_16x16x32_bf16 v[34:37], v[138:141], v[170:173], v[34:37]
	v_mfma_f32_16x16x32_bf16 v[62:65], v[134:137], v[150:153], v[62:65]
	v_mfma_f32_16x16x32_bf16 v[58:61], v[142:145], v[150:153], v[58:61]
	v_mfma_f32_16x16x32_bf16 v[54:57], v[134:137], v[158:161], v[54:57]
	v_mfma_f32_16x16x32_bf16 v[50:53], v[142:145], v[158:161], v[50:53]
	v_mfma_f32_16x16x32_bf16 v[46:49], v[134:137], v[166:169], v[46:49]
	v_mfma_f32_16x16x32_bf16 v[42:45], v[142:145], v[166:169], v[42:45]
	v_mfma_f32_16x16x32_bf16 v[38:41], v[134:137], v[174:177], v[38:41]
	v_mfma_f32_16x16x32_bf16 v[34:37], v[142:145], v[174:177], v[34:37]
	v_mfma_f32_16x16x32_bf16 v[30:33], v[178:181], v[146:149], v[30:33]
	v_mfma_f32_16x16x32_bf16 v[26:29], v[186:189], v[146:149], v[26:29]
	v_mfma_f32_16x16x32_bf16 v[22:25], v[178:181], v[154:157], v[22:25]
	v_mfma_f32_16x16x32_bf16 v[18:21], v[186:189], v[154:157], v[18:21]
	v_mfma_f32_16x16x32_bf16 v[14:17], v[178:181], v[162:165], v[14:17]
	v_mfma_f32_16x16x32_bf16 v[10:13], v[186:189], v[162:165], v[10:13]
	v_mfma_f32_16x16x32_bf16 v[6:9], v[178:181], v[170:173], v[6:9]
	v_mfma_f32_16x16x32_bf16 v[2:5], v[186:189], v[170:173], v[2:5]
	v_mfma_f32_16x16x32_bf16 v[30:33], v[182:185], v[150:153], v[30:33]
	v_mfma_f32_16x16x32_bf16 v[26:29], v[190:193], v[150:153], v[26:29]
	v_mfma_f32_16x16x32_bf16 v[22:25], v[182:185], v[158:161], v[22:25]
	v_mfma_f32_16x16x32_bf16 v[18:21], v[190:193], v[158:161], v[18:21]
	v_mfma_f32_16x16x32_bf16 v[14:17], v[182:185], v[166:169], v[14:17]
	v_mfma_f32_16x16x32_bf16 v[10:13], v[190:193], v[166:169], v[10:13]
	v_mfma_f32_16x16x32_bf16 v[6:9], v[182:185], v[174:177], v[6:9]
	v_mfma_f32_16x16x32_bf16 v[2:5], v[190:193], v[174:177], v[2:5]
	s_setprio 0
	s_barrier
	ds_read_b128 v[130:133], v253 offset:32768
	ds_read_b128 v[134:137], v253 offset:33792
	ds_read_b128 v[138:141], v253 offset:34816
	ds_read_b128 v[142:145], v253 offset:35840
	ds_read_b128 v[146:149], v199 offset:32768
	ds_read_b128 v[150:153], v199 offset:33792
	ds_read_b128 v[154:157], v199 offset:34816
	ds_read_b128 v[158:161], v199 offset:35840
	ds_read_b128 v[162:165], v199 offset:36864
	ds_read_b128 v[166:169], v199 offset:37888
	ds_read_b128 v[170:173], v199 offset:38912
	ds_read_b128 v[174:177], v199 offset:39936
	ds_read_b128 v[178:181], v253 offset:49152
	ds_read_b128 v[182:185], v253 offset:50176
	ds_read_b128 v[186:189], v253 offset:51200
	ds_read_b128 v[190:193], v253 offset:52224
	s_add_u32 s10, s10, 0x40000
	s_addc_u32 s11, s11, 0
	s_mov_b32 m0, s70
	s_nop 0
	global_load_lds_dwordx4 v206, s[10:11]
	s_mov_b32 m0, s71
	s_nop 0
	global_load_lds_dwordx4 v208, s[10:11]
	s_waitcnt vmcnt(8)
	s_waitcnt lgkmcnt(0)
	s_setprio 1
	s_barrier
	v_mfma_f32_16x16x32_bf16 v[126:129], v[130:133], v[146:149], v[126:129]
	v_mfma_f32_16x16x32_bf16 v[122:125], v[138:141], v[146:149], v[122:125]
	v_mfma_f32_16x16x32_bf16 v[118:121], v[130:133], v[154:157], v[118:121]
	v_mfma_f32_16x16x32_bf16 v[114:117], v[138:141], v[154:157], v[114:117]
	v_mfma_f32_16x16x32_bf16 v[110:113], v[130:133], v[162:165], v[110:113]
	v_mfma_f32_16x16x32_bf16 v[106:109], v[138:141], v[162:165], v[106:109]
	v_mfma_f32_16x16x32_bf16 v[102:105], v[130:133], v[170:173], v[102:105]
	v_mfma_f32_16x16x32_bf16 v[98:101], v[138:141], v[170:173], v[98:101]
	v_mfma_f32_16x16x32_bf16 v[126:129], v[134:137], v[150:153], v[126:129]
	v_mfma_f32_16x16x32_bf16 v[122:125], v[142:145], v[150:153], v[122:125]
	v_mfma_f32_16x16x32_bf16 v[118:121], v[134:137], v[158:161], v[118:121]
	v_mfma_f32_16x16x32_bf16 v[114:117], v[142:145], v[158:161], v[114:117]
	v_mfma_f32_16x16x32_bf16 v[110:113], v[134:137], v[166:169], v[110:113]
	v_mfma_f32_16x16x32_bf16 v[106:109], v[142:145], v[166:169], v[106:109]
	v_mfma_f32_16x16x32_bf16 v[102:105], v[134:137], v[174:177], v[102:105]
	v_mfma_f32_16x16x32_bf16 v[98:101], v[142:145], v[174:177], v[98:101]
	v_mfma_f32_16x16x32_bf16 v[94:97], v[178:181], v[146:149], v[94:97]
	v_mfma_f32_16x16x32_bf16 v[90:93], v[186:189], v[146:149], v[90:93]
	v_mfma_f32_16x16x32_bf16 v[86:89], v[178:181], v[154:157], v[86:89]
	v_mfma_f32_16x16x32_bf16 v[82:85], v[186:189], v[154:157], v[82:85]
	v_mfma_f32_16x16x32_bf16 v[78:81], v[178:181], v[162:165], v[78:81]
	v_mfma_f32_16x16x32_bf16 v[74:77], v[186:189], v[162:165], v[74:77]
	v_mfma_f32_16x16x32_bf16 v[70:73], v[178:181], v[170:173], v[70:73]
	v_mfma_f32_16x16x32_bf16 v[66:69], v[186:189], v[170:173], v[66:69]
	v_mfma_f32_16x16x32_bf16 v[94:97], v[182:185], v[150:153], v[94:97]
	v_mfma_f32_16x16x32_bf16 v[90:93], v[190:193], v[150:153], v[90:93]
	v_mfma_f32_16x16x32_bf16 v[86:89], v[182:185], v[158:161], v[86:89]
	v_mfma_f32_16x16x32_bf16 v[82:85], v[190:193], v[158:161], v[82:85]
	v_mfma_f32_16x16x32_bf16 v[78:81], v[182:185], v[166:169], v[78:81]
	v_mfma_f32_16x16x32_bf16 v[74:77], v[190:193], v[166:169], v[74:77]
	v_mfma_f32_16x16x32_bf16 v[70:73], v[182:185], v[174:177], v[70:73]
	v_mfma_f32_16x16x32_bf16 v[66:69], v[190:193], v[174:177], v[66:69]
	s_setprio 0
	s_barrier
	ds_read_b128 v[146:149], v199 offset:49152
	ds_read_b128 v[150:153], v199 offset:50176
	ds_read_b128 v[154:157], v199 offset:51200
	ds_read_b128 v[158:161], v199 offset:52224
	ds_read_b128 v[162:165], v199 offset:53248
	ds_read_b128 v[166:169], v199 offset:54272
	ds_read_b128 v[170:173], v199 offset:55296
	ds_read_b128 v[174:177], v199 offset:56320
	s_mov_b32 m0, s78
	s_add_u32 s98, s52, 0x80
	s_addc_u32 s99, s53, 0
	global_load_lds_dwordx4 v194, s[98:99]
	s_mov_b32 m0, s79
	s_nop 0
	global_load_lds_dwordx4 v210, s[98:99]
	s_mov_b32 m0, s26
	s_add_u32 s100, s10, 0xfffc0080
	s_addc_u32 s101, s11, -1
	global_load_lds_dwordx4 v206, s[100:101]
	s_mov_b32 m0, s4
	s_nop 0
	global_load_lds_dwordx4 v208, s[100:101]
	s_add_u32 s10, s52, 0x40080
	s_addc_u32 s11, s53, 0
	s_mov_b32 m0, s5
	s_nop 0
	global_load_lds_dwordx4 v194, s[10:11]
	s_mov_b32 m0, s58
	s_nop 0
	global_load_lds_dwordx4 v210, s[10:11]
	s_waitcnt vmcnt(8)
	s_waitcnt lgkmcnt(0)
	s_setprio 1
	s_barrier
	v_mfma_f32_16x16x32_bf16 v[62:65], v[130:133], v[146:149], v[62:65]
	v_mfma_f32_16x16x32_bf16 v[58:61], v[138:141], v[146:149], v[58:61]
	v_mfma_f32_16x16x32_bf16 v[54:57], v[130:133], v[154:157], v[54:57]
	v_mfma_f32_16x16x32_bf16 v[50:53], v[138:141], v[154:157], v[50:53]
	v_mfma_f32_16x16x32_bf16 v[46:49], v[130:133], v[162:165], v[46:49]
	v_mfma_f32_16x16x32_bf16 v[42:45], v[138:141], v[162:165], v[42:45]
	v_mfma_f32_16x16x32_bf16 v[38:41], v[130:133], v[170:173], v[38:41]
	v_mfma_f32_16x16x32_bf16 v[34:37], v[138:141], v[170:173], v[34:37]
	v_mfma_f32_16x16x32_bf16 v[62:65], v[134:137], v[150:153], v[62:65]
	v_mfma_f32_16x16x32_bf16 v[58:61], v[142:145], v[150:153], v[58:61]
	v_mfma_f32_16x16x32_bf16 v[54:57], v[134:137], v[158:161], v[54:57]
	v_mfma_f32_16x16x32_bf16 v[50:53], v[142:145], v[158:161], v[50:53]
	v_mfma_f32_16x16x32_bf16 v[46:49], v[134:137], v[166:169], v[46:49]
	v_mfma_f32_16x16x32_bf16 v[42:45], v[142:145], v[166:169], v[42:45]
	v_mfma_f32_16x16x32_bf16 v[38:41], v[134:137], v[174:177], v[38:41]
	v_mfma_f32_16x16x32_bf16 v[34:37], v[142:145], v[174:177], v[34:37]
	v_mfma_f32_16x16x32_bf16 v[30:33], v[178:181], v[146:149], v[30:33]
	v_mfma_f32_16x16x32_bf16 v[26:29], v[186:189], v[146:149], v[26:29]
	v_mfma_f32_16x16x32_bf16 v[22:25], v[178:181], v[154:157], v[22:25]
	v_mfma_f32_16x16x32_bf16 v[18:21], v[186:189], v[154:157], v[18:21]
	v_mfma_f32_16x16x32_bf16 v[14:17], v[178:181], v[162:165], v[14:17]
	v_mfma_f32_16x16x32_bf16 v[10:13], v[186:189], v[162:165], v[10:13]
	v_mfma_f32_16x16x32_bf16 v[6:9], v[178:181], v[170:173], v[6:9]
	v_mfma_f32_16x16x32_bf16 v[2:5], v[186:189], v[170:173], v[2:5]
	v_mfma_f32_16x16x32_bf16 v[30:33], v[182:185], v[150:153], v[30:33]
	v_mfma_f32_16x16x32_bf16 v[26:29], v[190:193], v[150:153], v[26:29]
	v_mfma_f32_16x16x32_bf16 v[22:25], v[182:185], v[158:161], v[22:25]
	v_mfma_f32_16x16x32_bf16 v[18:21], v[190:193], v[158:161], v[18:21]
	v_mfma_f32_16x16x32_bf16 v[14:17], v[182:185], v[166:169], v[14:17]
	v_mfma_f32_16x16x32_bf16 v[10:13], v[190:193], v[166:169], v[10:13]
	v_mfma_f32_16x16x32_bf16 v[6:9], v[182:185], v[174:177], v[6:9]
	v_mfma_f32_16x16x32_bf16 v[2:5], v[190:193], v[174:177], v[2:5]
	s_setprio 0
	s_add_i32 s29, s29, 2
	s_add_u32 s8, s8, 0x100
	s_addc_u32 s9, s9, 0
	s_add_u32 s7, s7, 0x100
	s_addc_u32 s28, s28, 0
	s_cmp_gt_u32 s29, 13
	s_barrier
	s_cbranch_scc0 .LBB0_368
	s_cmp_gt_i32 s95, 1
	s_cselect_b64 s[52:53], -1, 0
	s_mul_i32 s7, s6, 0x680000
	s_lshl_b32 s8, s95, 12
	s_lshl_b32 s9, s54, 9
	s_add_i32 s7, s7, s8
	s_add_i32 s7, s7, s9
	s_add_i32 s7, s7, 0x3800
	s_add_u32 s20, s50, s7
	s_addc_u32 s21, s51, 0
	s_lshl_b32 s7, s6, 20
	s_add_i32 s7, s7, s9
	s_add_u32 s10, s96, s7
	s_addc_u32 s11, s97, 0
	s_mov_b32 s86, 0xbfb8aa3b
	s_mov_b32 s87, 0xbfb8aa3b
	v_mul_u32_u24_e32 v253, 0x6800, v197
	v_lshlrev_b32_e32 v255, 12, v197
	v_lshl_add_u32 v253, v203, 1, v253
	v_lshl_add_u32 v255, v203, 1, v255
	v_add_u32_e32 v254, 0x1000, v253
	s_cmp_eq_u32 s95, 2
	s_cbranch_scc1 .Lem_br2
	global_load_dwordx4 v[130:133], v253, s[20:21]
	global_load_dwordx4 v[134:137], v254, s[20:21]
	global_load_dwordx4 v[138:141], v253, s[20:21] offset:256
	global_load_dwordx4 v[142:145], v254, s[20:21] offset:256
	s_add_u32 s28, s20, 0x68000
	s_addc_u32 s29, s21, 0
	global_load_dwordx4 v[146:149], v253, s[28:29]
	global_load_dwordx4 v[150:153], v254, s[28:29]
	global_load_dwordx4 v[154:157], v253, s[28:29] offset:256
	global_load_dwordx4 v[158:161], v254, s[28:29] offset:256
	s_add_u32 s28, s20, 0xd0000
	s_addc_u32 s29, s21, 0
	global_load_dwordx4 v[162:165], v253, s[28:29]
	global_load_dwordx4 v[166:169], v254, s[28:29]
	global_load_dwordx4 v[170:173], v253, s[28:29] offset:256
	global_load_dwordx4 v[174:177], v254, s[28:29] offset:256
	s_add_u32 s28, s20, 0x138000
	s_addc_u32 s29, s21, 0
	global_load_dwordx4 v[178:181], v253, s[28:29]
	global_load_dwordx4 v[182:185], v254, s[28:29]
	global_load_dwordx4 v[186:189], v253, s[28:29] offset:256
	global_load_dwordx4 v[190:193], v254, s[28:29] offset:256
	s_waitcnt vmcnt(12)
	v_lshlrev_b32_e32 v216, 16, v130
	v_and_b32_e32 v217, 0xffff0000, v130
	v_lshlrev_b32_e32 v218, 16, v131
	v_and_b32_e32 v219, 0xffff0000, v131
	v_lshlrev_b32_e32 v220, 16, v132
	v_and_b32_e32 v221, 0xffff0000, v132
	v_lshlrev_b32_e32 v222, 16, v133
	v_and_b32_e32 v223, 0xffff0000, v133
	v_pk_mul_f32 v[216:217], v[216:217], s[86:87] op_sel_hi:[1,0]
	v_pk_mul_f32 v[218:219], v[218:219], s[86:87] op_sel_hi:[1,0]
	v_pk_mul_f32 v[220:221], v[220:221], s[86:87] op_sel_hi:[1,0]
	v_pk_mul_f32 v[222:223], v[222:223], s[86:87] op_sel_hi:[1,0]
	v_exp_f32_e32 v216, v216
	v_exp_f32_e32 v217, v217
	v_exp_f32_e32 v218, v218
	v_exp_f32_e32 v219, v219
	v_exp_f32_e32 v220, v220
	v_exp_f32_e32 v221, v221
	v_exp_f32_e32 v222, v222
	v_exp_f32_e32 v223, v223
	v_pk_add_f32 v[216:217], v[216:217], 1.0 op_sel_hi:[1,0]
	v_pk_add_f32 v[218:219], v[218:219], 1.0 op_sel_hi:[1,0]
	v_pk_add_f32 v[220:221], v[220:221], 1.0 op_sel_hi:[1,0]
	v_pk_add_f32 v[222:223], v[222:223], 1.0 op_sel_hi:[1,0]
	v_rcp_f32_e32 v216, v216
	v_rcp_f32_e32 v217, v217
	v_rcp_f32_e32 v218, v218
	v_rcp_f32_e32 v219, v219
	v_rcp_f32_e32 v220, v220
	v_rcp_f32_e32 v221, v221
	v_rcp_f32_e32 v222, v222
	v_rcp_f32_e32 v223, v223
	v_lshlrev_b32_e32 v242, 16, v134
	v_and_b32_e32 v243, 0xffff0000, v134
	v_lshlrev_b32_e32 v244, 16, v135
	v_and_b32_e32 v245, 0xffff0000, v135
	v_lshlrev_b32_e32 v246, 16, v136
	v_and_b32_e32 v247, 0xffff0000, v136
	v_lshlrev_b32_e32 v248, 16, v137
	v_and_b32_e32 v249, 0xffff0000, v137
	v_pk_mul_f32 v[242:243], v[242:243], s[86:87] op_sel_hi:[1,0]
	v_pk_mul_f32 v[244:245], v[244:245], s[86:87] op_sel_hi:[1,0]
	v_pk_mul_f32 v[246:247], v[246:247], s[86:87] op_sel_hi:[1,0]
	v_pk_mul_f32 v[248:249], v[248:249], s[86:87] op_sel_hi:[1,0]
	v_exp_f32_e32 v242, v242
	v_exp_f32_e32 v243, v243
	v_exp_f32_e32 v244, v244
	v_exp_f32_e32 v245, v245
	v_exp_f32_e32 v246, v246
	v_exp_f32_e32 v247, v247
	v_exp_f32_e32 v248, v248
	v_exp_f32_e32 v249, v249
	v_pk_add_f32 v[242:243], v[242:243], 1.0 op_sel_hi:[1,0]
	v_pk_add_f32 v[244:245], v[244:245], 1.0 op_sel_hi:[1,0]
	v_pk_add_f32 v[246:247], v[246:247], 1.0 op_sel_hi:[1,0]
	v_pk_add_f32 v[248:249], v[248:249], 1.0 op_sel_hi:[1,0]
	v_pk_mul_f32 v[216:217], v[216:217], v[242:243]
	v_pk_mul_f32 v[218:219], v[218:219], v[244:245]
	v_pk_mul_f32 v[220:221], v[220:221], v[246:247]
	v_pk_mul_f32 v[222:223], v[222:223], v[248:249]
	v_pk_mul_f32 v[126:127], v[126:127], v[216:217]
	v_pk_mul_f32 v[128:129], v[128:129], v[218:219]
	v_pk_mul_f32 v[122:123], v[122:123], v[220:221]
	v_pk_mul_f32 v[124:125], v[124:125], v[222:223]
	v_lshlrev_b32_e32 v216, 16, v138
	v_and_b32_e32 v217, 0xffff0000, v138
	v_lshlrev_b32_e32 v218, 16, v139
	v_and_b32_e32 v219, 0xffff0000, v139
	v_lshlrev_b32_e32 v220, 16, v140
	v_and_b32_e32 v221, 0xffff0000, v140
	v_lshlrev_b32_e32 v222, 16, v141
	v_and_b32_e32 v223, 0xffff0000, v141
	v_pk_mul_f32 v[216:217], v[216:217], s[86:87] op_sel_hi:[1,0]
	v_pk_mul_f32 v[218:219], v[218:219], s[86:87] op_sel_hi:[1,0]
	v_pk_mul_f32 v[220:221], v[220:221], s[86:87] op_sel_hi:[1,0]
	v_pk_mul_f32 v[222:223], v[222:223], s[86:87] op_sel_hi:[1,0]
	v_exp_f32_e32 v216, v216
	v_exp_f32_e32 v217, v217
	v_exp_f32_e32 v218, v218
	v_exp_f32_e32 v219, v219
	v_exp_f32_e32 v220, v220
	v_exp_f32_e32 v221, v221
	v_exp_f32_e32 v222, v222
	v_exp_f32_e32 v223, v223
	v_pk_add_f32 v[216:217], v[216:217], 1.0 op_sel_hi:[1,0]
	v_pk_add_f32 v[218:219], v[218:219], 1.0 op_sel_hi:[1,0]
	v_pk_add_f32 v[220:221], v[220:221], 1.0 op_sel_hi:[1,0]
	v_pk_add_f32 v[222:223], v[222:223], 1.0 op_sel_hi:[1,0]
	v_rcp_f32_e32 v216, v216
	v_rcp_f32_e32 v217, v217
	v_rcp_f32_e32 v218, v218
	v_rcp_f32_e32 v219, v219
	v_rcp_f32_e32 v220, v220
	v_rcp_f32_e32 v221, v221
	v_rcp_f32_e32 v222, v222
	v_rcp_f32_e32 v223, v223
	v_lshlrev_b32_e32 v242, 16, v142
	v_and_b32_e32 v243, 0xffff0000, v142
	v_lshlrev_b32_e32 v244, 16, v143
	v_and_b32_e32 v245, 0xffff0000, v143
	v_lshlrev_b32_e32 v246, 16, v144
	v_and_b32_e32 v247, 0xffff0000, v144
	v_lshlrev_b32_e32 v248, 16, v145
	v_and_b32_e32 v249, 0xffff0000, v145
	v_pk_mul_f32 v[242:243], v[242:243], s[86:87] op_sel_hi:[1,0]
	v_pk_mul_f32 v[244:245], v[244:245], s[86:87] op_sel_hi:[1,0]
	v_pk_mul_f32 v[246:247], v[246:247], s[86:87] op_sel_hi:[1,0]
	v_pk_mul_f32 v[248:249], v[248:249], s[86:87] op_sel_hi:[1,0]
	v_exp_f32_e32 v242, v242
	v_exp_f32_e32 v243, v243
	v_exp_f32_e32 v244, v244
	v_exp_f32_e32 v245, v245
	v_exp_f32_e32 v246, v246
	v_exp_f32_e32 v247, v247
	v_exp_f32_e32 v248, v248
	v_exp_f32_e32 v249, v249
	v_pk_add_f32 v[242:243], v[242:243], 1.0 op_sel_hi:[1,0]
	v_pk_add_f32 v[244:245], v[244:245], 1.0 op_sel_hi:[1,0]
	v_pk_add_f32 v[246:247], v[246:247], 1.0 op_sel_hi:[1,0]
	v_pk_add_f32 v[248:249], v[248:249], 1.0 op_sel_hi:[1,0]
	v_pk_mul_f32 v[216:217], v[216:217], v[242:243]
	v_pk_mul_f32 v[218:219], v[218:219], v[244:245]
	v_pk_mul_f32 v[220:221], v[220:221], v[246:247]
	v_pk_mul_f32 v[222:223], v[222:223], v[248:249]
	v_pk_mul_f32 v[94:95], v[94:95], v[216:217]
	v_pk_mul_f32 v[96:97], v[96:97], v[218:219]
	v_pk_mul_f32 v[90:91], v[90:91], v[220:221]
	v_pk_mul_f32 v[92:93], v[92:93], v[222:223]
	s_add_u32 s28, s20, 0x340000
	s_addc_u32 s29, s21, 0
	global_load_dwordx4 v[130:133], v253, s[28:29]
	global_load_dwordx4 v[134:137], v254, s[28:29]
	global_load_dwordx4 v[138:141], v253, s[28:29] offset:256
	global_load_dwordx4 v[142:145], v254, s[28:29] offset:256
	s_waitcnt vmcnt(12)
	v_lshlrev_b32_e32 v216, 16, v146
	v_and_b32_e32 v217, 0xffff0000, v146
	v_lshlrev_b32_e32 v218, 16, v147
	v_and_b32_e32 v219, 0xffff0000, v147
	v_lshlrev_b32_e32 v220, 16, v148
	v_and_b32_e32 v221, 0xffff0000, v148
	v_lshlrev_b32_e32 v222, 16, v149
	v_and_b32_e32 v223, 0xffff0000, v149
	v_pk_mul_f32 v[216:217], v[216:217], s[86:87] op_sel_hi:[1,0]
	v_pk_mul_f32 v[218:219], v[218:219], s[86:87] op_sel_hi:[1,0]
	v_pk_mul_f32 v[220:221], v[220:221], s[86:87] op_sel_hi:[1,0]
	v_pk_mul_f32 v[222:223], v[222:223], s[86:87] op_sel_hi:[1,0]
	v_exp_f32_e32 v216, v216
	v_exp_f32_e32 v217, v217
	v_exp_f32_e32 v218, v218
	v_exp_f32_e32 v219, v219
	v_exp_f32_e32 v220, v220
	v_exp_f32_e32 v221, v221
	v_exp_f32_e32 v222, v222
	v_exp_f32_e32 v223, v223
	v_pk_add_f32 v[216:217], v[216:217], 1.0 op_sel_hi:[1,0]
	v_pk_add_f32 v[218:219], v[218:219], 1.0 op_sel_hi:[1,0]
	v_pk_add_f32 v[220:221], v[220:221], 1.0 op_sel_hi:[1,0]
	v_pk_add_f32 v[222:223], v[222:223], 1.0 op_sel_hi:[1,0]
	v_rcp_f32_e32 v216, v216
	v_rcp_f32_e32 v217, v217
	v_rcp_f32_e32 v218, v218
	v_rcp_f32_e32 v219, v219
	v_rcp_f32_e32 v220, v220
	v_rcp_f32_e32 v221, v221
	v_rcp_f32_e32 v222, v222
	v_rcp_f32_e32 v223, v223
	v_lshlrev_b32_e32 v242, 16, v150
	v_and_b32_e32 v243, 0xffff0000, v150
	v_lshlrev_b32_e32 v244, 16, v151
	v_and_b32_e32 v245, 0xffff0000, v151
	v_lshlrev_b32_e32 v246, 16, v152
	v_and_b32_e32 v247, 0xffff0000, v152
	v_lshlrev_b32_e32 v248, 16, v153
	v_and_b32_e32 v249, 0xffff0000, v153
	v_pk_mul_f32 v[242:243], v[242:243], s[86:87] op_sel_hi:[1,0]
	v_pk_mul_f32 v[244:245], v[244:245], s[86:87] op_sel_hi:[1,0]
	v_pk_mul_f32 v[246:247], v[246:247], s[86:87] op_sel_hi:[1,0]
	v_pk_mul_f32 v[248:249], v[248:249], s[86:87] op_sel_hi:[1,0]
	v_exp_f32_e32 v242, v242
	v_exp_f32_e32 v243, v243
	v_exp_f32_e32 v244, v244
	v_exp_f32_e32 v245, v245
	v_exp_f32_e32 v246, v246
	v_exp_f32_e32 v247, v247
	v_exp_f32_e32 v248, v248
	v_exp_f32_e32 v249, v249
	v_pk_add_f32 v[242:243], v[242:243], 1.0 op_sel_hi:[1,0]
	v_pk_add_f32 v[244:245], v[244:245], 1.0 op_sel_hi:[1,0]
	v_pk_add_f32 v[246:247], v[246:247], 1.0 op_sel_hi:[1,0]
	v_pk_add_f32 v[248:249], v[248:249], 1.0 op_sel_hi:[1,0]
	v_pk_mul_f32 v[216:217], v[216:217], v[242:243]
	v_pk_mul_f32 v[218:219], v[218:219], v[244:245]
	v_pk_mul_f32 v[220:221], v[220:221], v[246:247]
	v_pk_mul_f32 v[222:223], v[222:223], v[248:249]
	v_pk_mul_f32 v[118:119], v[118:119], v[216:217]
	v_pk_mul_f32 v[120:121], v[120:121], v[218:219]
	v_pk_mul_f32 v[114:115], v[114:115], v[220:221]
	v_pk_mul_f32 v[116:117], v[116:117], v[222:223]
	v_lshlrev_b32_e32 v216, 16, v154
	v_and_b32_e32 v217, 0xffff0000, v154
	v_lshlrev_b32_e32 v218, 16, v155
	v_and_b32_e32 v219, 0xffff0000, v155
	v_lshlrev_b32_e32 v220, 16, v156
	v_and_b32_e32 v221, 0xffff0000, v156
	v_lshlrev_b32_e32 v222, 16, v157
	v_and_b32_e32 v223, 0xffff0000, v157
	v_pk_mul_f32 v[216:217], v[216:217], s[86:87] op_sel_hi:[1,0]
	v_pk_mul_f32 v[218:219], v[218:219], s[86:87] op_sel_hi:[1,0]
	v_pk_mul_f32 v[220:221], v[220:221], s[86:87] op_sel_hi:[1,0]
	v_pk_mul_f32 v[222:223], v[222:223], s[86:87] op_sel_hi:[1,0]
	v_exp_f32_e32 v216, v216
	v_exp_f32_e32 v217, v217
	v_exp_f32_e32 v218, v218
	v_exp_f32_e32 v219, v219
	v_exp_f32_e32 v220, v220
	v_exp_f32_e32 v221, v221
	v_exp_f32_e32 v222, v222
	v_exp_f32_e32 v223, v223
	v_pk_add_f32 v[216:217], v[216:217], 1.0 op_sel_hi:[1,0]
	v_pk_add_f32 v[218:219], v[218:219], 1.0 op_sel_hi:[1,0]
	v_pk_add_f32 v[220:221], v[220:221], 1.0 op_sel_hi:[1,0]
	v_pk_add_f32 v[222:223], v[222:223], 1.0 op_sel_hi:[1,0]
	v_rcp_f32_e32 v216, v216
	v_rcp_f32_e32 v217, v217
	v_rcp_f32_e32 v218, v218
	v_rcp_f32_e32 v219, v219
	v_rcp_f32_e32 v220, v220
	v_rcp_f32_e32 v221, v221
	v_rcp_f32_e32 v222, v222
	v_rcp_f32_e32 v223, v223
	v_lshlrev_b32_e32 v242, 16, v158
	v_and_b32_e32 v243, 0xffff0000, v158
	v_lshlrev_b32_e32 v244, 16, v159
	v_and_b32_e32 v245, 0xffff0000, v159
	v_lshlrev_b32_e32 v246, 16, v160
	v_and_b32_e32 v247, 0xffff0000, v160
	v_lshlrev_b32_e32 v248, 16, v161
	v_and_b32_e32 v249, 0xffff0000, v161
	v_pk_mul_f32 v[242:243], v[242:243], s[86:87] op_sel_hi:[1,0]
	v_pk_mul_f32 v[244:245], v[244:245], s[86:87] op_sel_hi:[1,0]
	v_pk_mul_f32 v[246:247], v[246:247], s[86:87] op_sel_hi:[1,0]
	v_pk_mul_f32 v[248:249], v[248:249], s[86:87] op_sel_hi:[1,0]
	v_exp_f32_e32 v242, v242
	v_exp_f32_e32 v243, v243
	v_exp_f32_e32 v244, v244
	v_exp_f32_e32 v245, v245
	v_exp_f32_e32 v246, v246
	v_exp_f32_e32 v247, v247
	v_exp_f32_e32 v248, v248
	v_exp_f32_e32 v249, v249
	v_pk_add_f32 v[242:243], v[242:243], 1.0 op_sel_hi:[1,0]
	v_pk_add_f32 v[244:245], v[244:245], 1.0 op_sel_hi:[1,0]
	v_pk_add_f32 v[246:247], v[246:247], 1.0 op_sel_hi:[1,0]
	v_pk_add_f32 v[248:249], v[248:249], 1.0 op_sel_hi:[1,0]
	v_pk_mul_f32 v[216:217], v[216:217], v[242:243]
	v_pk_mul_f32 v[218:219], v[218:219], v[244:245]
	v_pk_mul_f32 v[220:221], v[220:221], v[246:247]
	v_pk_mul_f32 v[222:223], v[222:223], v[248:249]
	v_pk_mul_f32 v[86:87], v[86:87], v[216:217]
	v_pk_mul_f32 v[88:89], v[88:89], v[218:219]
	v_pk_mul_f32 v[82:83], v[82:83], v[220:221]
	v_pk_mul_f32 v[84:85], v[84:85], v[222:223]
	s_add_u32 s28, s20, 0x3a8000
	s_addc_u32 s29, s21, 0
	global_load_dwordx4 v[146:149], v253, s[28:29]
	global_load_dwordx4 v[150:153], v254, s[28:29]
	global_load_dwordx4 v[154:157], v253, s[28:29] offset:256
	global_load_dwordx4 v[158:161], v254, s[28:29] offset:256
	s_waitcnt vmcnt(12)
	v_lshlrev_b32_e32 v216, 16, v162
	v_and_b32_e32 v217, 0xffff0000, v162
	v_lshlrev_b32_e32 v218, 16, v163
	v_and_b32_e32 v219, 0xffff0000, v163
	v_lshlrev_b32_e32 v220, 16, v164
	v_and_b32_e32 v221, 0xffff0000, v164
	v_lshlrev_b32_e32 v222, 16, v165
	v_and_b32_e32 v223, 0xffff0000, v165
	v_pk_mul_f32 v[216:217], v[216:217], s[86:87] op_sel_hi:[1,0]
	v_pk_mul_f32 v[218:219], v[218:219], s[86:87] op_sel_hi:[1,0]
	v_pk_mul_f32 v[220:221], v[220:221], s[86:87] op_sel_hi:[1,0]
	v_pk_mul_f32 v[222:223], v[222:223], s[86:87] op_sel_hi:[1,0]
	v_exp_f32_e32 v216, v216
	v_exp_f32_e32 v217, v217
	v_exp_f32_e32 v218, v218
	v_exp_f32_e32 v219, v219
	v_exp_f32_e32 v220, v220
	v_exp_f32_e32 v221, v221
	v_exp_f32_e32 v222, v222
	v_exp_f32_e32 v223, v223
	v_pk_add_f32 v[216:217], v[216:217], 1.0 op_sel_hi:[1,0]
	v_pk_add_f32 v[218:219], v[218:219], 1.0 op_sel_hi:[1,0]
	v_pk_add_f32 v[220:221], v[220:221], 1.0 op_sel_hi:[1,0]
	v_pk_add_f32 v[222:223], v[222:223], 1.0 op_sel_hi:[1,0]
	v_rcp_f32_e32 v216, v216
	v_rcp_f32_e32 v217, v217
	v_rcp_f32_e32 v218, v218
	v_rcp_f32_e32 v219, v219
	v_rcp_f32_e32 v220, v220
	v_rcp_f32_e32 v221, v221
	v_rcp_f32_e32 v222, v222
	v_rcp_f32_e32 v223, v223
	v_lshlrev_b32_e32 v242, 16, v166
	v_and_b32_e32 v243, 0xffff0000, v166
	v_lshlrev_b32_e32 v244, 16, v167
	v_and_b32_e32 v245, 0xffff0000, v167
	v_lshlrev_b32_e32 v246, 16, v168
	v_and_b32_e32 v247, 0xffff0000, v168
	v_lshlrev_b32_e32 v248, 16, v169
	v_and_b32_e32 v249, 0xffff0000, v169
	v_pk_mul_f32 v[242:243], v[242:243], s[86:87] op_sel_hi:[1,0]
	v_pk_mul_f32 v[244:245], v[244:245], s[86:87] op_sel_hi:[1,0]
	v_pk_mul_f32 v[246:247], v[246:247], s[86:87] op_sel_hi:[1,0]
	v_pk_mul_f32 v[248:249], v[248:249], s[86:87] op_sel_hi:[1,0]
	v_exp_f32_e32 v242, v242
	v_exp_f32_e32 v243, v243
	v_exp_f32_e32 v244, v244
	v_exp_f32_e32 v245, v245
	v_exp_f32_e32 v246, v246
	v_exp_f32_e32 v247, v247
	v_exp_f32_e32 v248, v248
	v_exp_f32_e32 v249, v249
	v_pk_add_f32 v[242:243], v[242:243], 1.0 op_sel_hi:[1,0]
	v_pk_add_f32 v[244:245], v[244:245], 1.0 op_sel_hi:[1,0]
	v_pk_add_f32 v[246:247], v[246:247], 1.0 op_sel_hi:[1,0]
	v_pk_add_f32 v[248:249], v[248:249], 1.0 op_sel_hi:[1,0]
	v_pk_mul_f32 v[216:217], v[216:217], v[242:243]
	v_pk_mul_f32 v[218:219], v[218:219], v[244:245]
	v_pk_mul_f32 v[220:221], v[220:221], v[246:247]
	v_pk_mul_f32 v[222:223], v[222:223], v[248:249]
	v_pk_mul_f32 v[110:111], v[110:111], v[216:217]
	v_pk_mul_f32 v[112:113], v[112:113], v[218:219]
	v_pk_mul_f32 v[106:107], v[106:107], v[220:221]
	v_pk_mul_f32 v[108:109], v[108:109], v[222:223]
	v_lshlrev_b32_e32 v216, 16, v170
	v_and_b32_e32 v217, 0xffff0000, v170
	v_lshlrev_b32_e32 v218, 16, v171
	v_and_b32_e32 v219, 0xffff0000, v171
	v_lshlrev_b32_e32 v220, 16, v172
	v_and_b32_e32 v221, 0xffff0000, v172
	v_lshlrev_b32_e32 v222, 16, v173
	v_and_b32_e32 v223, 0xffff0000, v173
	v_pk_mul_f32 v[216:217], v[216:217], s[86:87] op_sel_hi:[1,0]
	v_pk_mul_f32 v[218:219], v[218:219], s[86:87] op_sel_hi:[1,0]
	v_pk_mul_f32 v[220:221], v[220:221], s[86:87] op_sel_hi:[1,0]
	v_pk_mul_f32 v[222:223], v[222:223], s[86:87] op_sel_hi:[1,0]
	v_exp_f32_e32 v216, v216
	v_exp_f32_e32 v217, v217
	v_exp_f32_e32 v218, v218
	v_exp_f32_e32 v219, v219
	v_exp_f32_e32 v220, v220
	v_exp_f32_e32 v221, v221
	v_exp_f32_e32 v222, v222
	v_exp_f32_e32 v223, v223
	v_pk_add_f32 v[216:217], v[216:217], 1.0 op_sel_hi:[1,0]
	v_pk_add_f32 v[218:219], v[218:219], 1.0 op_sel_hi:[1,0]
	v_pk_add_f32 v[220:221], v[220:221], 1.0 op_sel_hi:[1,0]
	v_pk_add_f32 v[222:223], v[222:223], 1.0 op_sel_hi:[1,0]
	v_rcp_f32_e32 v216, v216
	v_rcp_f32_e32 v217, v217
	v_rcp_f32_e32 v218, v218
	v_rcp_f32_e32 v219, v219
	v_rcp_f32_e32 v220, v220
	v_rcp_f32_e32 v221, v221
	v_rcp_f32_e32 v222, v222
	v_rcp_f32_e32 v223, v223
	v_lshlrev_b32_e32 v242, 16, v174
	v_and_b32_e32 v243, 0xffff0000, v174
	v_lshlrev_b32_e32 v244, 16, v175
	v_and_b32_e32 v245, 0xffff0000, v175
	v_lshlrev_b32_e32 v246, 16, v176
	v_and_b32_e32 v247, 0xffff0000, v176
	v_lshlrev_b32_e32 v248, 16, v177
	v_and_b32_e32 v249, 0xffff0000, v177
	v_pk_mul_f32 v[242:243], v[242:243], s[86:87] op_sel_hi:[1,0]
	v_pk_mul_f32 v[244:245], v[244:245], s[86:87] op_sel_hi:[1,0]
	v_pk_mul_f32 v[246:247], v[246:247], s[86:87] op_sel_hi:[1,0]
	v_pk_mul_f32 v[248:249], v[248:249], s[86:87] op_sel_hi:[1,0]
	v_exp_f32_e32 v242, v242
	v_exp_f32_e32 v243, v243
	v_exp_f32_e32 v244, v244
	v_exp_f32_e32 v245, v245
	v_exp_f32_e32 v246, v246
	v_exp_f32_e32 v247, v247
	v_exp_f32_e32 v248, v248
	v_exp_f32_e32 v249, v249
	v_pk_add_f32 v[242:243], v[242:243], 1.0 op_sel_hi:[1,0]
	v_pk_add_f32 v[244:245], v[244:245], 1.0 op_sel_hi:[1,0]
	v_pk_add_f32 v[246:247], v[246:247], 1.0 op_sel_hi:[1,0]
	v_pk_add_f32 v[248:249], v[248:249], 1.0 op_sel_hi:[1,0]
	v_pk_mul_f32 v[216:217], v[216:217], v[242:243]
	v_pk_mul_f32 v[218:219], v[218:219], v[244:245]
	v_pk_mul_f32 v[220:221], v[220:221], v[246:247]
	v_pk_mul_f32 v[222:223], v[222:223], v[248:249]
	v_pk_mul_f32 v[78:79], v[78:79], v[216:217]
	v_pk_mul_f32 v[80:81], v[80:81], v[218:219]
	v_pk_mul_f32 v[74:75], v[74:75], v[220:221]
	v_pk_mul_f32 v[76:77], v[76:77], v[222:223]
	s_add_u32 s28, s20, 0x410000
	s_addc_u32 s29, s21, 0
	global_load_dwordx4 v[162:165], v253, s[28:29]
	global_load_dwordx4 v[166:169], v254, s[28:29]
	global_load_dwordx4 v[170:173], v253, s[28:29] offset:256
	global_load_dwordx4 v[174:177], v254, s[28:29] offset:256
	s_waitcnt vmcnt(12)
	v_lshlrev_b32_e32 v216, 16, v178
	v_and_b32_e32 v217, 0xffff0000, v178
	v_lshlrev_b32_e32 v218, 16, v179
	v_and_b32_e32 v219, 0xffff0000, v179
	v_lshlrev_b32_e32 v220, 16, v180
	v_and_b32_e32 v221, 0xffff0000, v180
	v_lshlrev_b32_e32 v222, 16, v181
	v_and_b32_e32 v223, 0xffff0000, v181
	v_pk_mul_f32 v[216:217], v[216:217], s[86:87] op_sel_hi:[1,0]
	v_pk_mul_f32 v[218:219], v[218:219], s[86:87] op_sel_hi:[1,0]
	v_pk_mul_f32 v[220:221], v[220:221], s[86:87] op_sel_hi:[1,0]
	v_pk_mul_f32 v[222:223], v[222:223], s[86:87] op_sel_hi:[1,0]
	v_exp_f32_e32 v216, v216
	v_exp_f32_e32 v217, v217
	v_exp_f32_e32 v218, v218
	v_exp_f32_e32 v219, v219
	v_exp_f32_e32 v220, v220
	v_exp_f32_e32 v221, v221
	v_exp_f32_e32 v222, v222
	v_exp_f32_e32 v223, v223
	v_pk_add_f32 v[216:217], v[216:217], 1.0 op_sel_hi:[1,0]
	v_pk_add_f32 v[218:219], v[218:219], 1.0 op_sel_hi:[1,0]
	v_pk_add_f32 v[220:221], v[220:221], 1.0 op_sel_hi:[1,0]
	v_pk_add_f32 v[222:223], v[222:223], 1.0 op_sel_hi:[1,0]
	v_rcp_f32_e32 v216, v216
	v_rcp_f32_e32 v217, v217
	v_rcp_f32_e32 v218, v218
	v_rcp_f32_e32 v219, v219
	v_rcp_f32_e32 v220, v220
	v_rcp_f32_e32 v221, v221
	v_rcp_f32_e32 v222, v222
	v_rcp_f32_e32 v223, v223
	v_lshlrev_b32_e32 v242, 16, v182
	v_and_b32_e32 v243, 0xffff0000, v182
	v_lshlrev_b32_e32 v244, 16, v183
	v_and_b32_e32 v245, 0xffff0000, v183
	v_lshlrev_b32_e32 v246, 16, v184
	v_and_b32_e32 v247, 0xffff0000, v184
	v_lshlrev_b32_e32 v248, 16, v185
	v_and_b32_e32 v249, 0xffff0000, v185
	v_pk_mul_f32 v[242:243], v[242:243], s[86:87] op_sel_hi:[1,0]
	v_pk_mul_f32 v[244:245], v[244:245], s[86:87] op_sel_hi:[1,0]
	v_pk_mul_f32 v[246:247], v[246:247], s[86:87] op_sel_hi:[1,0]
	v_pk_mul_f32 v[248:249], v[248:249], s[86:87] op_sel_hi:[1,0]
	v_exp_f32_e32 v242, v242
	v_exp_f32_e32 v243, v243
	v_exp_f32_e32 v244, v244
	v_exp_f32_e32 v245, v245
	v_exp_f32_e32 v246, v246
	v_exp_f32_e32 v247, v247
	v_exp_f32_e32 v248, v248
	v_exp_f32_e32 v249, v249
	v_pk_add_f32 v[242:243], v[242:243], 1.0 op_sel_hi:[1,0]
	v_pk_add_f32 v[244:245], v[244:245], 1.0 op_sel_hi:[1,0]
	v_pk_add_f32 v[246:247], v[246:247], 1.0 op_sel_hi:[1,0]
	v_pk_add_f32 v[248:249], v[248:249], 1.0 op_sel_hi:[1,0]
	v_pk_mul_f32 v[216:217], v[216:217], v[242:243]
	v_pk_mul_f32 v[218:219], v[218:219], v[244:245]
	v_pk_mul_f32 v[220:221], v[220:221], v[246:247]
	v_pk_mul_f32 v[222:223], v[222:223], v[248:249]
	v_pk_mul_f32 v[102:103], v[102:103], v[216:217]
	v_pk_mul_f32 v[104:105], v[104:105], v[218:219]
	v_pk_mul_f32 v[98:99], v[98:99], v[220:221]
	v_pk_mul_f32 v[100:101], v[100:101], v[222:223]
	v_lshlrev_b32_e32 v216, 16, v186
	v_and_b32_e32 v217, 0xffff0000, v186
	v_lshlrev_b32_e32 v218, 16, v187
	v_and_b32_e32 v219, 0xffff0000, v187
	v_lshlrev_b32_e32 v220, 16, v188
	v_and_b32_e32 v221, 0xffff0000, v188
	v_lshlrev_b32_e32 v222, 16, v189
	v_and_b32_e32 v223, 0xffff0000, v189
	v_pk_mul_f32 v[216:217], v[216:217], s[86:87] op_sel_hi:[1,0]
	v_pk_mul_f32 v[218:219], v[218:219], s[86:87] op_sel_hi:[1,0]
	v_pk_mul_f32 v[220:221], v[220:221], s[86:87] op_sel_hi:[1,0]
	v_pk_mul_f32 v[222:223], v[222:223], s[86:87] op_sel_hi:[1,0]
	v_exp_f32_e32 v216, v216
	v_exp_f32_e32 v217, v217
	v_exp_f32_e32 v218, v218
	v_exp_f32_e32 v219, v219
	v_exp_f32_e32 v220, v220
	v_exp_f32_e32 v221, v221
	v_exp_f32_e32 v222, v222
	v_exp_f32_e32 v223, v223
	v_pk_add_f32 v[216:217], v[216:217], 1.0 op_sel_hi:[1,0]
	v_pk_add_f32 v[218:219], v[218:219], 1.0 op_sel_hi:[1,0]
	v_pk_add_f32 v[220:221], v[220:221], 1.0 op_sel_hi:[1,0]
	v_pk_add_f32 v[222:223], v[222:223], 1.0 op_sel_hi:[1,0]
	v_rcp_f32_e32 v216, v216
	v_rcp_f32_e32 v217, v217
	v_rcp_f32_e32 v218, v218
	v_rcp_f32_e32 v219, v219
	v_rcp_f32_e32 v220, v220
	v_rcp_f32_e32 v221, v221
	v_rcp_f32_e32 v222, v222
	v_rcp_f32_e32 v223, v223
	v_lshlrev_b32_e32 v242, 16, v190
	v_and_b32_e32 v243, 0xffff0000, v190
	v_lshlrev_b32_e32 v244, 16, v191
	v_and_b32_e32 v245, 0xffff0000, v191
	v_lshlrev_b32_e32 v246, 16, v192
	v_and_b32_e32 v247, 0xffff0000, v192
	v_lshlrev_b32_e32 v248, 16, v193
	v_and_b32_e32 v249, 0xffff0000, v193
	v_pk_mul_f32 v[242:243], v[242:243], s[86:87] op_sel_hi:[1,0]
	v_pk_mul_f32 v[244:245], v[244:245], s[86:87] op_sel_hi:[1,0]
	v_pk_mul_f32 v[246:247], v[246:247], s[86:87] op_sel_hi:[1,0]
	v_pk_mul_f32 v[248:249], v[248:249], s[86:87] op_sel_hi:[1,0]
	v_exp_f32_e32 v242, v242
	v_exp_f32_e32 v243, v243
	v_exp_f32_e32 v244, v244
	v_exp_f32_e32 v245, v245
	v_exp_f32_e32 v246, v246
	v_exp_f32_e32 v247, v247
	v_exp_f32_e32 v248, v248
	v_exp_f32_e32 v249, v249
	v_pk_add_f32 v[242:243], v[242:243], 1.0 op_sel_hi:[1,0]
	v_pk_add_f32 v[244:245], v[244:245], 1.0 op_sel_hi:[1,0]
	v_pk_add_f32 v[246:247], v[246:247], 1.0 op_sel_hi:[1,0]
	v_pk_add_f32 v[248:249], v[248:249], 1.0 op_sel_hi:[1,0]
	v_pk_mul_f32 v[216:217], v[216:217], v[242:243]
	v_pk_mul_f32 v[218:219], v[218:219], v[244:245]
	v_pk_mul_f32 v[220:221], v[220:221], v[246:247]
	v_pk_mul_f32 v[222:223], v[222:223], v[248:249]
	v_pk_mul_f32 v[70:71], v[70:71], v[216:217]
	v_pk_mul_f32 v[72:73], v[72:73], v[218:219]
	v_pk_mul_f32 v[66:67], v[66:67], v[220:221]
	v_pk_mul_f32 v[68:69], v[68:69], v[222:223]
	s_add_u32 s28, s20, 0x478000
	s_addc_u32 s29, s21, 0
	global_load_dwordx4 v[178:181], v253, s[28:29]
	global_load_dwordx4 v[182:185], v254, s[28:29]
	global_load_dwordx4 v[186:189], v253, s[28:29] offset:256
	global_load_dwordx4 v[190:193], v254, s[28:29] offset:256
	s_waitcnt vmcnt(12)
	v_lshlrev_b32_e32 v216, 16, v130
	v_and_b32_e32 v217, 0xffff0000, v130
	v_lshlrev_b32_e32 v218, 16, v131
	v_and_b32_e32 v219, 0xffff0000, v131
	v_lshlrev_b32_e32 v220, 16, v132
	v_and_b32_e32 v221, 0xffff0000, v132
	v_lshlrev_b32_e32 v222, 16, v133
	v_and_b32_e32 v223, 0xffff0000, v133
	v_pk_mul_f32 v[216:217], v[216:217], s[86:87] op_sel_hi:[1,0]
	v_pk_mul_f32 v[218:219], v[218:219], s[86:87] op_sel_hi:[1,0]
	v_pk_mul_f32 v[220:221], v[220:221], s[86:87] op_sel_hi:[1,0]
	v_pk_mul_f32 v[222:223], v[222:223], s[86:87] op_sel_hi:[1,0]
	v_exp_f32_e32 v216, v216
	v_exp_f32_e32 v217, v217
	v_exp_f32_e32 v218, v218
	v_exp_f32_e32 v219, v219
	v_exp_f32_e32 v220, v220
	v_exp_f32_e32 v221, v221
	v_exp_f32_e32 v222, v222
	v_exp_f32_e32 v223, v223
	v_pk_add_f32 v[216:217], v[216:217], 1.0 op_sel_hi:[1,0]
	v_pk_add_f32 v[218:219], v[218:219], 1.0 op_sel_hi:[1,0]
	v_pk_add_f32 v[220:221], v[220:221], 1.0 op_sel_hi:[1,0]
	v_pk_add_f32 v[222:223], v[222:223], 1.0 op_sel_hi:[1,0]
	v_rcp_f32_e32 v216, v216
	v_rcp_f32_e32 v217, v217
	v_rcp_f32_e32 v218, v218
	v_rcp_f32_e32 v219, v219
	v_rcp_f32_e32 v220, v220
	v_rcp_f32_e32 v221, v221
	v_rcp_f32_e32 v222, v222
	v_rcp_f32_e32 v223, v223
	v_lshlrev_b32_e32 v242, 16, v134
	v_and_b32_e32 v243, 0xffff0000, v134
	v_lshlrev_b32_e32 v244, 16, v135
	v_and_b32_e32 v245, 0xffff0000, v135
	v_lshlrev_b32_e32 v246, 16, v136
	v_and_b32_e32 v247, 0xffff0000, v136
	v_lshlrev_b32_e32 v248, 16, v137
	v_and_b32_e32 v249, 0xffff0000, v137
	v_pk_mul_f32 v[242:243], v[242:243], s[86:87] op_sel_hi:[1,0]
	v_pk_mul_f32 v[244:245], v[244:245], s[86:87] op_sel_hi:[1,0]
	v_pk_mul_f32 v[246:247], v[246:247], s[86:87] op_sel_hi:[1,0]
	v_pk_mul_f32 v[248:249], v[248:249], s[86:87] op_sel_hi:[1,0]
	v_exp_f32_e32 v242, v242
	v_exp_f32_e32 v243, v243
	v_exp_f32_e32 v244, v244
	v_exp_f32_e32 v245, v245
	v_exp_f32_e32 v246, v246
	v_exp_f32_e32 v247, v247
	v_exp_f32_e32 v248, v248
	v_exp_f32_e32 v249, v249
	v_pk_add_f32 v[242:243], v[242:243], 1.0 op_sel_hi:[1,0]
	v_pk_add_f32 v[244:245], v[244:245], 1.0 op_sel_hi:[1,0]
	v_pk_add_f32 v[246:247], v[246:247], 1.0 op_sel_hi:[1,0]
	v_pk_add_f32 v[248:249], v[248:249], 1.0 op_sel_hi:[1,0]
	v_pk_mul_f32 v[216:217], v[216:217], v[242:243]
	v_pk_mul_f32 v[218:219], v[218:219], v[244:245]
	v_pk_mul_f32 v[220:221], v[220:221], v[246:247]
	v_pk_mul_f32 v[222:223], v[222:223], v[248:249]
	v_pk_mul_f32 v[62:63], v[62:63], v[216:217]
	v_pk_mul_f32 v[64:65], v[64:65], v[218:219]
	v_pk_mul_f32 v[58:59], v[58:59], v[220:221]
	v_pk_mul_f32 v[60:61], v[60:61], v[222:223]
	v_lshlrev_b32_e32 v216, 16, v138
	v_and_b32_e32 v217, 0xffff0000, v138
	v_lshlrev_b32_e32 v218, 16, v139
	v_and_b32_e32 v219, 0xffff0000, v139
	v_lshlrev_b32_e32 v220, 16, v140
	v_and_b32_e32 v221, 0xffff0000, v140
	v_lshlrev_b32_e32 v222, 16, v141
	v_and_b32_e32 v223, 0xffff0000, v141
	v_pk_mul_f32 v[216:217], v[216:217], s[86:87] op_sel_hi:[1,0]
	v_pk_mul_f32 v[218:219], v[218:219], s[86:87] op_sel_hi:[1,0]
	v_pk_mul_f32 v[220:221], v[220:221], s[86:87] op_sel_hi:[1,0]
	v_pk_mul_f32 v[222:223], v[222:223], s[86:87] op_sel_hi:[1,0]
	v_exp_f32_e32 v216, v216
	v_exp_f32_e32 v217, v217
	v_exp_f32_e32 v218, v218
	v_exp_f32_e32 v219, v219
	v_exp_f32_e32 v220, v220
	v_exp_f32_e32 v221, v221
	v_exp_f32_e32 v222, v222
	v_exp_f32_e32 v223, v223
	v_pk_add_f32 v[216:217], v[216:217], 1.0 op_sel_hi:[1,0]
	v_pk_add_f32 v[218:219], v[218:219], 1.0 op_sel_hi:[1,0]
	v_pk_add_f32 v[220:221], v[220:221], 1.0 op_sel_hi:[1,0]
	v_pk_add_f32 v[222:223], v[222:223], 1.0 op_sel_hi:[1,0]
	v_rcp_f32_e32 v216, v216
	v_rcp_f32_e32 v217, v217
	v_rcp_f32_e32 v218, v218
	v_rcp_f32_e32 v219, v219
	v_rcp_f32_e32 v220, v220
	v_rcp_f32_e32 v221, v221
	v_rcp_f32_e32 v222, v222
	v_rcp_f32_e32 v223, v223
	v_lshlrev_b32_e32 v242, 16, v142
	v_and_b32_e32 v243, 0xffff0000, v142
	v_lshlrev_b32_e32 v244, 16, v143
	v_and_b32_e32 v245, 0xffff0000, v143
	v_lshlrev_b32_e32 v246, 16, v144
	v_and_b32_e32 v247, 0xffff0000, v144
	v_lshlrev_b32_e32 v248, 16, v145
	v_and_b32_e32 v249, 0xffff0000, v145
	v_pk_mul_f32 v[242:243], v[242:243], s[86:87] op_sel_hi:[1,0]
	v_pk_mul_f32 v[244:245], v[244:245], s[86:87] op_sel_hi:[1,0]
	v_pk_mul_f32 v[246:247], v[246:247], s[86:87] op_sel_hi:[1,0]
	v_pk_mul_f32 v[248:249], v[248:249], s[86:87] op_sel_hi:[1,0]
	v_exp_f32_e32 v242, v242
	v_exp_f32_e32 v243, v243
	v_exp_f32_e32 v244, v244
	v_exp_f32_e32 v245, v245
	v_exp_f32_e32 v246, v246
	v_exp_f32_e32 v247, v247
	v_exp_f32_e32 v248, v248
	v_exp_f32_e32 v249, v249
	v_pk_add_f32 v[242:243], v[242:243], 1.0 op_sel_hi:[1,0]
	v_pk_add_f32 v[244:245], v[244:245], 1.0 op_sel_hi:[1,0]
	v_pk_add_f32 v[246:247], v[246:247], 1.0 op_sel_hi:[1,0]
	v_pk_add_f32 v[248:249], v[248:249], 1.0 op_sel_hi:[1,0]
	v_pk_mul_f32 v[216:217], v[216:217], v[242:243]
	v_pk_mul_f32 v[218:219], v[218:219], v[244:245]
	v_pk_mul_f32 v[220:221], v[220:221], v[246:247]
	v_pk_mul_f32 v[222:223], v[222:223], v[248:249]
	v_pk_mul_f32 v[30:31], v[30:31], v[216:217]
	v_pk_mul_f32 v[32:33], v[32:33], v[218:219]
	v_pk_mul_f32 v[26:27], v[26:27], v[220:221]
	v_pk_mul_f32 v[28:29], v[28:29], v[222:223]
	s_waitcnt vmcnt(8)
	v_lshlrev_b32_e32 v216, 16, v146
	v_and_b32_e32 v217, 0xffff0000, v146
	v_lshlrev_b32_e32 v218, 16, v147
	v_and_b32_e32 v219, 0xffff0000, v147
	v_lshlrev_b32_e32 v220, 16, v148
	v_and_b32_e32 v221, 0xffff0000, v148
	v_lshlrev_b32_e32 v222, 16, v149
	v_and_b32_e32 v223, 0xffff0000, v149
	v_pk_mul_f32 v[216:217], v[216:217], s[86:87] op_sel_hi:[1,0]
	v_pk_mul_f32 v[218:219], v[218:219], s[86:87] op_sel_hi:[1,0]
	v_pk_mul_f32 v[220:221], v[220:221], s[86:87] op_sel_hi:[1,0]
	v_pk_mul_f32 v[222:223], v[222:223], s[86:87] op_sel_hi:[1,0]
	v_exp_f32_e32 v216, v216
	v_exp_f32_e32 v217, v217
	v_exp_f32_e32 v218, v218
	v_exp_f32_e32 v219, v219
	v_exp_f32_e32 v220, v220
	v_exp_f32_e32 v221, v221
	v_exp_f32_e32 v222, v222
	v_exp_f32_e32 v223, v223
	v_pk_add_f32 v[216:217], v[216:217], 1.0 op_sel_hi:[1,0]
	v_pk_add_f32 v[218:219], v[218:219], 1.0 op_sel_hi:[1,0]
	v_pk_add_f32 v[220:221], v[220:221], 1.0 op_sel_hi:[1,0]
	v_pk_add_f32 v[222:223], v[222:223], 1.0 op_sel_hi:[1,0]
	v_rcp_f32_e32 v216, v216
	v_rcp_f32_e32 v217, v217
	v_rcp_f32_e32 v218, v218
	v_rcp_f32_e32 v219, v219
	v_rcp_f32_e32 v220, v220
	v_rcp_f32_e32 v221, v221
	v_rcp_f32_e32 v222, v222
	v_rcp_f32_e32 v223, v223
	v_lshlrev_b32_e32 v242, 16, v150
	v_and_b32_e32 v243, 0xffff0000, v150
	v_lshlrev_b32_e32 v244, 16, v151
	v_and_b32_e32 v245, 0xffff0000, v151
	v_lshlrev_b32_e32 v246, 16, v152
	v_and_b32_e32 v247, 0xffff0000, v152
	v_lshlrev_b32_e32 v248, 16, v153
	v_and_b32_e32 v249, 0xffff0000, v153
	v_pk_mul_f32 v[242:243], v[242:243], s[86:87] op_sel_hi:[1,0]
	v_pk_mul_f32 v[244:245], v[244:245], s[86:87] op_sel_hi:[1,0]
	v_pk_mul_f32 v[246:247], v[246:247], s[86:87] op_sel_hi:[1,0]
	v_pk_mul_f32 v[248:249], v[248:249], s[86:87] op_sel_hi:[1,0]
	v_exp_f32_e32 v242, v242
	v_exp_f32_e32 v243, v243
	v_exp_f32_e32 v244, v244
	v_exp_f32_e32 v245, v245
	v_exp_f32_e32 v246, v246
	v_exp_f32_e32 v247, v247
	v_exp_f32_e32 v248, v248
	v_exp_f32_e32 v249, v249
	v_pk_add_f32 v[242:243], v[242:243], 1.0 op_sel_hi:[1,0]
	v_pk_add_f32 v[244:245], v[244:245], 1.0 op_sel_hi:[1,0]
	v_pk_add_f32 v[246:247], v[246:247], 1.0 op_sel_hi:[1,0]
	v_pk_add_f32 v[248:249], v[248:249], 1.0 op_sel_hi:[1,0]
	v_pk_mul_f32 v[216:217], v[216:217], v[242:243]
	v_pk_mul_f32 v[218:219], v[218:219], v[244:245]
	v_pk_mul_f32 v[220:221], v[220:221], v[246:247]
	v_pk_mul_f32 v[222:223], v[222:223], v[248:249]
	v_pk_mul_f32 v[54:55], v[54:55], v[216:217]
	v_pk_mul_f32 v[56:57], v[56:57], v[218:219]
	v_pk_mul_f32 v[50:51], v[50:51], v[220:221]
	v_pk_mul_f32 v[52:53], v[52:53], v[222:223]
	v_lshlrev_b32_e32 v216, 16, v154
	v_and_b32_e32 v217, 0xffff0000, v154
	v_lshlrev_b32_e32 v218, 16, v155
	v_and_b32_e32 v219, 0xffff0000, v155
	v_lshlrev_b32_e32 v220, 16, v156
	v_and_b32_e32 v221, 0xffff0000, v156
	v_lshlrev_b32_e32 v222, 16, v157
	v_and_b32_e32 v223, 0xffff0000, v157
	v_pk_mul_f32 v[216:217], v[216:217], s[86:87] op_sel_hi:[1,0]
	v_pk_mul_f32 v[218:219], v[218:219], s[86:87] op_sel_hi:[1,0]
	v_pk_mul_f32 v[220:221], v[220:221], s[86:87] op_sel_hi:[1,0]
	v_pk_mul_f32 v[222:223], v[222:223], s[86:87] op_sel_hi:[1,0]
	v_exp_f32_e32 v216, v216
	v_exp_f32_e32 v217, v217
	v_exp_f32_e32 v218, v218
	v_exp_f32_e32 v219, v219
	v_exp_f32_e32 v220, v220
	v_exp_f32_e32 v221, v221
	v_exp_f32_e32 v222, v222
	v_exp_f32_e32 v223, v223
	v_pk_add_f32 v[216:217], v[216:217], 1.0 op_sel_hi:[1,0]
	v_pk_add_f32 v[218:219], v[218:219], 1.0 op_sel_hi:[1,0]
	v_pk_add_f32 v[220:221], v[220:221], 1.0 op_sel_hi:[1,0]
	v_pk_add_f32 v[222:223], v[222:223], 1.0 op_sel_hi:[1,0]
	v_rcp_f32_e32 v216, v216
	v_rcp_f32_e32 v217, v217
	v_rcp_f32_e32 v218, v218
	v_rcp_f32_e32 v219, v219
	v_rcp_f32_e32 v220, v220
	v_rcp_f32_e32 v221, v221
	v_rcp_f32_e32 v222, v222
	v_rcp_f32_e32 v223, v223
	v_lshlrev_b32_e32 v242, 16, v158
	v_and_b32_e32 v243, 0xffff0000, v158
	v_lshlrev_b32_e32 v244, 16, v159
	v_and_b32_e32 v245, 0xffff0000, v159
	v_lshlrev_b32_e32 v246, 16, v160
	v_and_b32_e32 v247, 0xffff0000, v160
	v_lshlrev_b32_e32 v248, 16, v161
	v_and_b32_e32 v249, 0xffff0000, v161
	v_pk_mul_f32 v[242:243], v[242:243], s[86:87] op_sel_hi:[1,0]
	v_pk_mul_f32 v[244:245], v[244:245], s[86:87] op_sel_hi:[1,0]
	v_pk_mul_f32 v[246:247], v[246:247], s[86:87] op_sel_hi:[1,0]
	v_pk_mul_f32 v[248:249], v[248:249], s[86:87] op_sel_hi:[1,0]
	v_exp_f32_e32 v242, v242
	v_exp_f32_e32 v243, v243
	v_exp_f32_e32 v244, v244
	v_exp_f32_e32 v245, v245
	v_exp_f32_e32 v246, v246
	v_exp_f32_e32 v247, v247
	v_exp_f32_e32 v248, v248
	v_exp_f32_e32 v249, v249
	v_pk_add_f32 v[242:243], v[242:243], 1.0 op_sel_hi:[1,0]
	v_pk_add_f32 v[244:245], v[244:245], 1.0 op_sel_hi:[1,0]
	v_pk_add_f32 v[246:247], v[246:247], 1.0 op_sel_hi:[1,0]
	v_pk_add_f32 v[248:249], v[248:249], 1.0 op_sel_hi:[1,0]
	v_pk_mul_f32 v[216:217], v[216:217], v[242:243]
	v_pk_mul_f32 v[218:219], v[218:219], v[244:245]
	v_pk_mul_f32 v[220:221], v[220:221], v[246:247]
	v_pk_mul_f32 v[222:223], v[222:223], v[248:249]
	v_pk_mul_f32 v[22:23], v[22:23], v[216:217]
	v_pk_mul_f32 v[24:25], v[24:25], v[218:219]
	v_pk_mul_f32 v[18:19], v[18:19], v[220:221]
	v_pk_mul_f32 v[20:21], v[20:21], v[222:223]
	s_waitcnt vmcnt(4)
	v_lshlrev_b32_e32 v216, 16, v162
	v_and_b32_e32 v217, 0xffff0000, v162
	v_lshlrev_b32_e32 v218, 16, v163
	v_and_b32_e32 v219, 0xffff0000, v163
	v_lshlrev_b32_e32 v220, 16, v164
	v_and_b32_e32 v221, 0xffff0000, v164
	v_lshlrev_b32_e32 v222, 16, v165
	v_and_b32_e32 v223, 0xffff0000, v165
	v_pk_mul_f32 v[216:217], v[216:217], s[86:87] op_sel_hi:[1,0]
	v_pk_mul_f32 v[218:219], v[218:219], s[86:87] op_sel_hi:[1,0]
	v_pk_mul_f32 v[220:221], v[220:221], s[86:87] op_sel_hi:[1,0]
	v_pk_mul_f32 v[222:223], v[222:223], s[86:87] op_sel_hi:[1,0]
	v_exp_f32_e32 v216, v216
	v_exp_f32_e32 v217, v217
	v_exp_f32_e32 v218, v218
	v_exp_f32_e32 v219, v219
	v_exp_f32_e32 v220, v220
	v_exp_f32_e32 v221, v221
	v_exp_f32_e32 v222, v222
	v_exp_f32_e32 v223, v223
	v_pk_add_f32 v[216:217], v[216:217], 1.0 op_sel_hi:[1,0]
	v_pk_add_f32 v[218:219], v[218:219], 1.0 op_sel_hi:[1,0]
	v_pk_add_f32 v[220:221], v[220:221], 1.0 op_sel_hi:[1,0]
	v_pk_add_f32 v[222:223], v[222:223], 1.0 op_sel_hi:[1,0]
	v_rcp_f32_e32 v216, v216
	v_rcp_f32_e32 v217, v217
	v_rcp_f32_e32 v218, v218
	v_rcp_f32_e32 v219, v219
	v_rcp_f32_e32 v220, v220
	v_rcp_f32_e32 v221, v221
	v_rcp_f32_e32 v222, v222
	v_rcp_f32_e32 v223, v223
	v_lshlrev_b32_e32 v242, 16, v166
	v_and_b32_e32 v243, 0xffff0000, v166
	v_lshlrev_b32_e32 v244, 16, v167
	v_and_b32_e32 v245, 0xffff0000, v167
	v_lshlrev_b32_e32 v246, 16, v168
	v_and_b32_e32 v247, 0xffff0000, v168
	v_lshlrev_b32_e32 v248, 16, v169
	v_and_b32_e32 v249, 0xffff0000, v169
	v_pk_mul_f32 v[242:243], v[242:243], s[86:87] op_sel_hi:[1,0]
	v_pk_mul_f32 v[244:245], v[244:245], s[86:87] op_sel_hi:[1,0]
	v_pk_mul_f32 v[246:247], v[246:247], s[86:87] op_sel_hi:[1,0]
	v_pk_mul_f32 v[248:249], v[248:249], s[86:87] op_sel_hi:[1,0]
	v_exp_f32_e32 v242, v242
	v_exp_f32_e32 v243, v243
	v_exp_f32_e32 v244, v244
	v_exp_f32_e32 v245, v245
	v_exp_f32_e32 v246, v246
	v_exp_f32_e32 v247, v247
	v_exp_f32_e32 v248, v248
	v_exp_f32_e32 v249, v249
	v_pk_add_f32 v[242:243], v[242:243], 1.0 op_sel_hi:[1,0]
	v_pk_add_f32 v[244:245], v[244:245], 1.0 op_sel_hi:[1,0]
	v_pk_add_f32 v[246:247], v[246:247], 1.0 op_sel_hi:[1,0]
	v_pk_add_f32 v[248:249], v[248:249], 1.0 op_sel_hi:[1,0]
	v_pk_mul_f32 v[216:217], v[216:217], v[242:243]
	v_pk_mul_f32 v[218:219], v[218:219], v[244:245]
	v_pk_mul_f32 v[220:221], v[220:221], v[246:247]
	v_pk_mul_f32 v[222:223], v[222:223], v[248:249]
	v_pk_mul_f32 v[46:47], v[46:47], v[216:217]
	v_pk_mul_f32 v[48:49], v[48:49], v[218:219]
	v_pk_mul_f32 v[42:43], v[42:43], v[220:221]
	v_pk_mul_f32 v[44:45], v[44:45], v[222:223]
	v_lshlrev_b32_e32 v216, 16, v170
	v_and_b32_e32 v217, 0xffff0000, v170
	v_lshlrev_b32_e32 v218, 16, v171
	v_and_b32_e32 v219, 0xffff0000, v171
	v_lshlrev_b32_e32 v220, 16, v172
	v_and_b32_e32 v221, 0xffff0000, v172
	v_lshlrev_b32_e32 v222, 16, v173
	v_and_b32_e32 v223, 0xffff0000, v173
	v_pk_mul_f32 v[216:217], v[216:217], s[86:87] op_sel_hi:[1,0]
	v_pk_mul_f32 v[218:219], v[218:219], s[86:87] op_sel_hi:[1,0]
	v_pk_mul_f32 v[220:221], v[220:221], s[86:87] op_sel_hi:[1,0]
	v_pk_mul_f32 v[222:223], v[222:223], s[86:87] op_sel_hi:[1,0]
	v_exp_f32_e32 v216, v216
	v_exp_f32_e32 v217, v217
	v_exp_f32_e32 v218, v218
	v_exp_f32_e32 v219, v219
	v_exp_f32_e32 v220, v220
	v_exp_f32_e32 v221, v221
	v_exp_f32_e32 v222, v222
	v_exp_f32_e32 v223, v223
	v_pk_add_f32 v[216:217], v[216:217], 1.0 op_sel_hi:[1,0]
	v_pk_add_f32 v[218:219], v[218:219], 1.0 op_sel_hi:[1,0]
	v_pk_add_f32 v[220:221], v[220:221], 1.0 op_sel_hi:[1,0]
	v_pk_add_f32 v[222:223], v[222:223], 1.0 op_sel_hi:[1,0]
	v_rcp_f32_e32 v216, v216
	v_rcp_f32_e32 v217, v217
	v_rcp_f32_e32 v218, v218
	v_rcp_f32_e32 v219, v219
	v_rcp_f32_e32 v220, v220
	v_rcp_f32_e32 v221, v221
	v_rcp_f32_e32 v222, v222
	v_rcp_f32_e32 v223, v223
	v_lshlrev_b32_e32 v242, 16, v174
	v_and_b32_e32 v243, 0xffff0000, v174
	v_lshlrev_b32_e32 v244, 16, v175
	v_and_b32_e32 v245, 0xffff0000, v175
	v_lshlrev_b32_e32 v246, 16, v176
	v_and_b32_e32 v247, 0xffff0000, v176
	v_lshlrev_b32_e32 v248, 16, v177
	v_and_b32_e32 v249, 0xffff0000, v177
	v_pk_mul_f32 v[242:243], v[242:243], s[86:87] op_sel_hi:[1,0]
	v_pk_mul_f32 v[244:245], v[244:245], s[86:87] op_sel_hi:[1,0]
	v_pk_mul_f32 v[246:247], v[246:247], s[86:87] op_sel_hi:[1,0]
	v_pk_mul_f32 v[248:249], v[248:249], s[86:87] op_sel_hi:[1,0]
	v_exp_f32_e32 v242, v242
	v_exp_f32_e32 v243, v243
	v_exp_f32_e32 v244, v244
	v_exp_f32_e32 v245, v245
	v_exp_f32_e32 v246, v246
	v_exp_f32_e32 v247, v247
	v_exp_f32_e32 v248, v248
	v_exp_f32_e32 v249, v249
	v_pk_add_f32 v[242:243], v[242:243], 1.0 op_sel_hi:[1,0]
	v_pk_add_f32 v[244:245], v[244:245], 1.0 op_sel_hi:[1,0]
	v_pk_add_f32 v[246:247], v[246:247], 1.0 op_sel_hi:[1,0]
	v_pk_add_f32 v[248:249], v[248:249], 1.0 op_sel_hi:[1,0]
	v_pk_mul_f32 v[216:217], v[216:217], v[242:243]
	v_pk_mul_f32 v[218:219], v[218:219], v[244:245]
	v_pk_mul_f32 v[220:221], v[220:221], v[246:247]
	v_pk_mul_f32 v[222:223], v[222:223], v[248:249]
	v_pk_mul_f32 v[14:15], v[14:15], v[216:217]
	v_pk_mul_f32 v[16:17], v[16:17], v[218:219]
	v_pk_mul_f32 v[10:11], v[10:11], v[220:221]
	v_pk_mul_f32 v[12:13], v[12:13], v[222:223]
	s_waitcnt vmcnt(0)
	v_lshlrev_b32_e32 v216, 16, v178
	v_and_b32_e32 v217, 0xffff0000, v178
	v_lshlrev_b32_e32 v218, 16, v179
	v_and_b32_e32 v219, 0xffff0000, v179
	v_lshlrev_b32_e32 v220, 16, v180
	v_and_b32_e32 v221, 0xffff0000, v180
	v_lshlrev_b32_e32 v222, 16, v181
	v_and_b32_e32 v223, 0xffff0000, v181
	v_pk_mul_f32 v[216:217], v[216:217], s[86:87] op_sel_hi:[1,0]
	v_pk_mul_f32 v[218:219], v[218:219], s[86:87] op_sel_hi:[1,0]
	v_pk_mul_f32 v[220:221], v[220:221], s[86:87] op_sel_hi:[1,0]
	v_pk_mul_f32 v[222:223], v[222:223], s[86:87] op_sel_hi:[1,0]
	v_exp_f32_e32 v216, v216
	v_exp_f32_e32 v217, v217
	v_exp_f32_e32 v218, v218
	v_exp_f32_e32 v219, v219
	v_exp_f32_e32 v220, v220
	v_exp_f32_e32 v221, v221
	v_exp_f32_e32 v222, v222
	v_exp_f32_e32 v223, v223
	v_pk_add_f32 v[216:217], v[216:217], 1.0 op_sel_hi:[1,0]
	v_pk_add_f32 v[218:219], v[218:219], 1.0 op_sel_hi:[1,0]
	v_pk_add_f32 v[220:221], v[220:221], 1.0 op_sel_hi:[1,0]
	v_pk_add_f32 v[222:223], v[222:223], 1.0 op_sel_hi:[1,0]
	v_rcp_f32_e32 v216, v216
	v_rcp_f32_e32 v217, v217
	v_rcp_f32_e32 v218, v218
	v_rcp_f32_e32 v219, v219
	v_rcp_f32_e32 v220, v220
	v_rcp_f32_e32 v221, v221
	v_rcp_f32_e32 v222, v222
	v_rcp_f32_e32 v223, v223
	v_lshlrev_b32_e32 v242, 16, v182
	v_and_b32_e32 v243, 0xffff0000, v182
	v_lshlrev_b32_e32 v244, 16, v183
	v_and_b32_e32 v245, 0xffff0000, v183
	v_lshlrev_b32_e32 v246, 16, v184
	v_and_b32_e32 v247, 0xffff0000, v184
	v_lshlrev_b32_e32 v248, 16, v185
	v_and_b32_e32 v249, 0xffff0000, v185
	v_pk_mul_f32 v[242:243], v[242:243], s[86:87] op_sel_hi:[1,0]
	v_pk_mul_f32 v[244:245], v[244:245], s[86:87] op_sel_hi:[1,0]
	v_pk_mul_f32 v[246:247], v[246:247], s[86:87] op_sel_hi:[1,0]
	v_pk_mul_f32 v[248:249], v[248:249], s[86:87] op_sel_hi:[1,0]
	v_exp_f32_e32 v242, v242
	v_exp_f32_e32 v243, v243
	v_exp_f32_e32 v244, v244
	v_exp_f32_e32 v245, v245
	v_exp_f32_e32 v246, v246
	v_exp_f32_e32 v247, v247
	v_exp_f32_e32 v248, v248
	v_exp_f32_e32 v249, v249
	v_pk_add_f32 v[242:243], v[242:243], 1.0 op_sel_hi:[1,0]
	v_pk_add_f32 v[244:245], v[244:245], 1.0 op_sel_hi:[1,0]
	v_pk_add_f32 v[246:247], v[246:247], 1.0 op_sel_hi:[1,0]
	v_pk_add_f32 v[248:249], v[248:249], 1.0 op_sel_hi:[1,0]
	v_pk_mul_f32 v[216:217], v[216:217], v[242:243]
	v_pk_mul_f32 v[218:219], v[218:219], v[244:245]
	v_pk_mul_f32 v[220:221], v[220:221], v[246:247]
	v_pk_mul_f32 v[222:223], v[222:223], v[248:249]
	v_pk_mul_f32 v[38:39], v[38:39], v[216:217]
	v_pk_mul_f32 v[40:41], v[40:41], v[218:219]
	v_pk_mul_f32 v[34:35], v[34:35], v[220:221]
	v_pk_mul_f32 v[36:37], v[36:37], v[222:223]
	v_lshlrev_b32_e32 v216, 16, v186
	v_and_b32_e32 v217, 0xffff0000, v186
	v_lshlrev_b32_e32 v218, 16, v187
	v_and_b32_e32 v219, 0xffff0000, v187
	v_lshlrev_b32_e32 v220, 16, v188
	v_and_b32_e32 v221, 0xffff0000, v188
	v_lshlrev_b32_e32 v222, 16, v189
	v_and_b32_e32 v223, 0xffff0000, v189
	v_pk_mul_f32 v[216:217], v[216:217], s[86:87] op_sel_hi:[1,0]
	v_pk_mul_f32 v[218:219], v[218:219], s[86:87] op_sel_hi:[1,0]
	v_pk_mul_f32 v[220:221], v[220:221], s[86:87] op_sel_hi:[1,0]
	v_pk_mul_f32 v[222:223], v[222:223], s[86:87] op_sel_hi:[1,0]
	v_exp_f32_e32 v216, v216
	v_exp_f32_e32 v217, v217
	v_exp_f32_e32 v218, v218
	v_exp_f32_e32 v219, v219
	v_exp_f32_e32 v220, v220
	v_exp_f32_e32 v221, v221
	v_exp_f32_e32 v222, v222
	v_exp_f32_e32 v223, v223
	v_pk_add_f32 v[216:217], v[216:217], 1.0 op_sel_hi:[1,0]
	v_pk_add_f32 v[218:219], v[218:219], 1.0 op_sel_hi:[1,0]
	v_pk_add_f32 v[220:221], v[220:221], 1.0 op_sel_hi:[1,0]
	v_pk_add_f32 v[222:223], v[222:223], 1.0 op_sel_hi:[1,0]
	v_rcp_f32_e32 v216, v216
	v_rcp_f32_e32 v217, v217
	v_rcp_f32_e32 v218, v218
	v_rcp_f32_e32 v219, v219
	v_rcp_f32_e32 v220, v220
	v_rcp_f32_e32 v221, v221
	v_rcp_f32_e32 v222, v222
	v_rcp_f32_e32 v223, v223
	v_lshlrev_b32_e32 v242, 16, v190
	v_and_b32_e32 v243, 0xffff0000, v190
	v_lshlrev_b32_e32 v244, 16, v191
	v_and_b32_e32 v245, 0xffff0000, v191
	v_lshlrev_b32_e32 v246, 16, v192
	v_and_b32_e32 v247, 0xffff0000, v192
	v_lshlrev_b32_e32 v248, 16, v193
	v_and_b32_e32 v249, 0xffff0000, v193
	v_pk_mul_f32 v[242:243], v[242:243], s[86:87] op_sel_hi:[1,0]
	v_pk_mul_f32 v[244:245], v[244:245], s[86:87] op_sel_hi:[1,0]
	v_pk_mul_f32 v[246:247], v[246:247], s[86:87] op_sel_hi:[1,0]
	v_pk_mul_f32 v[248:249], v[248:249], s[86:87] op_sel_hi:[1,0]
	v_exp_f32_e32 v242, v242
	v_exp_f32_e32 v243, v243
	v_exp_f32_e32 v244, v244
	v_exp_f32_e32 v245, v245
	v_exp_f32_e32 v246, v246
	v_exp_f32_e32 v247, v247
	v_exp_f32_e32 v248, v248
	v_exp_f32_e32 v249, v249
	v_pk_add_f32 v[242:243], v[242:243], 1.0 op_sel_hi:[1,0]
	v_pk_add_f32 v[244:245], v[244:245], 1.0 op_sel_hi:[1,0]
	v_pk_add_f32 v[246:247], v[246:247], 1.0 op_sel_hi:[1,0]
	v_pk_add_f32 v[248:249], v[248:249], 1.0 op_sel_hi:[1,0]
	v_pk_mul_f32 v[216:217], v[216:217], v[242:243]
	v_pk_mul_f32 v[218:219], v[218:219], v[244:245]
	v_pk_mul_f32 v[220:221], v[220:221], v[246:247]
	v_pk_mul_f32 v[222:223], v[222:223], v[248:249]
	v_pk_mul_f32 v[6:7], v[6:7], v[216:217]
	v_pk_mul_f32 v[8:9], v[8:9], v[218:219]
	v_pk_mul_f32 v[2:3], v[2:3], v[220:221]
	v_pk_mul_f32 v[4:5], v[4:5], v[222:223]
	s_branch .Lem_done

.LBB0_500:
	v_lshrrev_b32_e32 v9, 1, v8
	s_sext_i32_i8 s28, s0
	s_mul_i32 s0, s24, 0x36000
	v_and_b32_e32 v19, 24, v9
	s_add_u32 s63, s94, s0
	v_and_b32_e32 v18, 15, v8
	v_lshlrev_b32_e32 v9, 1, v19
	v_lshlrev_b32_e32 v8, 2, v8
	s_addc_u32 s67, s95, 0
	v_lshl_or_b32 v9, v18, 6, v9
	s_lshl_b32 s0, s4, 13
	v_and_b32_e32 v8, 32, v8
	v_bitop3_b32 v162, v9, s0, v8 bitop3:0xde
	s_lshl_b32 s0, s1, 5
	s_lshl_b32 s5, s4, 6
	s_and_b32 s4, s0, 0x60
	v_lshl_add_u64 v[10:11], s[54:55], 0, v[194:195]
	v_mov_b32_e32 v139, v195
	s_lshl_b32 s0, s4, 7
	s_add_i32 s70, s42, 0x18000
	v_lshl_add_u64 v[12:13], s[54:55], 0, v[138:139]
	v_mov_b32_e32 v143, v195
	v_bitop3_b32 v163, v9, s0, v8 bitop3:0xde
	v_lshl_add_u64 v[8:9], v[10:11], 0, s[76:77]
	s_mov_b32 m0, s70
	s_add_i32 s71, s42, 0x1a000
	v_lshl_add_u64 v[14:15], s[52:53], 0, v[142:143]
	v_mov_b32_e32 v141, v195
	s_waitcnt vmcnt(0)
	s_barrier
	global_load_lds_dwordx4 v[8:9], off
	v_lshl_add_u64 v[8:9], v[12:13], 0, s[76:77]
	s_mov_b32 m0, s71
	s_add_i32 s78, s42, 0x8000
	s_add_i32 s79, s42, 0xa000
	v_lshl_add_u64 v[16:17], s[52:53], 0, v[140:141]
	global_load_lds_dwordx4 v[8:9], off
	v_lshl_add_u64 v[8:9], v[14:15], 0, s[76:77]
	s_mov_b32 m0, s78
	s_add_u32 s0, s54, 0x80080
	global_load_lds_dwordx4 v[8:9], off
	v_lshl_add_u64 v[8:9], v[16:17], 0, s[76:77]
	s_mov_b32 m0, s79
	s_addc_u32 s1, s55, 0
	s_add_i32 s80, s42, 0x1c000
	global_load_lds_dwordx4 v[8:9], off
	v_lshl_add_u64 v[8:9], s[0:1], 0, v[194:195]
	s_mov_b32 m0, s80
	s_add_i32 s81, s42, 0x1e000
	global_load_lds_dwordx4 v[8:9], off
	v_lshl_add_u64 v[8:9], s[0:1], 0, v[138:139]
	s_mov_b32 m0, s81
	s_ashr_i32 s0, s5, 31
	global_load_lds_dwordx4 v[8:9], off
	v_or_b32_e32 v8, s5, v18
	v_mov_b32_e32 v9, s0
	v_lshlrev_b64 v[144:145], 11, v[8:9]
	v_lshlrev_b32_e32 v8, 15, v6
	v_and_b32_e32 v8, 0xffff0000, v8
	v_lshl_add_u32 v5, v5, 12, v8
	v_and_b32_e32 v6, 1, v6
	v_lshl_or_b32 v5, v6, 6, v5
	v_lshl_add_u32 v146, v7, 1, v5
	v_lshlrev_b32_e32 v5, 15, v2
	v_and_b32_e32 v5, 0xffff0000, v5
	s_waitcnt vmcnt(6)
	v_lshl_add_u32 v3, v3, 12, v5
	v_and_b32_e32 v2, 1, v2
	v_lshl_or_b32 v2, v2, 6, v3
	v_or_b32_e32 v164, s4, v19
	v_mov_b32_e32 v147, v195
	v_lshl_add_u32 v148, v4, 1, v2
	v_mov_b32_e32 v149, v195
	s_mov_b32 s82, 0
	s_mov_b64 s[34:35], s[54:55]
	s_mov_b64 s[8:9], s[52:53]
	s_barrier

.LBB0_504:
	v_add_u32_e32 v253, 0x10000, v163
	ds_read_b128 v[130:133], v253
	ds_read_b128 v[134:137], v253 offset:1024
	ds_read_b128 v[150:153], v253 offset:2048
	ds_read_b128 v[154:157], v253 offset:3072
	ds_read_b128 v[158:161], v162
	ds_read_b128 v[166:169], v162 offset:1024
	ds_read_b128 v[170:173], v162 offset:2048
	ds_read_b128 v[174:177], v162 offset:3072
	ds_read_b128 v[178:181], v162 offset:4096
	ds_read_b128 v[182:185], v162 offset:5120
	ds_read_b128 v[186:189], v162 offset:6144
	ds_read_b128 v[190:193], v162 offset:7168
	ds_read_b128 v[206:209], v253 offset:16384
	ds_read_b128 v[210:213], v253 offset:17408
	ds_read_b128 v[214:217], v253 offset:18432
	ds_read_b128 v[218:221], v253 offset:19456
	s_add_u32 s10, s52, 0xfff80080
	s_addc_u32 s11, s53, -1
	s_cmp_eq_u32 s29, 28
	s_cselect_b32 s11, s9, s11
	s_cselect_b32 s10, s8, s10
	s_cselect_b32 s55, s35, s7
	s_cselect_b32 s54, s34, s5
	s_add_i32 m0, s42, 0xc000
	s_nop 0
	global_load_lds_dwordx4 v146, s[52:53]
	s_add_i32 m0, s42, 0xe000
	s_nop 0
	global_load_lds_dwordx4 v148, s[52:53]
	s_waitcnt vmcnt(8)
	s_waitcnt lgkmcnt(0)
	s_setprio 1
	s_barrier
	v_mfma_f32_16x16x32_bf16 v[126:129], v[130:133], v[158:161], v[126:129]
	v_mfma_f32_16x16x32_bf16 v[122:125], v[150:153], v[158:161], v[122:125]
	v_mfma_f32_16x16x32_bf16 v[118:121], v[130:133], v[170:173], v[118:121]
	v_mfma_f32_16x16x32_bf16 v[114:117], v[150:153], v[170:173], v[114:117]
	v_mfma_f32_16x16x32_bf16 v[110:113], v[130:133], v[178:181], v[110:113]
	v_mfma_f32_16x16x32_bf16 v[106:109], v[150:153], v[178:181], v[106:109]
	v_mfma_f32_16x16x32_bf16 v[102:105], v[130:133], v[186:189], v[102:105]
	v_mfma_f32_16x16x32_bf16 v[98:101], v[150:153], v[186:189], v[98:101]
	v_mfma_f32_16x16x32_bf16 v[126:129], v[134:137], v[166:169], v[126:129]
	v_mfma_f32_16x16x32_bf16 v[122:125], v[154:157], v[166:169], v[122:125]
	v_mfma_f32_16x16x32_bf16 v[118:121], v[134:137], v[174:177], v[118:121]
	v_mfma_f32_16x16x32_bf16 v[114:117], v[154:157], v[174:177], v[114:117]
	v_mfma_f32_16x16x32_bf16 v[110:113], v[134:137], v[182:185], v[110:113]
	v_mfma_f32_16x16x32_bf16 v[106:109], v[154:157], v[182:185], v[106:109]
	v_mfma_f32_16x16x32_bf16 v[102:105], v[134:137], v[190:193], v[102:105]
	v_mfma_f32_16x16x32_bf16 v[98:101], v[154:157], v[190:193], v[98:101]
	v_mfma_f32_16x16x32_bf16 v[62:65], v[206:209], v[158:161], v[62:65]
	v_mfma_f32_16x16x32_bf16 v[58:61], v[214:217], v[158:161], v[58:61]
	v_mfma_f32_16x16x32_bf16 v[54:57], v[206:209], v[170:173], v[54:57]
	v_mfma_f32_16x16x32_bf16 v[46:49], v[214:217], v[170:173], v[46:49]
	v_mfma_f32_16x16x32_bf16 v[50:53], v[206:209], v[178:181], v[50:53]
	v_mfma_f32_16x16x32_bf16 v[42:45], v[214:217], v[178:181], v[42:45]
	v_mfma_f32_16x16x32_bf16 v[38:41], v[206:209], v[186:189], v[38:41]
	v_mfma_f32_16x16x32_bf16 v[34:37], v[214:217], v[186:189], v[34:37]
	v_mfma_f32_16x16x32_bf16 v[62:65], v[210:213], v[166:169], v[62:65]
	v_mfma_f32_16x16x32_bf16 v[58:61], v[218:221], v[166:169], v[58:61]
	v_mfma_f32_16x16x32_bf16 v[54:57], v[210:213], v[174:177], v[54:57]
	v_mfma_f32_16x16x32_bf16 v[46:49], v[218:221], v[174:177], v[46:49]
	v_mfma_f32_16x16x32_bf16 v[50:53], v[210:213], v[182:185], v[50:53]
	v_mfma_f32_16x16x32_bf16 v[42:45], v[218:221], v[182:185], v[42:45]
	v_mfma_f32_16x16x32_bf16 v[38:41], v[210:213], v[190:193], v[38:41]
	v_mfma_f32_16x16x32_bf16 v[34:37], v[218:221], v[190:193], v[34:37]
	s_setprio 0
	s_barrier
	ds_read_b128 v[158:161], v162 offset:16384
	ds_read_b128 v[166:169], v162 offset:17408
	ds_read_b128 v[170:173], v162 offset:18432
	ds_read_b128 v[174:177], v162 offset:19456
	ds_read_b128 v[178:181], v162 offset:20480
	ds_read_b128 v[182:185], v162 offset:21504
	ds_read_b128 v[186:189], v162 offset:22528
	ds_read_b128 v[190:193], v162 offset:23552
	s_mov_b32 m0, s41
	s_nop 0
	global_load_lds_dwordx4 v194, s[54:55]
	s_mov_b32 m0, s57
	s_nop 0
	global_load_lds_dwordx4 v138, s[54:55]
	s_mov_b32 m0, s42
	s_nop 0
	global_load_lds_dwordx4 v142, s[10:11]
	s_mov_b32 m0, s58
	s_nop 0
	global_load_lds_dwordx4 v140, s[10:11]
	s_add_u32 s86, s54, 0x80000
	s_addc_u32 s87, s55, 0
	s_mov_b32 m0, s59
	s_nop 0
	global_load_lds_dwordx4 v194, s[86:87]
	s_mov_b32 m0, s60
	s_nop 0
	global_load_lds_dwordx4 v138, s[86:87]
	s_waitcnt vmcnt(8)
	s_waitcnt lgkmcnt(0)
	s_setprio 1
	s_barrier
	v_mfma_f32_16x16x32_bf16 v[94:97], v[130:133], v[158:161], v[94:97]
	v_mfma_f32_16x16x32_bf16 v[90:93], v[150:153], v[158:161], v[90:93]
	v_mfma_f32_16x16x32_bf16 v[86:89], v[130:133], v[170:173], v[86:89]
	v_mfma_f32_16x16x32_bf16 v[82:85], v[150:153], v[170:173], v[82:85]
	v_mfma_f32_16x16x32_bf16 v[78:81], v[130:133], v[178:181], v[78:81]
	v_mfma_f32_16x16x32_bf16 v[74:77], v[150:153], v[178:181], v[74:77]
	v_mfma_f32_16x16x32_bf16 v[70:73], v[130:133], v[186:189], v[70:73]
	v_mfma_f32_16x16x32_bf16 v[66:69], v[150:153], v[186:189], v[66:69]
	v_mfma_f32_16x16x32_bf16 v[94:97], v[134:137], v[166:169], v[94:97]
	v_mfma_f32_16x16x32_bf16 v[90:93], v[154:157], v[166:169], v[90:93]
	v_mfma_f32_16x16x32_bf16 v[86:89], v[134:137], v[174:177], v[86:89]
	v_mfma_f32_16x16x32_bf16 v[82:85], v[154:157], v[174:177], v[82:85]
	v_mfma_f32_16x16x32_bf16 v[78:81], v[134:137], v[182:185], v[78:81]
	v_mfma_f32_16x16x32_bf16 v[74:77], v[154:157], v[182:185], v[74:77]
	v_mfma_f32_16x16x32_bf16 v[70:73], v[134:137], v[190:193], v[70:73]
	v_mfma_f32_16x16x32_bf16 v[66:69], v[154:157], v[190:193], v[66:69]
	v_mfma_f32_16x16x32_bf16 v[30:33], v[206:209], v[158:161], v[30:33]
	v_mfma_f32_16x16x32_bf16 v[18:21], v[214:217], v[158:161], v[18:21]
	v_mfma_f32_16x16x32_bf16 v[26:29], v[206:209], v[170:173], v[26:29]
	v_mfma_f32_16x16x32_bf16 v[14:17], v[214:217], v[170:173], v[14:17]
	v_mfma_f32_16x16x32_bf16 v[22:25], v[206:209], v[178:181], v[22:25]
	v_mfma_f32_16x16x32_bf16 v[6:9], v[214:217], v[178:181], v[6:9]
	v_mfma_f32_16x16x32_bf16 v[10:13], v[206:209], v[186:189], v[10:13]
	v_mfma_f32_16x16x32_bf16 v[2:5], v[214:217], v[186:189], v[2:5]
	v_mfma_f32_16x16x32_bf16 v[30:33], v[210:213], v[166:169], v[30:33]
	v_mfma_f32_16x16x32_bf16 v[18:21], v[218:221], v[166:169], v[18:21]
	v_mfma_f32_16x16x32_bf16 v[26:29], v[210:213], v[174:177], v[26:29]
	v_mfma_f32_16x16x32_bf16 v[14:17], v[218:221], v[174:177], v[14:17]
	v_mfma_f32_16x16x32_bf16 v[22:25], v[210:213], v[182:185], v[22:25]
	v_mfma_f32_16x16x32_bf16 v[6:9], v[218:221], v[182:185], v[6:9]
	v_mfma_f32_16x16x32_bf16 v[10:13], v[210:213], v[190:193], v[10:13]
	v_mfma_f32_16x16x32_bf16 v[2:5], v[218:221], v[190:193], v[2:5]
	s_setprio 0
	s_barrier
	ds_read_b128 v[130:133], v253 offset:32768
	ds_read_b128 v[134:137], v253 offset:33792
	ds_read_b128 v[150:153], v253 offset:34816
	ds_read_b128 v[154:157], v253 offset:35840
	ds_read_b128 v[158:161], v162 offset:32768
	ds_read_b128 v[166:169], v162 offset:33792
	ds_read_b128 v[170:173], v162 offset:34816
	ds_read_b128 v[174:177], v162 offset:35840
	ds_read_b128 v[178:181], v162 offset:36864
	ds_read_b128 v[182:185], v162 offset:37888
	ds_read_b128 v[186:189], v162 offset:38912
	ds_read_b128 v[190:193], v162 offset:39936
	ds_read_b128 v[206:209], v253 offset:49152
	ds_read_b128 v[210:213], v253 offset:50176
	ds_read_b128 v[214:217], v253 offset:51200
	ds_read_b128 v[218:221], v253 offset:52224
	s_add_u32 s10, s10, 0x80000
	s_addc_u32 s11, s11, 0
	s_mov_b32 m0, s61
	s_nop 0
	global_load_lds_dwordx4 v142, s[10:11]
	s_mov_b32 m0, s62
	s_nop 0
	global_load_lds_dwordx4 v140, s[10:11]
	s_waitcnt vmcnt(8)
	s_waitcnt lgkmcnt(0)
	s_setprio 1
	s_barrier
	v_mfma_f32_16x16x32_bf16 v[126:129], v[130:133], v[158:161], v[126:129]
	v_mfma_f32_16x16x32_bf16 v[122:125], v[150:153], v[158:161], v[122:125]
	v_mfma_f32_16x16x32_bf16 v[118:121], v[130:133], v[170:173], v[118:121]
	v_mfma_f32_16x16x32_bf16 v[114:117], v[150:153], v[170:173], v[114:117]
	v_mfma_f32_16x16x32_bf16 v[110:113], v[130:133], v[178:181], v[110:113]
	v_mfma_f32_16x16x32_bf16 v[106:109], v[150:153], v[178:181], v[106:109]
	v_mfma_f32_16x16x32_bf16 v[102:105], v[130:133], v[186:189], v[102:105]
	v_mfma_f32_16x16x32_bf16 v[98:101], v[150:153], v[186:189], v[98:101]
	v_mfma_f32_16x16x32_bf16 v[126:129], v[134:137], v[166:169], v[126:129]
	v_mfma_f32_16x16x32_bf16 v[122:125], v[154:157], v[166:169], v[122:125]
	v_mfma_f32_16x16x32_bf16 v[118:121], v[134:137], v[174:177], v[118:121]
	v_mfma_f32_16x16x32_bf16 v[114:117], v[154:157], v[174:177], v[114:117]
	v_mfma_f32_16x16x32_bf16 v[110:113], v[134:137], v[182:185], v[110:113]
	v_mfma_f32_16x16x32_bf16 v[106:109], v[154:157], v[182:185], v[106:109]
	v_mfma_f32_16x16x32_bf16 v[102:105], v[134:137], v[190:193], v[102:105]
	v_mfma_f32_16x16x32_bf16 v[98:101], v[154:157], v[190:193], v[98:101]
	v_mfma_f32_16x16x32_bf16 v[62:65], v[206:209], v[158:161], v[62:65]
	v_mfma_f32_16x16x32_bf16 v[58:61], v[214:217], v[158:161], v[58:61]
	v_mfma_f32_16x16x32_bf16 v[54:57], v[206:209], v[170:173], v[54:57]
	v_mfma_f32_16x16x32_bf16 v[46:49], v[214:217], v[170:173], v[46:49]
	v_mfma_f32_16x16x32_bf16 v[50:53], v[206:209], v[178:181], v[50:53]
	v_mfma_f32_16x16x32_bf16 v[42:45], v[214:217], v[178:181], v[42:45]
	v_mfma_f32_16x16x32_bf16 v[38:41], v[206:209], v[186:189], v[38:41]
	v_mfma_f32_16x16x32_bf16 v[34:37], v[214:217], v[186:189], v[34:37]
	v_mfma_f32_16x16x32_bf16 v[62:65], v[210:213], v[166:169], v[62:65]
	v_mfma_f32_16x16x32_bf16 v[58:61], v[218:221], v[166:169], v[58:61]
	v_mfma_f32_16x16x32_bf16 v[54:57], v[210:213], v[174:177], v[54:57]
	v_mfma_f32_16x16x32_bf16 v[46:49], v[218:221], v[174:177], v[46:49]
	v_mfma_f32_16x16x32_bf16 v[50:53], v[210:213], v[182:185], v[50:53]
	v_mfma_f32_16x16x32_bf16 v[42:45], v[218:221], v[182:185], v[42:45]
	v_mfma_f32_16x16x32_bf16 v[38:41], v[210:213], v[190:193], v[38:41]
	v_mfma_f32_16x16x32_bf16 v[34:37], v[218:221], v[190:193], v[34:37]
	s_setprio 0
	s_barrier
	ds_read_b128 v[158:161], v162 offset:49152
	ds_read_b128 v[166:169], v162 offset:50176
	ds_read_b128 v[170:173], v162 offset:51200
	ds_read_b128 v[174:177], v162 offset:52224
	ds_read_b128 v[178:181], v162 offset:53248
	ds_read_b128 v[182:185], v162 offset:54272
	ds_read_b128 v[186:189], v162 offset:55296
	ds_read_b128 v[190:193], v162 offset:56320
	s_mov_b32 m0, s70
	s_add_u32 s98, s54, 0x80
	s_addc_u32 s99, s55, 0
	global_load_lds_dwordx4 v194, s[98:99]
	s_mov_b32 m0, s71
	s_nop 0
	global_load_lds_dwordx4 v138, s[98:99]
	s_mov_b32 m0, s78
	s_add_u32 s100, s10, 0xfff80080
	s_addc_u32 s101, s11, -1
	global_load_lds_dwordx4 v142, s[100:101]
	s_mov_b32 m0, s79
	s_nop 0
	global_load_lds_dwordx4 v140, s[100:101]
	s_add_u32 s10, s54, 0x80080
	s_addc_u32 s11, s55, 0
	s_mov_b32 m0, s80
	s_nop 0
	global_load_lds_dwordx4 v194, s[10:11]
	s_mov_b32 m0, s81
	s_nop 0
	global_load_lds_dwordx4 v138, s[10:11]
	s_waitcnt vmcnt(8)
	s_waitcnt lgkmcnt(0)
	s_setprio 1
	s_barrier
	v_mfma_f32_16x16x32_bf16 v[94:97], v[130:133], v[158:161], v[94:97]
	v_mfma_f32_16x16x32_bf16 v[90:93], v[150:153], v[158:161], v[90:93]
	v_mfma_f32_16x16x32_bf16 v[86:89], v[130:133], v[170:173], v[86:89]
	v_mfma_f32_16x16x32_bf16 v[82:85], v[150:153], v[170:173], v[82:85]
	v_mfma_f32_16x16x32_bf16 v[78:81], v[130:133], v[178:181], v[78:81]
	v_mfma_f32_16x16x32_bf16 v[74:77], v[150:153], v[178:181], v[74:77]
	v_mfma_f32_16x16x32_bf16 v[70:73], v[130:133], v[186:189], v[70:73]
	v_mfma_f32_16x16x32_bf16 v[66:69], v[150:153], v[186:189], v[66:69]
	v_mfma_f32_16x16x32_bf16 v[94:97], v[134:137], v[166:169], v[94:97]
	v_mfma_f32_16x16x32_bf16 v[90:93], v[154:157], v[166:169], v[90:93]
	v_mfma_f32_16x16x32_bf16 v[86:89], v[134:137], v[174:177], v[86:89]
	v_mfma_f32_16x16x32_bf16 v[82:85], v[154:157], v[174:177], v[82:85]
	v_mfma_f32_16x16x32_bf16 v[78:81], v[134:137], v[182:185], v[78:81]
	v_mfma_f32_16x16x32_bf16 v[74:77], v[154:157], v[182:185], v[74:77]
	v_mfma_f32_16x16x32_bf16 v[70:73], v[134:137], v[190:193], v[70:73]
	v_mfma_f32_16x16x32_bf16 v[66:69], v[154:157], v[190:193], v[66:69]
	v_mfma_f32_16x16x32_bf16 v[30:33], v[206:209], v[158:161], v[30:33]
	v_mfma_f32_16x16x32_bf16 v[18:21], v[214:217], v[158:161], v[18:21]
	v_mfma_f32_16x16x32_bf16 v[26:29], v[206:209], v[170:173], v[26:29]
	v_mfma_f32_16x16x32_bf16 v[14:17], v[214:217], v[170:173], v[14:17]
	v_mfma_f32_16x16x32_bf16 v[22:25], v[206:209], v[178:181], v[22:25]
	v_mfma_f32_16x16x32_bf16 v[6:9], v[214:217], v[178:181], v[6:9]
	v_mfma_f32_16x16x32_bf16 v[10:13], v[206:209], v[186:189], v[10:13]
	v_mfma_f32_16x16x32_bf16 v[2:5], v[214:217], v[186:189], v[2:5]
	v_mfma_f32_16x16x32_bf16 v[30:33], v[210:213], v[166:169], v[30:33]
	v_mfma_f32_16x16x32_bf16 v[18:21], v[218:221], v[166:169], v[18:21]
	v_mfma_f32_16x16x32_bf16 v[26:29], v[210:213], v[174:177], v[26:29]
	v_mfma_f32_16x16x32_bf16 v[14:17], v[218:221], v[174:177], v[14:17]
	v_mfma_f32_16x16x32_bf16 v[22:25], v[210:213], v[182:185], v[22:25]
	v_mfma_f32_16x16x32_bf16 v[6:9], v[218:221], v[182:185], v[6:9]
	v_mfma_f32_16x16x32_bf16 v[10:13], v[210:213], v[190:193], v[10:13]
	v_mfma_f32_16x16x32_bf16 v[2:5], v[218:221], v[190:193], v[2:5]
	s_setprio 0
	s_add_i32 s29, s29, 2
	s_add_u32 s52, s52, 0x100
	s_addc_u32 s53, s53, 0
	s_add_u32 s5, s5, 0x100
	s_addc_u32 s7, s7, 0
	s_cmp_gt_u32 s29, 29
	s_barrier
	s_cbranch_scc0 .LBB0_504
	v_readlane_b32 s10, v250, 21
	s_cmp_gt_i32 s40, 63
	v_readlane_b32 s11, v250, 22
	s_mov_b64 s[20:21], s[48:49]
	s_cselect_b32 s11, s21, s11
	s_cselect_b32 s10, s20, s10
	v_readlane_b32 s20, v252, 0
	v_readlane_b32 s26, v252, 6
	v_readlane_b32 s27, v252, 7
	s_cselect_b32 s53, s3, s27
	s_cselect_b32 s52, s2, s26
	s_sub_i32 s5, s40, 64
	s_cmp_gt_i32 s40, 63
	s_cselect_b32 s54, s5, s40
	s_lshr_b32 s5, s40, 3
	s_cmp_gt_i32 s40, 63
	s_mulk_i32 s5, 0x1800
	v_lshl_or_b32 v130, s28, 8, v164
	s_cselect_b32 s28, 0xc000, s5
	s_ashr_i32 s29, s28, 31
	s_lshl_b64 s[28:29], s[28:29], 2
	s_add_u32 s28, s63, s28
	v_ashrrev_i32_e32 v131, 31, v130
	s_addc_u32 s29, s67, s29
	v_lshlrev_b64 v[130:131], 2, v[130:131]
	v_lshl_add_u64 v[132:133], s[28:29], 0, v[130:131]
	s_mov_b64 s[28:29], 0x6484000
	s_ashr_i32 s55, s54, 31
	v_lshl_add_u64 v[154:155], v[132:133], 0, s[28:29]
	s_lshl_b64 s[28:29], s[54:55], 19
	v_lshl_add_u64 v[134:135], s[28:29], 0, v[144:145]
	v_lshlrev_b64 v[134:135], 2, v[134:135]
	v_lshl_add_u64 v[136:137], s[10:11], 0, v[134:135]
	v_lshl_add_u64 v[134:135], s[52:53], 0, v[134:135]
	s_mov_b32 s5, 0x6484000
	v_lshl_add_u64 v[150:151], v[136:137], 0, v[130:131]
	v_lshl_add_u64 v[152:153], v[134:135], 0, v[130:131]
	v_add_co_u32_e32 v130, vcc, s5, v132
	s_mov_b64 s[10:11], 0x20000
	s_nop 0
	v_addc_co_u32_e32 v131, vcc, 0, v133, vcc
	v_add_co_u32_e32 v156, vcc, s13, v150
	global_load_dwordx4 v[134:137], v[130:131], off
	s_nop 0
	global_load_dwordx4 v[130:133], v[154:155], off offset:16
	global_load_dwordx4 v[166:169], v[150:151], off offset:16
	global_load_dwordx4 v[170:173], v[150:151], off
	v_lshl_add_u64 v[158:159], v[150:151], 0, s[10:11]
	v_addc_co_u32_e32 v157, vcc, 0, v151, vcc
	s_mov_b32 s5, 0x40000
	global_load_dwordx4 v[174:177], v[156:157], off
	global_load_dwordx4 v[178:181], v[158:159], off offset:16
	s_mov_b64 s[10:11], 0x40000
	v_add_co_u32_e32 v158, vcc, s5, v150
	v_lshl_add_u64 v[160:161], v[150:151], 0, s[10:11]
	s_nop 0
	v_addc_co_u32_e32 v159, vcc, 0, v151, vcc
	s_mov_b32 s7, 0x60000
	global_load_dwordx4 v[182:185], v[158:159], off
	global_load_dwordx4 v[186:189], v[160:161], off offset:16
	s_mov_b64 s[10:11], 0x60000
	v_add_co_u32_e32 v160, vcc, s7, v150
	v_lshl_add_u64 v[206:207], v[150:151], 0, s[10:11]
	s_nop 0
	v_addc_co_u32_e32 v161, vcc, 0, v151, vcc
	global_load_dwordx4 v[190:193], v[160:161], off
	s_nop 0
	global_load_dwordx4 v[206:209], v[206:207], off offset:16
	v_readlane_b32 s21, v252, 1
	v_readlane_b32 s22, v252, 2
	v_readlane_b32 s23, v252, 3
	v_readlane_b32 s24, v252, 4
	v_readlane_b32 s25, v252, 5
	s_waitcnt vmcnt(0)
	v_pk_fma_f32 v[124:125], v[124:125], v[132:133], v[168:169]
	v_pk_fma_f32 v[122:123], v[122:123], v[130:131], v[166:167]
	global_store_dwordx4 v[152:153], v[122:125], off offset:16
	v_pk_fma_f32 v[128:129], v[128:129], v[136:137], v[172:173]
	v_pk_fma_f32 v[126:127], v[126:127], v[134:135], v[170:171]
	v_pk_fma_f32 v[122:123], v[120:121], v[136:137], v[176:177]
	v_pk_fma_f32 v[120:121], v[118:119], v[134:135], v[174:175]
	v_add_co_u32_e32 v118, vcc, s13, v152
	v_pk_fma_f32 v[116:117], v[116:117], v[132:133], v[180:181]
	s_nop 0
	v_addc_co_u32_e32 v119, vcc, 0, v153, vcc
	v_pk_fma_f32 v[114:115], v[114:115], v[130:131], v[178:179]
	global_store_dwordx4 v[118:119], v[114:117], off offset:16
	v_pk_fma_f32 v[108:109], v[108:109], v[132:133], v[188:189]
	v_pk_fma_f32 v[106:107], v[106:107], v[130:131], v[186:187]
	v_pk_fma_f32 v[114:115], v[112:113], v[136:137], v[184:185]
	v_pk_fma_f32 v[112:113], v[110:111], v[134:135], v[182:183]
	v_add_co_u32_e32 v110, vcc, s5, v152
	global_store_dwordx4 v[152:153], v[126:129], off
	s_nop 0
	v_addc_co_u32_e32 v111, vcc, 0, v153, vcc
	global_store_dwordx4 v[110:111], v[106:109], off offset:16
	v_pk_fma_f32 v[100:101], v[100:101], v[132:133], v[208:209]
	v_pk_fma_f32 v[98:99], v[98:99], v[130:131], v[206:207]
	v_pk_fma_f32 v[106:107], v[104:105], v[136:137], v[192:193]
	v_pk_fma_f32 v[104:105], v[102:103], v[134:135], v[190:191]
	v_add_co_u32_e32 v102, vcc, s7, v152
	global_store_dwordx4 v[118:119], v[120:123], off
	s_nop 0
	v_addc_co_u32_e32 v103, vcc, 0, v153, vcc
	global_store_dwordx4 v[110:111], v[112:115], off
	global_store_dwordx4 v[102:103], v[104:107], off
	global_store_dwordx4 v[102:103], v[98:101], off offset:16
	s_mov_b32 s5, 0x100000
	s_mov_b64 s[10:11], 0x100000
	v_add_co_u32_e32 v98, vcc, s5, v150
	v_lshl_add_u64 v[100:101], v[150:151], 0, s[10:11]
	s_nop 0
	v_addc_co_u32_e32 v99, vcc, 0, v151, vcc
	global_load_dwordx4 v[112:115], v[98:99], off
	global_load_dwordx4 v[120:123], v[100:101], off offset:16
	s_mov_b64 s[10:11], 0x120000
	v_add_co_u32_e32 v100, vcc, s45, v150
	v_lshl_add_u64 v[104:105], v[150:151], 0, s[10:11]
	s_nop 0
	v_addc_co_u32_e32 v101, vcc, 0, v151, vcc
	s_mov_b64 s[10:11], 0x140000
	s_mov_b32 s7, 0x140000
	global_load_dwordx4 v[124:127], v[100:101], off
	global_load_dwordx4 v[166:169], v[104:105], off offset:16
	v_lshl_add_u64 v[106:107], v[150:151], 0, s[10:11]
	v_add_co_u32_e32 v104, vcc, s7, v150
	s_mov_b64 s[10:11], 0x160000
	s_nop 0
	v_addc_co_u32_e32 v105, vcc, 0, v151, vcc
	v_lshl_add_u64 v[108:109], v[150:151], 0, s[10:11]
	s_mov_b32 s10, 0x160000
	global_load_dwordx4 v[170:173], v[104:105], off
	global_load_dwordx4 v[174:177], v[106:107], off offset:16
	v_add_co_u32_e32 v106, vcc, s10, v150
	s_waitcnt vmcnt(0)
	v_pk_fma_f32 v[112:113], v[94:95], v[134:135], v[112:113]
	v_addc_co_u32_e32 v107, vcc, 0, v151, vcc
	global_load_dwordx4 v[178:181], v[106:107], off
	global_load_dwordx4 v[182:185], v[108:109], off offset:16
	v_add_co_u32_e32 v94, vcc, s5, v152
	v_pk_fma_f32 v[92:93], v[92:93], v[132:133], v[122:123]
	s_nop 0
	v_addc_co_u32_e32 v95, vcc, 0, v153, vcc
	v_pk_fma_f32 v[90:91], v[90:91], v[130:131], v[120:121]
	global_store_dwordx4 v[94:95], v[90:93], off offset:16
	v_pk_fma_f32 v[84:85], v[84:85], v[132:133], v[168:169]
	v_pk_fma_f32 v[82:83], v[82:83], v[130:131], v[166:167]
	v_pk_fma_f32 v[90:91], v[88:89], v[136:137], v[126:127]
	v_pk_fma_f32 v[88:89], v[86:87], v[134:135], v[124:125]
	v_add_co_u32_e32 v86, vcc, s45, v152
	v_pk_fma_f32 v[114:115], v[96:97], v[136:137], v[114:115]
	s_nop 0
	v_addc_co_u32_e32 v87, vcc, 0, v153, vcc
	global_store_dwordx4 v[86:87], v[82:85], off offset:16
	v_pk_fma_f32 v[76:77], v[76:77], v[132:133], v[176:177]
	v_pk_fma_f32 v[74:75], v[74:75], v[130:131], v[174:175]
	v_pk_fma_f32 v[82:83], v[80:81], v[136:137], v[172:173]
	v_pk_fma_f32 v[80:81], v[78:79], v[134:135], v[170:171]
	v_add_co_u32_e32 v78, vcc, s7, v152
	global_store_dwordx4 v[94:95], v[112:115], off
	s_nop 0
	v_addc_co_u32_e32 v79, vcc, 0, v153, vcc
	global_store_dwordx4 v[78:79], v[74:77], off offset:16
	global_store_dwordx4 v[86:87], v[88:91], off
	global_store_dwordx4 v[78:79], v[80:83], off
	v_add_co_u32_e32 v74, vcc, s10, v152
	s_waitcnt vmcnt(0)
	v_pk_fma_f32 v[72:73], v[72:73], v[136:137], v[180:181]
	v_pk_fma_f32 v[70:71], v[70:71], v[134:135], v[178:179]
	v_addc_co_u32_e32 v75, vcc, 0, v153, vcc
	v_pk_fma_f32 v[68:69], v[68:69], v[132:133], v[184:185]
	v_pk_fma_f32 v[66:67], v[66:67], v[130:131], v[182:183]
	global_store_dwordx4 v[74:75], v[70:73], off
	global_store_dwordx4 v[74:75], v[66:69], off offset:16
	s_mov_b64 s[10:11], 0x20200
	v_lshl_add_u64 v[76:77], v[150:151], 0, s[10:11]
	s_mov_b64 s[10:11], 0x40200
	global_load_dwordx4 v[80:83], v[150:151], off offset:512
	global_load_dwordx4 v[70:73], v[154:155], off offset:512
	global_load_dwordx4 v[66:69], v[154:155], off offset:528
	global_load_dwordx4 v[88:91], v[150:151], off offset:528
	global_load_dwordx4 v[112:115], v[156:157], off offset:512
	global_load_dwordx4 v[120:123], v[158:159], off offset:512
	global_load_dwordx4 v[124:127], v[76:77], off offset:16
	v_lshl_add_u64 v[76:77], v[150:151], 0, s[10:11]
	s_mov_b64 s[10:11], 0x60200
	global_load_dwordx4 v[128:131], v[76:77], off offset:16
	global_load_dwordx4 v[132:135], v[160:161], off offset:512
	v_lshl_add_u64 v[76:77], v[150:151], 0, s[10:11]
	global_load_dwordx4 v[154:157], v[76:77], off offset:16
	s_waitcnt vmcnt(0)
	v_pk_fma_f32 v[64:65], v[64:65], v[72:73], v[82:83]
	v_pk_fma_f32 v[62:63], v[62:63], v[70:71], v[80:81]
	v_pk_fma_f32 v[60:61], v[60:61], v[68:69], v[90:91]
	v_pk_fma_f32 v[58:59], v[58:59], v[66:67], v[88:89]
	v_pk_fma_f32 v[52:53], v[52:53], v[72:73], v[122:123]
	v_pk_fma_f32 v[50:51], v[50:51], v[70:71], v[120:121]
	v_pk_fma_f32 v[48:49], v[48:49], v[68:69], v[126:127]
	v_pk_fma_f32 v[46:47], v[46:47], v[66:67], v[124:125]
	v_pk_fma_f32 v[56:57], v[56:57], v[72:73], v[114:115]
	v_pk_fma_f32 v[54:55], v[54:55], v[70:71], v[112:113]
	global_store_dwordx4 v[152:153], v[62:65], off offset:512
	global_store_dwordx4 v[152:153], v[58:61], off offset:528
	global_store_dwordx4 v[118:119], v[54:57], off offset:512
	global_store_dwordx4 v[110:111], v[50:53], off offset:512
	v_pk_fma_f32 v[44:45], v[44:45], v[68:69], v[130:131]
	v_pk_fma_f32 v[42:43], v[42:43], v[66:67], v[128:129]
	v_pk_fma_f32 v[40:41], v[40:41], v[72:73], v[134:135]
	v_pk_fma_f32 v[38:39], v[38:39], v[70:71], v[132:133]
	v_pk_fma_f32 v[36:37], v[36:37], v[68:69], v[156:157]
	v_pk_fma_f32 v[34:35], v[34:35], v[66:67], v[154:155]
	global_store_dwordx4 v[118:119], v[46:49], off offset:528
	global_store_dwordx4 v[110:111], v[42:45], off offset:528
	global_store_dwordx4 v[102:103], v[38:41], off offset:512
	global_store_dwordx4 v[102:103], v[34:37], off offset:528
	s_mov_b64 s[10:11], 0x100200
	v_lshl_add_u64 v[50:51], v[150:151], 0, s[10:11]
	s_mov_b64 s[10:11], 0x120200
	v_lshl_add_u64 v[54:55], v[150:151], 0, s[10:11]
	s_mov_b64 s[10:11], 0x140200
	v_lshl_add_u64 v[58:59], v[150:151], 0, s[10:11]
	s_mov_b64 s[10:11], 0x160200
	global_load_dwordx4 v[34:37], v[98:99], off offset:512
	global_load_dwordx4 v[38:41], v[100:101], off offset:512
	global_load_dwordx4 v[42:45], v[104:105], off offset:512
	global_load_dwordx4 v[46:49], v[106:107], off offset:512
	v_lshl_add_u64 v[62:63], v[150:151], 0, s[10:11]
	global_load_dwordx4 v[50:53], v[50:51], off offset:16
	s_waitcnt vmcnt(0)
	v_pk_fma_f32 v[32:33], v[32:33], v[72:73], v[36:37]
	global_load_dwordx4 v[54:57], v[54:55], off offset:16
	v_pk_fma_f32 v[30:31], v[30:31], v[70:71], v[34:35]
	global_load_dwordx4 v[58:61], v[58:59], off offset:16
	v_pk_fma_f32 v[28:29], v[28:29], v[72:73], v[40:41]
	global_load_dwordx4 v[62:65], v[62:63], off offset:16
	v_pk_fma_f32 v[26:27], v[26:27], v[70:71], v[38:39]
	v_pk_fma_f32 v[24:25], v[24:25], v[72:73], v[44:45]
	v_pk_fma_f32 v[22:23], v[22:23], v[70:71], v[42:43]
	v_pk_fma_f32 v[12:13], v[12:13], v[72:73], v[48:49]
	v_pk_fma_f32 v[10:11], v[10:11], v[70:71], v[46:47]
	v_pk_fma_f32 v[20:21], v[20:21], v[68:69], v[52:53]
	v_pk_fma_f32 v[18:19], v[18:19], v[66:67], v[50:51]
	global_store_dwordx4 v[94:95], v[30:33], off offset:512
	global_store_dwordx4 v[86:87], v[26:29], off offset:512
	global_store_dwordx4 v[78:79], v[22:25], off offset:512
	global_store_dwordx4 v[74:75], v[10:13], off offset:512
	s_waitcnt vmcnt(0)
	v_pk_fma_f32 v[16:17], v[16:17], v[68:69], v[56:57]
	v_pk_fma_f32 v[14:15], v[14:15], v[66:67], v[54:55]
	v_pk_fma_f32 v[8:9], v[8:9], v[68:69], v[60:61]
	v_pk_fma_f32 v[6:7], v[6:7], v[66:67], v[58:59]
	v_pk_fma_f32 v[4:5], v[4:5], v[68:69], v[64:65]
	v_pk_fma_f32 v[2:3], v[2:3], v[66:67], v[62:63]
	global_store_dwordx4 v[94:95], v[18:21], off offset:528
	global_store_dwordx4 v[86:87], v[14:17], off offset:528
	global_store_dwordx4 v[78:79], v[6:9], off offset:528
	global_store_dwordx4 v[74:75], v[2:5], off offset:528
	s_and_b64 vcc, exec, s[0:1]
	s_mov_b32 s40, s6
	s_mov_b32 s28, s4
	s_mov_b64 s[54:55], s[34:35]
	s_mov_b64 s[52:53], s[8:9]
	s_cbranch_vccz .LBB0_501
	s_waitcnt vmcnt(0)
	v_readlane_b32 s28, v250, 12
	v_readlane_b32 s26, v250, 15
	s_cmpk_gt_u32 s12, 0xff
	v_readlane_b32 s29, v250, 13
	v_readlane_b32 s27, v250, 16
	s_mov_b32 s70, 0x800000
	v_readlane_b32 s79, v250, 18
	s_cbranch_scc1 .LBB0_508
	s_barrier
